# GEMM K-loops: one rendezvous per super-phase instead of two (leading half drops pre-MFMA barriers, trailing half drops post-MFMA barriers, offset barriers removed); trailing MFMA blocks at priority 2
# baseline (speedup 1.0000x reference)
; template <class Epi, class Sched, bool ALIGN_EPI = false, bool SP2 = false, class Hook = NoHook, bool REVK = false>
; __device__ __forceinline__ void gemm_phase(PG8_LAS unsigned char* lds, const Gemm g, const Sched& S, const Epi& E, const Hook H = Hook()) {
;     int tid_ = threadIdx.x; asm volatile("" : "+v"(tid_));
;     const int tid = tid_, wid = __builtin_amdgcn_readfirstlane(tid >> 6), lane = tid & 63, wr = wid >> 2, wc = wid & 3, fr = lane & 15, fq = lane >> 4;
;     const int K = g.K, nt = K / BK;
;     unsigned voffA[2], voffB[2];
; #pragma unroll
;     for (int i = 0; i < 2; ++i) { int R, C; stage_rc(tid * 16 + i * 8192, R, C); const int Rb = Epi::PERM ? ((R & ~31) + perm32(R & 31)) : R;
;         voffA[i] = (unsigned)(R * K + C) * 2u; voffB[i] = (unsigned)(Rb * K + C) * 2u; }
;     const long kstep = REVK ? -(long)(BK * 2) : (long)(BK * 2);
;     const size_t krev = REVK ? (size_t)(K / BK - 1) * (size_t)(BK * 2) : 0;
;     const size_t hstep = (size_t)HALF * K * 2;
;     const size_t tstep = 2 * hstep;
;     const unsigned ldsw = (unsigned)wid * 1024u;
;     const int aoff = lds_byte(wr * 64 + fr, fq * 8), boff = lds_byte(wc * 32 + fr, fq * 8);
;     ...
;     Unit cur, nxt; int ui = 0;
;     if (!S.next(0, cur)) return;
;     f32x4 acc[2][2][4][2];
; #pragma unroll
;     for (int a = 0; a < 2; ++a)
; #pragma unroll
;         for (int b = 0; b < 2; ++b)
; #pragma unroll
;             for (int m = 0; m < 4; ++m)
; #pragma unroll
;                 for (int n = 0; n < 2; ++n) acc[a][b][m][n] = (f32x4){0.f, 0.f, 0.f, 0.f};
;     bf16x8 At[4][2], B0[2][2], B1[2][2];
;     const char* cA = (const char*)g.A + (size_t)cur.pm * tstep + krev; const char* cB = (const char*)g.Bt + (size_t)cur.pn * tstep + krev;
;     S.a_ready(cur);
;     if constexpr (SP2) {
;         PG8_STAGE(PG8_SB(0, 0), cB, voffB); PG8_STAGE(PG8_SB(0, 1), cB + hstep, voffB); PG8_STAGE(PG8_SA(0, 0), cA, voffA); PG8_STAGE(PG8_SA(0, 1), cA + hstep, voffA);
;         if (wr == 1) PG8_BAR;
;         PG8_WAIT_V(2); PG8_BAR;
;         PG8_STAGE(PG8_SB(1, 0), cB + kstep, voffB); PG8_STAGE(PG8_SA(1, 0), cA + kstep, voffA); PG8_STAGE(PG8_SB(1, 1), cB + hstep + kstep, voffB);
;         PG8_WAIT_V(6); PG8_BAR;
;     } else {
;         PG8_STAGE(PG8_SB(0, 0), cB, voffB); PG8_STAGE(PG8_SA(0, 0), cA, voffA); PG8_STAGE(PG8_SB(0, 1), cB + hstep, voffB); PG8_STAGE(PG8_SA(0, 1), cA + hstep, voffA);
.LBB0_50:
	v_readlane_b32 s4, v250, 3
	v_mov_b32_e32 v9, v199
	v_readlane_b32 s5, v250, 4
	s_mul_hi_u32 s27, s74, 0xf00000
	s_mul_i32 s35, s74, 0xf00000
	s_waitcnt lgkmcnt(0)
	s_barrier
	s_andn2_b64 vcc, exec, s[4:5]
	v_readfirstlane_b32 s4, v9
	s_cbranch_vccnz .LBB0_84
	v_lshlrev_b32_e32 v0, 4, v9
	v_add_u32_e32 v1, 0x2000, v0
	v_ashrrev_i32_e32 v2, 31, v1
	v_lshrrev_b32_e32 v2, 22, v2
	v_add_u32_e32 v2, v1, v2
	v_ashrrev_i32_e32 v8, 10, v2
	v_mul_i32_i24_e32 v2, 0x400, v8
	v_sub_u32_e32 v1, v1, v2
	v_lshrrev_b32_e32 v2, 4, v1
	v_bitop3_b32 v1, v2, v1, 32 bitop3:0x6c
	v_ashrrev_i32_e32 v2, 31, v1
	v_lshrrev_b32_e32 v2, 26, v2
	v_add_u32_e32 v2, v1, v2
	v_lshlrev_b32_e32 v3, 3, v8
	v_ashrrev_i32_e32 v10, 6, v2
	v_and_b32_e32 v3, -16, v3
	v_add_u32_e32 v3, v10, v3
	v_and_b32_e32 v4, 3, v10
	s_mov_b32 s7, 0xfffe0
	v_lshrrev_b32_e32 v5, 2, v3
	v_lshlrev_b32_e32 v6, 1, v3
	v_and_b32_e32 v2, 0xc0, v2
	v_and_or_b32 v4, v3, s7, v4
	v_and_b32_e32 v5, 4, v5
	v_and_b32_e32 v6, 24, v6
	v_sub_u32_e32 v1, v1, v2
	v_or3_b32 v4, v4, v5, v6
	v_lshlrev_b32_e32 v5, 5, v8
	v_ashrrev_i16_sdwa v1, v219, sext(v1) dst_sel:DWORD dst_unused:UNUSED_PAD src0_sel:DWORD src1_sel:BYTE_0
	v_and_b32_e32 v5, 32, v5
	v_bfe_i32 v11, v1, 0, 16
	v_add_lshl_u32 v1, v5, v11, 1
	v_lshl_add_u32 v146, v4, 12, v1
	v_lshl_add_u32 v148, v3, 12, v1
	v_bfe_i32 v1, v9, 27, 1
	v_lshrrev_b32_e32 v1, 22, v1
	v_add_u32_e32 v1, v0, v1
	v_and_b32_e32 v1, 0xfffffc00, v1
	v_sub_u32_e32 v0, v0, v1
	v_lshrrev_b32_e32 v1, 4, v0
	v_ashrrev_i32_e32 v2, 31, v9
	v_bitop3_b32 v0, v1, v0, 32 bitop3:0x6c
	v_lshrrev_b32_e32 v2, 26, v2
	v_ashrrev_i32_e32 v1, 31, v0
	v_add_u32_e32 v2, v9, v2
	v_lshrrev_b32_e32 v1, 26, v1
	v_ashrrev_i32_e32 v13, 6, v2
	s_ashr_i32 s5, s4, 6
	v_add_u32_e32 v1, v0, v1
	v_lshlrev_b32_e32 v2, 3, v13
	s_ashr_i32 s6, s4, 8
	s_lshl_b32 s38, s5, 10
	v_ashrrev_i32_e32 v12, 6, v1
	v_and_b32_e32 v2, -16, v2
	s_add_u32 s39, s22, 0x15c00000
	v_add_u32_e32 v2, v12, v2
	s_addc_u32 s40, s23, 0
	v_and_b32_e32 v3, 3, v12
	v_lshrrev_b32_e32 v4, 2, v2
	v_lshlrev_b32_e32 v5, 1, v2
	v_and_b32_e32 v1, 0xc0, v1
	s_add_u32 s41, s22, s35
	v_and_or_b32 v3, v2, s7, v3
	v_and_b32_e32 v4, 4, v4
	v_and_b32_e32 v5, 24, v5
	v_sub_u32_e32 v0, v0, v1
	s_addc_u32 s42, s23, s27
	v_or3_b32 v3, v3, v4, v5
	v_lshlrev_b32_e32 v4, 5, v13
	v_ashrrev_i16_sdwa v0, v219, sext(v0) dst_sel:DWORD dst_unused:UNUSED_PAD src0_sel:DWORD src1_sel:BYTE_0
	v_readlane_b32 s10, v250, 18
	v_and_b32_e32 v4, 32, v4
	s_waitcnt vmcnt(8)
	v_bfe_i32 v14, v0, 0, 16
	v_readlane_b32 s11, v250, 19
	s_add_u32 s20, s41, s10
	v_add_lshl_u32 v0, v4, v14, 1
	s_addc_u32 s21, s42, s11
	s_add_i32 s43, s38, 0
	v_lshl_add_u32 v150, v3, 12, v0
	s_add_i32 m0, s43, 0x10000
	v_lshl_add_u32 v152, v2, 12, v0
	global_load_lds_dwordx4 v150, s[20:21]
	s_add_i32 m0, s43, 0x12000
	s_add_u32 s10, s20, 0x80000
	global_load_lds_dwordx4 v146, s[20:21]
	s_addc_u32 s11, s21, 0
	s_add_i32 m0, s43, 0x14000
	s_load_dwordx4 s[12:15], s[8:9], 0x30
	global_load_lds_dwordx4 v150, s[10:11]
	s_add_i32 m0, s43, 0x16000
	v_mov_b32_e32 v151, v129
	global_load_lds_dwordx4 v146, s[10:11]
	v_readlane_b32 s10, v250, 16
	v_readlane_b32 s11, v250, 17
	s_add_u32 s26, s39, s10
	s_addc_u32 s27, s40, s11
	s_add_i32 s75, s43, 0x2000
	s_mov_b32 m0, s43
	s_add_u32 s10, s26, 0x80000
	global_load_lds_dwordx4 v152, s[26:27]
	s_mov_b32 m0, s75
	s_addc_u32 s11, s27, 0
	s_add_i32 s77, s43, 0x4000
	global_load_lds_dwordx4 v148, s[26:27]
	s_mov_b32 m0, s77
	s_add_i32 s79, s43, 0x6000
	global_load_lds_dwordx4 v152, s[10:11]
	s_mov_b32 m0, s79
	v_mov_b32_e32 v147, v129
	global_load_lds_dwordx4 v148, s[10:11]
	v_mov_b32_e32 v153, v129
	v_mov_b32_e32 v149, v129
	s_cmp_eq_u32 s6, 1
	v_lshl_add_u64 v[6:7], s[20:21], 0, v[150:151]
	v_lshl_add_u64 v[4:5], s[20:21], 0, v[146:147]
	v_lshl_add_u64 v[0:1], s[26:27], 0, v[152:153]
	s_cselect_b64 s[8:9], -1, 0
	s_mov_b32 s32, s6
	s_cmp_lg_u32 s6, 1
	v_lshl_add_u64 v[2:3], s[26:27], 0, v[148:149]
	s_cbranch_scc1 .LBB0_53

; #define PG8_STAGE(bufoff, gbase, voff) do { _Pragma("unroll") for (int _i = 0; _i < 2; ++_i) \
;         __builtin_amdgcn_global_load_lds((const unsigned*)((const char*)(gbase) + (voff)[_i]), (PG8_LAS unsigned*)(lds + (bufoff) + ldsw + _i * 8192), 16, 0, 0); } while (0)
; #define PG8_LDA(dst, b, h) do { _Pragma("unroll") for (int m = 0; m < 4; ++m) _Pragma("unroll") for (int k = 0; k < 2; ++k) dst[m][k] = *(const PG8_LAS bf16x8*)(lds + PG8_SA(b, h) + aoff + m * 2048 + k * 1024); } while (0)
; #define PG8_LDB(dst, b, h) do { _Pragma("unroll") for (int n = 0; n < 2; ++n) _Pragma("unroll") for (int k = 0; k < 2; ++k) dst[n][k] = *(const PG8_LAS bf16x8*)(lds + PG8_SB(b, h) + boff + n * 2048 + k * 1024); } while (0)
; #define PG8_WAIT_V(n) asm volatile("s_waitcnt vmcnt(" #n ")" ::: "memory")
; #define PG8_WAIT_L(n) asm volatile("s_waitcnt lgkmcnt(" #n ")" ::: "memory")
; template <class Epi, class Sched, bool ALIGN_EPI = false, bool SP2 = false, class Hook = NoHook, bool REVK = false>
; __device__ __forceinline__ void gemm_phase(PG8_LAS unsigned char* lds, const Gemm g, const Sched& S, const Epi& E, const Hook H = Hook()) {
;     ...
;         const bool has_next = S.next(ui + 1, nxt);
;         const char* nA = has_next ? (const char*)g.A + (size_t)nxt.pm * tstep + krev : cA; const char* nB = has_next ? (const char*)g.Bt + (size_t)nxt.pn * tstep + krev : cB;
;         for (int t = 0; t < nt; t += 2) {
;             if constexpr (Hook::ENABLED) H(acc, t, nt, ui, wr, fr);
;             const bool last = (t == nt - 2);
;             const char* a1 = cA + (long)(t + 1) * kstep;
;             const char* a2 = last ? nA : cA + (long)(t + 2) * kstep; const char* b2 = last ? nB : cB + (long)(t + 2) * kstep;
;             const char* a3 = a2 + kstep; const char* b3 = b2 + kstep;
;             if (last && has_next) S.a_ready(nxt);
;             if constexpr (SP2) {
;             PG8_LDB(B0, 0, 0); PG8_LDB(B1, 0, 1); PG8_SCHED; PG8_LDA(At, 0, 0); PG8_STAGE(PG8_SA(1, 1), a1 + hstep, voffA);
;             PG8_WAIT_V(8); PG8_WAIT_L(0); PG8_BAR; PG8_MMA(0, 0, At, B0); PG8_MMA(0, 1, At, B1); PG8_BAR; PG8_SCHED;
;             PG8_LDA(At, 0, 1); PG8_STAGE(PG8_SB(0, 0), b2, voffB); PG8_STAGE(PG8_SB(0, 1), b2 + hstep, voffB); PG8_STAGE(PG8_SA(0, 0), a2, voffA);
;             PG8_WAIT_V(8); PG8_WAIT_L(0); PG8_BAR; PG8_MMA(1, 0, At, B0); PG8_MMA(1, 1, At, B1); PG8_BAR; PG8_SCHED;
.LBB0_58:
	s_ashr_i32 s93, s92, 31
	s_lshl_b64 s[22:23], s[92:93], 20
	s_add_u32 s94, s39, s22
	s_addc_u32 s95, s40, s23
	s_and_b64 s[22:23], s[6:7], exec
	s_cselect_b32 s29, s95, s27
	s_cselect_b32 s30, s94, s26
	s_ashr_i32 s91, s90, 31
	s_lshl_b64 s[22:23], s[90:91], 20
	s_add_u32 s96, s41, s22
	s_addc_u32 s97, s42, s23
	s_and_b64 s[22:23], s[6:7], exec
	s_cselect_b32 s31, s97, s21
	s_cselect_b32 s91, s96, s20
	s_add_u32 s22, s26, 0x80080
	s_addc_u32 s23, s27, 0
	s_add_u32 s93, s20, 0x100
	s_addc_u32 s98, s21, 0
	s_mov_b32 s99, -2
	s_waitcnt vmcnt(0)
	s_add_u32 s20, s22, 0xfff80080
	s_addc_u32 s21, s23, -1
	s_add_i32 s46, 0, 0x10000
	s_cmp_eq_u32 s99, 28
	s_cselect_b32 s27, s29, s21
	s_cselect_b32 s26, s30, s20
	s_cselect_b32 s21, s31, s98
	s_cselect_b32 s20, s91, s93
	s_add_i32 s58, 0, 0x14000
	v_add_u32_e32 v108, s46, v164
	v_add_u32_e32 v128, s58, v164
	ds_read_b128 v[96:99], v108
	ds_read_b128 v[100:103], v108 offset:1024
	ds_read_b128 v[104:107], v108 offset:2048
	ds_read_b128 v[108:111], v108 offset:3072
	ds_read_b128 v[182:185], v128
	ds_read_b128 v[186:189], v128 offset:1024
	ds_read_b128 v[190:193], v128 offset:2048
	ds_read_b128 v[194:197], v128 offset:3072
	v_lshl_add_u64 v[162:163], s[22:23], 0, v[158:159]
	s_add_i32 m0, s43, 0xc000
	ds_read_b128 v[200:203], v167
	ds_read_b128 v[204:207], v167 offset:1024
	ds_read_b128 v[210:213], v167 offset:2048
	ds_read_b128 v[226:229], v167 offset:3072
	ds_read_b128 v[230:233], v167 offset:4096
	ds_read_b128 v[234:237], v167 offset:5120
	ds_read_b128 v[238:241], v167 offset:6144
	ds_read_b128 v[242:245], v167 offset:7168
	global_load_lds_dwordx4 v[162:163], off
	v_lshl_add_u64 v[162:163], s[22:23], 0, v[160:161]
	s_add_i32 m0, s43, 0xe000
	s_nop 0
	global_load_lds_dwordx4 v[162:163], off
	s_waitcnt vmcnt(8)
	s_waitcnt lgkmcnt(0)
	s_setprio 1
	s_cmp_eq_u32 s32, 0
	s_cbranch_scc1 .Lrs_0
	s_barrier
	s_setprio 2
.Lrs_0:
	v_mfma_f32_16x16x32_bf16 v[142:145], v[96:99], v[200:203], 0
	v_mfma_f32_16x16x32_bf16 v[142:145], v[100:103], v[204:207], v[142:145]
	v_mfma_f32_16x16x32_bf16 v[138:141], v[108:111], v[204:207], 0
	v_mfma_f32_16x16x32_bf16 v[138:141], v[104:107], v[200:203], v[138:141]
	v_mfma_f32_16x16x32_bf16 v[130:133], v[182:185], v[200:203], 0
	v_mfma_f32_16x16x32_bf16 v[130:133], v[186:189], v[204:207], v[130:133]
	v_mfma_f32_16x16x32_bf16 v[134:137], v[194:197], v[204:207], 0
	v_mfma_f32_16x16x32_bf16 v[134:137], v[190:193], v[200:203], v[134:137]
	v_mfma_f32_16x16x32_bf16 v[124:127], v[190:193], v[210:213], 0
	v_mfma_f32_16x16x32_bf16 v[124:127], v[194:197], v[226:229], v[124:127]
	v_mfma_f32_16x16x32_bf16 v[112:115], v[186:189], v[226:229], 0
	v_mfma_f32_16x16x32_bf16 v[112:115], v[182:185], v[210:213], v[112:115]
	v_mfma_f32_16x16x32_bf16 v[120:123], v[104:107], v[210:213], 0
	v_mfma_f32_16x16x32_bf16 v[120:123], v[108:111], v[226:229], v[120:123]
	v_mfma_f32_16x16x32_bf16 v[116:119], v[100:103], v[226:229], 0
	v_mfma_f32_16x16x32_bf16 v[116:119], v[96:99], v[210:213], v[116:119]
	v_mfma_f32_16x16x32_bf16 v[84:87], v[96:99], v[230:233], 0
	v_mfma_f32_16x16x32_bf16 v[84:87], v[100:103], v[234:237], v[84:87]
	v_mfma_f32_16x16x32_bf16 v[88:91], v[108:111], v[234:237], 0
	v_mfma_f32_16x16x32_bf16 v[88:91], v[104:107], v[230:233], v[88:91]
	v_mfma_f32_16x16x32_bf16 v[80:83], v[182:185], v[230:233], 0
	v_mfma_f32_16x16x32_bf16 v[80:83], v[186:189], v[234:237], v[80:83]
	v_mfma_f32_16x16x32_bf16 v[92:95], v[194:197], v[234:237], 0
	v_mfma_f32_16x16x32_bf16 v[92:95], v[190:193], v[230:233], v[92:95]
	v_mfma_f32_16x16x32_bf16 v[76:79], v[190:193], v[238:241], 0
	v_mfma_f32_16x16x32_bf16 v[76:79], v[194:197], v[242:245], v[76:79]
	v_mfma_f32_16x16x32_bf16 v[64:67], v[186:189], v[242:245], 0
	v_mfma_f32_16x16x32_bf16 v[64:67], v[182:185], v[238:241], v[64:67]
	v_mfma_f32_16x16x32_bf16 v[72:75], v[104:107], v[238:241], 0
	v_mfma_f32_16x16x32_bf16 v[72:75], v[108:111], v[242:245], v[72:75]
	v_mfma_f32_16x16x32_bf16 v[68:71], v[100:103], v[242:245], 0
	v_mfma_f32_16x16x32_bf16 v[68:71], v[96:99], v[238:241], v[68:71]
	s_cmp_lg_u32 s32, 0
	s_cbranch_scc1 .Lrs_1
	s_barrier
.Lrs_1:
	s_setprio 0
	s_add_i32 s46, s46, s38
	v_lshl_add_u64 v[162:163], s[20:21], 0, v[150:151]
	s_mov_b32 m0, s46
	ds_read_b128 v[200:203], v167 offset:16384
	ds_read_b128 v[204:207], v167 offset:17408
	ds_read_b128 v[210:213], v167 offset:18432
	ds_read_b128 v[226:229], v167 offset:19456
	ds_read_b128 v[230:233], v167 offset:20480
	ds_read_b128 v[234:237], v167 offset:21504
	ds_read_b128 v[238:241], v167 offset:22528
	ds_read_b128 v[242:245], v167 offset:23552
	global_load_lds_dwordx4 v[162:163], off
	s_add_i32 m0, s46, 0x2000
	s_add_u32 s56, s20, 0x80000
	v_lshl_add_u64 v[168:169], s[20:21], 0, v[146:147]
	s_addc_u32 s57, s21, 0
	s_add_i32 s46, s58, s38
	global_load_lds_dwordx4 v[168:169], off
	v_lshl_add_u64 v[214:215], s[56:57], 0, v[150:151]
	s_mov_b32 m0, s46
	v_lshl_add_u64 v[246:247], s[26:27], 0, v[148:149]
	global_load_lds_dwordx4 v[214:215], off
	v_lshl_add_u64 v[214:215], s[56:57], 0, v[146:147]
	s_add_i32 m0, s46, 0x2000
	s_nop 0
	global_load_lds_dwordx4 v[214:215], off
	v_lshl_add_u64 v[214:215], s[26:27], 0, v[152:153]
	s_mov_b32 m0, s43
	s_nop 0
	global_load_lds_dwordx4 v[214:215], off
	s_mov_b32 m0, s75
	s_nop 0
	global_load_lds_dwordx4 v[246:247], off
	s_waitcnt vmcnt(8)
	s_waitcnt lgkmcnt(0)
	s_setprio 1
	s_cmp_eq_u32 s32, 0
	s_cbranch_scc1 .Lrs_2
	s_barrier
	s_setprio 2
; #define PG8_STAGE(bufoff, gbase, voff) do { _Pragma("unroll") for (int _i = 0; _i < 2; ++_i) \
;         __builtin_amdgcn_global_load_lds((const unsigned*)((const char*)(gbase) + (voff)[_i]), (PG8_LAS unsigned*)(lds + (bufoff) + ldsw + _i * 8192), 16, 0, 0); } while (0)
; #define PG8_LDA(dst, b, h) do { _Pragma("unroll") for (int m = 0; m < 4; ++m) _Pragma("unroll") for (int k = 0; k < 2; ++k) dst[m][k] = *(const PG8_LAS bf16x8*)(lds + PG8_SA(b, h) + aoff + m * 2048 + k * 1024); } while (0)
; #define PG8_LDB(dst, b, h) do { _Pragma("unroll") for (int n = 0; n < 2; ++n) _Pragma("unroll") for (int k = 0; k < 2; ++k) dst[n][k] = *(const PG8_LAS bf16x8*)(lds + PG8_SB(b, h) + boff + n * 2048 + k * 1024); } while (0)
; #define PG8_MMA(ai, bj, At, Bt) do { __builtin_amdgcn_s_setprio(1); _Pragma("unroll") for (int m = 0; m < 4; ++m) _Pragma("unroll") for (int n = 0; n < 2; ++n) _Pragma("unroll") for (int k = 0; k < 2; ++k) \
;         acc[ai][bj][m][n] = __builtin_amdgcn_mfma_f32_16x16x32_bf16(Bt[n][k], At[m][k], acc[ai][bj][m][n], 0, 0, 0); __builtin_amdgcn_s_setprio(0); } while (0)
; #define PG8_WAIT_V(n) asm volatile("s_waitcnt vmcnt(" #n ")" ::: "memory")
; #define PG8_WAIT_L(n) asm volatile("s_waitcnt lgkmcnt(" #n ")" ::: "memory")
; #define PG8_BAR __builtin_amdgcn_s_barrier()
; #define PG8_SCHED __builtin_amdgcn_sched_barrier(0)
; template <class Epi, class Sched, bool ALIGN_EPI = false, bool SP2 = false, class Hook = NoHook, bool REVK = false>
; __device__ __forceinline__ void gemm_phase(PG8_LAS unsigned char* lds, const Gemm g, const Sched& S, const Epi& E, const Hook H = Hook()) {
;     ...
;             PG8_WAIT_V(8); PG8_WAIT_L(0); PG8_BAR; PG8_MMA(1, 0, At, B0); PG8_MMA(1, 1, At, B1); PG8_BAR; PG8_SCHED;
;             PG8_LDB(B0, 1, 0); PG8_LDB(B1, 1, 1); PG8_SCHED; PG8_LDA(At, 1, 0); PG8_STAGE(PG8_SA(0, 1), a2 + hstep, voffA);
;             PG8_WAIT_V(8); PG8_WAIT_L(0); PG8_BAR; PG8_MMA(0, 0, At, B0); PG8_MMA(0, 1, At, B1); PG8_BAR; PG8_SCHED;
;             PG8_LDA(At, 1, 1); PG8_STAGE(PG8_SB(1, 0), b3, voffB); PG8_STAGE(PG8_SB(1, 1), b3 + hstep, voffB); PG8_STAGE(PG8_SA(1, 0), a3, voffA);
.Lrs_2:
	v_mfma_f32_16x16x32_bf16 v[52:55], v[96:99], v[200:203], 0
	v_mfma_f32_16x16x32_bf16 v[52:55], v[100:103], v[204:207], v[52:55]
	v_mfma_f32_16x16x32_bf16 v[56:59], v[108:111], v[204:207], 0
	v_mfma_f32_16x16x32_bf16 v[56:59], v[104:107], v[200:203], v[56:59]
	v_mfma_f32_16x16x32_bf16 v[48:51], v[182:185], v[200:203], 0
	v_mfma_f32_16x16x32_bf16 v[48:51], v[186:189], v[204:207], v[48:51]
	v_mfma_f32_16x16x32_bf16 v[60:63], v[194:197], v[204:207], 0
	v_mfma_f32_16x16x32_bf16 v[60:63], v[190:193], v[200:203], v[60:63]
	v_mfma_f32_16x16x32_bf16 v[44:47], v[190:193], v[210:213], 0
	v_mfma_f32_16x16x32_bf16 v[44:47], v[194:197], v[226:229], v[44:47]
	v_mfma_f32_16x16x32_bf16 v[32:35], v[186:189], v[226:229], 0
	v_mfma_f32_16x16x32_bf16 v[32:35], v[182:185], v[210:213], v[32:35]
	v_mfma_f32_16x16x32_bf16 v[40:43], v[104:107], v[210:213], 0
	v_mfma_f32_16x16x32_bf16 v[40:43], v[108:111], v[226:229], v[40:43]
	v_mfma_f32_16x16x32_bf16 v[36:39], v[100:103], v[226:229], 0
	v_mfma_f32_16x16x32_bf16 v[36:39], v[96:99], v[210:213], v[36:39]
	v_mfma_f32_16x16x32_bf16 v[20:23], v[96:99], v[230:233], 0
	v_mfma_f32_16x16x32_bf16 v[20:23], v[100:103], v[234:237], v[20:23]
	v_mfma_f32_16x16x32_bf16 v[24:27], v[108:111], v[234:237], 0
	v_mfma_f32_16x16x32_bf16 v[24:27], v[104:107], v[230:233], v[24:27]
	v_mfma_f32_16x16x32_bf16 v[16:19], v[182:185], v[230:233], 0
	v_mfma_f32_16x16x32_bf16 v[16:19], v[186:189], v[234:237], v[16:19]
	v_mfma_f32_16x16x32_bf16 v[28:31], v[194:197], v[234:237], 0
	v_mfma_f32_16x16x32_bf16 v[28:31], v[190:193], v[230:233], v[28:31]
	v_mfma_f32_16x16x32_bf16 v[12:15], v[190:193], v[238:241], 0
	v_mfma_f32_16x16x32_bf16 v[12:15], v[194:197], v[242:245], v[12:15]
	v_mfma_f32_16x16x32_bf16 v[0:3], v[186:189], v[242:245], 0
	v_mfma_f32_16x16x32_bf16 v[0:3], v[182:185], v[238:241], v[0:3]
	v_mfma_f32_16x16x32_bf16 v[8:11], v[104:107], v[238:241], 0
	v_mfma_f32_16x16x32_bf16 v[8:11], v[108:111], v[242:245], v[8:11]
	v_mfma_f32_16x16x32_bf16 v[4:7], v[100:103], v[242:245], 0
	v_mfma_f32_16x16x32_bf16 v[4:7], v[96:99], v[238:241], v[4:7]
	s_cmp_lg_u32 s32, 0
	s_cbranch_scc1 .Lrs_3
	s_barrier
.Lrs_3:
	s_setprio 0
	s_add_i32 s46, 0, 0x18000
	s_add_i32 s56, 0, 0x1c000
	v_add_u32_e32 v108, s46, v164
	v_add_u32_e32 v128, s56, v164
	ds_read_b128 v[96:99], v108
	ds_read_b128 v[100:103], v108 offset:1024
	ds_read_b128 v[104:107], v108 offset:2048
	ds_read_b128 v[108:111], v108 offset:3072
	ds_read_b128 v[182:185], v128
	ds_read_b128 v[186:189], v128 offset:1024
	ds_read_b128 v[190:193], v128 offset:2048
	ds_read_b128 v[194:197], v128 offset:3072
	s_add_u32 s26, s26, 0x80000
	s_addc_u32 s27, s27, 0
	s_mov_b32 m0, s77
	v_lshl_add_u64 v[248:249], s[26:27], 0, v[152:153]
	ds_read_b128 v[200:203], v167 offset:32768
	ds_read_b128 v[204:207], v167 offset:33792
	ds_read_b128 v[210:213], v167 offset:34816
	ds_read_b128 v[226:229], v167 offset:35840
	ds_read_b128 v[230:233], v167 offset:36864
	ds_read_b128 v[234:237], v167 offset:37888
	ds_read_b128 v[238:241], v167 offset:38912
	ds_read_b128 v[242:245], v167 offset:39936
	global_load_lds_dwordx4 v[248:249], off
	v_lshl_add_u64 v[248:249], s[26:27], 0, v[148:149]
	s_mov_b32 m0, s79
	s_nop 0
	global_load_lds_dwordx4 v[248:249], off
	s_waitcnt vmcnt(8)
	s_waitcnt lgkmcnt(0)
	s_setprio 1
	s_cmp_eq_u32 s32, 0
	s_cbranch_scc1 .Lrs_4
	s_barrier
	s_setprio 2
.Lrs_4:
	v_mfma_f32_16x16x32_bf16 v[142:145], v[96:99], v[200:203], v[142:145]
	v_mfma_f32_16x16x32_bf16 v[142:145], v[100:103], v[204:207], v[142:145]
	v_mfma_f32_16x16x32_bf16 v[138:141], v[108:111], v[204:207], v[138:141]
	v_mfma_f32_16x16x32_bf16 v[138:141], v[104:107], v[200:203], v[138:141]
	v_mfma_f32_16x16x32_bf16 v[130:133], v[182:185], v[200:203], v[130:133]
	v_mfma_f32_16x16x32_bf16 v[130:133], v[186:189], v[204:207], v[130:133]
	v_mfma_f32_16x16x32_bf16 v[134:137], v[194:197], v[204:207], v[134:137]
	v_mfma_f32_16x16x32_bf16 v[134:137], v[190:193], v[200:203], v[134:137]
	v_mfma_f32_16x16x32_bf16 v[124:127], v[190:193], v[210:213], v[124:127]
	v_mfma_f32_16x16x32_bf16 v[124:127], v[194:197], v[226:229], v[124:127]
	v_mfma_f32_16x16x32_bf16 v[112:115], v[186:189], v[226:229], v[112:115]
	v_mfma_f32_16x16x32_bf16 v[112:115], v[182:185], v[210:213], v[112:115]
	v_mfma_f32_16x16x32_bf16 v[120:123], v[104:107], v[210:213], v[120:123]
	v_mfma_f32_16x16x32_bf16 v[120:123], v[108:111], v[226:229], v[120:123]
	v_mfma_f32_16x16x32_bf16 v[116:119], v[100:103], v[226:229], v[116:119]
	v_mfma_f32_16x16x32_bf16 v[116:119], v[96:99], v[210:213], v[116:119]
	v_mfma_f32_16x16x32_bf16 v[84:87], v[96:99], v[230:233], v[84:87]
	v_mfma_f32_16x16x32_bf16 v[84:87], v[100:103], v[234:237], v[84:87]
	v_mfma_f32_16x16x32_bf16 v[88:91], v[108:111], v[234:237], v[88:91]
	v_mfma_f32_16x16x32_bf16 v[88:91], v[104:107], v[230:233], v[88:91]
	v_mfma_f32_16x16x32_bf16 v[80:83], v[182:185], v[230:233], v[80:83]
	v_mfma_f32_16x16x32_bf16 v[80:83], v[186:189], v[234:237], v[80:83]
	v_mfma_f32_16x16x32_bf16 v[92:95], v[194:197], v[234:237], v[92:95]
	v_mfma_f32_16x16x32_bf16 v[92:95], v[190:193], v[230:233], v[92:95]
	v_mfma_f32_16x16x32_bf16 v[76:79], v[190:193], v[238:241], v[76:79]
	v_mfma_f32_16x16x32_bf16 v[76:79], v[194:197], v[242:245], v[76:79]
	v_mfma_f32_16x16x32_bf16 v[64:67], v[186:189], v[242:245], v[64:67]
	v_mfma_f32_16x16x32_bf16 v[64:67], v[182:185], v[238:241], v[64:67]
	v_mfma_f32_16x16x32_bf16 v[72:75], v[104:107], v[238:241], v[72:75]
	v_mfma_f32_16x16x32_bf16 v[72:75], v[108:111], v[242:245], v[72:75]
	v_mfma_f32_16x16x32_bf16 v[68:71], v[100:103], v[242:245], v[68:71]
	v_mfma_f32_16x16x32_bf16 v[68:71], v[96:99], v[238:241], v[68:71]
	s_cmp_lg_u32 s32, 0
	s_cbranch_scc1 .Lrs_5
	s_barrier
; #define PG8_STAGE(bufoff, gbase, voff) do { _Pragma("unroll") for (int _i = 0; _i < 2; ++_i) \
;         __builtin_amdgcn_global_load_lds((const unsigned*)((const char*)(gbase) + (voff)[_i]), (PG8_LAS unsigned*)(lds + (bufoff) + ldsw + _i * 8192), 16, 0, 0); } while (0)
; #define PG8_LDA(dst, b, h) do { _Pragma("unroll") for (int m = 0; m < 4; ++m) _Pragma("unroll") for (int k = 0; k < 2; ++k) dst[m][k] = *(const PG8_LAS bf16x8*)(lds + PG8_SA(b, h) + aoff + m * 2048 + k * 1024); } while (0)
; #define PG8_LDB(dst, b, h) do { _Pragma("unroll") for (int n = 0; n < 2; ++n) _Pragma("unroll") for (int k = 0; k < 2; ++k) dst[n][k] = *(const PG8_LAS bf16x8*)(lds + PG8_SB(b, h) + boff + n * 2048 + k * 1024); } while (0)
; #define PG8_MMA(ai, bj, At, Bt) do { __builtin_amdgcn_s_setprio(1); _Pragma("unroll") for (int m = 0; m < 4; ++m) _Pragma("unroll") for (int n = 0; n < 2; ++n) _Pragma("unroll") for (int k = 0; k < 2; ++k) \
;         acc[ai][bj][m][n] = __builtin_amdgcn_mfma_f32_16x16x32_bf16(Bt[n][k], At[m][k], acc[ai][bj][m][n], 0, 0, 0); __builtin_amdgcn_s_setprio(0); } while (0)
; template <class Epi, class Sched, bool ALIGN_EPI = false, bool SP2 = false, class Hook = NoHook, bool REVK = false>
; __device__ __forceinline__ void gemm_phase(PG8_LAS unsigned char* lds, const Gemm g, const Sched& S, const Epi& E, const Hook H = Hook()) {
;     ...
;             PG8_LDB(B0, 0, 0); PG8_LDB(B1, 0, 1); PG8_SCHED; PG8_LDA(At, 0, 0); PG8_STAGE(PG8_SA(1, 1), a1 + hstep, voffA);
;             PG8_WAIT_V(8); PG8_WAIT_L(0); PG8_BAR; PG8_MMA(0, 0, At, B0); PG8_MMA(0, 1, At, B1); PG8_BAR; PG8_SCHED;
;             PG8_LDA(At, 0, 1); PG8_STAGE(PG8_SB(0, 0), b2, voffB); PG8_STAGE(PG8_SB(0, 1), b2 + hstep, voffB); PG8_STAGE(PG8_SA(0, 0), a2, voffA);
;             PG8_WAIT_V(8); PG8_WAIT_L(0); PG8_BAR; PG8_MMA(1, 0, At, B0); PG8_MMA(1, 1, At, B1); PG8_BAR; PG8_SCHED;
;             PG8_LDB(B0, 1, 0); PG8_LDB(B1, 1, 1); PG8_SCHED; PG8_LDA(At, 1, 0); PG8_STAGE(PG8_SA(0, 1), a2 + hstep, voffA);
;             PG8_WAIT_V(8); PG8_WAIT_L(0); PG8_BAR; PG8_MMA(0, 0, At, B0); PG8_MMA(0, 1, At, B1); PG8_BAR; PG8_SCHED;
;             PG8_LDA(At, 1, 1); PG8_STAGE(PG8_SB(1, 0), b3, voffB); PG8_STAGE(PG8_SB(1, 1), b3 + hstep, voffB); PG8_STAGE(PG8_SA(1, 0), a3, voffA);
;             PG8_WAIT_V(8); PG8_WAIT_L(0); PG8_BAR; PG8_MMA(1, 0, At, B0); PG8_MMA(1, 1, At, B1); PG8_BAR; PG8_SCHED;
.Lrs_5:
	s_setprio 0
	s_add_i32 s26, s46, s38
	v_lshl_add_u64 v[162:163], v[162:163], 0, s[64:65]
	s_mov_b32 m0, s26
	ds_read_b128 v[200:203], v167 offset:49152
	ds_read_b128 v[204:207], v167 offset:50176
	ds_read_b128 v[210:213], v167 offset:51200
	ds_read_b128 v[226:229], v167 offset:52224
	ds_read_b128 v[230:233], v167 offset:53248
	ds_read_b128 v[234:237], v167 offset:54272
	ds_read_b128 v[238:241], v167 offset:55296
	ds_read_b128 v[242:245], v167 offset:56320
	global_load_lds_dwordx4 v[162:163], off
	s_add_i32 m0, s26, 0x2000
	s_add_u32 s20, s20, 0x80080
	v_lshl_add_u64 v[162:163], v[168:169], 0, s[64:65]
	s_addc_u32 s21, s21, 0
	s_add_i32 s26, s56, s38
	global_load_lds_dwordx4 v[162:163], off
	v_lshl_add_u64 v[162:163], s[20:21], 0, v[150:151]
	s_mov_b32 m0, s26
	s_nop 0
	global_load_lds_dwordx4 v[162:163], off
	v_lshl_add_u64 v[162:163], s[20:21], 0, v[146:147]
	s_add_i32 m0, s26, 0x2000
	s_nop 0
	global_load_lds_dwordx4 v[162:163], off
	v_lshl_add_u64 v[162:163], v[214:215], 0, s[64:65]
	s_mov_b32 m0, s44
	s_nop 0
	global_load_lds_dwordx4 v[162:163], off
	v_lshl_add_u64 v[162:163], v[246:247], 0, s[64:65]
	s_mov_b32 m0, s36
	s_nop 0
	global_load_lds_dwordx4 v[162:163], off
	s_waitcnt vmcnt(8)
	s_waitcnt lgkmcnt(0)
	s_setprio 1
	s_cmp_eq_u32 s32, 0
	s_cbranch_scc1 .Lrs_6
	s_barrier
	s_setprio 2
.Lrs_6:
	v_mfma_f32_16x16x32_bf16 v[52:55], v[96:99], v[200:203], v[52:55]
	v_mfma_f32_16x16x32_bf16 v[52:55], v[100:103], v[204:207], v[52:55]
	v_mfma_f32_16x16x32_bf16 v[56:59], v[108:111], v[204:207], v[56:59]
	v_mfma_f32_16x16x32_bf16 v[56:59], v[104:107], v[200:203], v[56:59]
	v_mfma_f32_16x16x32_bf16 v[48:51], v[182:185], v[200:203], v[48:51]
	v_mfma_f32_16x16x32_bf16 v[48:51], v[186:189], v[204:207], v[48:51]
	v_mfma_f32_16x16x32_bf16 v[60:63], v[194:197], v[204:207], v[60:63]
	v_mfma_f32_16x16x32_bf16 v[60:63], v[190:193], v[200:203], v[60:63]
	v_mfma_f32_16x16x32_bf16 v[44:47], v[190:193], v[210:213], v[44:47]
	v_mfma_f32_16x16x32_bf16 v[44:47], v[194:197], v[226:229], v[44:47]
	v_mfma_f32_16x16x32_bf16 v[32:35], v[186:189], v[226:229], v[32:35]
	v_mfma_f32_16x16x32_bf16 v[32:35], v[182:185], v[210:213], v[32:35]
	v_mfma_f32_16x16x32_bf16 v[40:43], v[104:107], v[210:213], v[40:43]
	v_mfma_f32_16x16x32_bf16 v[40:43], v[108:111], v[226:229], v[40:43]
	v_mfma_f32_16x16x32_bf16 v[36:39], v[100:103], v[226:229], v[36:39]
	v_mfma_f32_16x16x32_bf16 v[36:39], v[96:99], v[210:213], v[36:39]
	v_mfma_f32_16x16x32_bf16 v[20:23], v[96:99], v[230:233], v[20:23]
	v_mfma_f32_16x16x32_bf16 v[20:23], v[100:103], v[234:237], v[20:23]
	v_mfma_f32_16x16x32_bf16 v[24:27], v[108:111], v[234:237], v[24:27]
	v_mfma_f32_16x16x32_bf16 v[24:27], v[104:107], v[230:233], v[24:27]
	v_mfma_f32_16x16x32_bf16 v[16:19], v[182:185], v[230:233], v[16:19]
	v_mfma_f32_16x16x32_bf16 v[16:19], v[186:189], v[234:237], v[16:19]
	v_mfma_f32_16x16x32_bf16 v[28:31], v[194:197], v[234:237], v[28:31]
	v_mfma_f32_16x16x32_bf16 v[28:31], v[190:193], v[230:233], v[28:31]
	v_mfma_f32_16x16x32_bf16 v[12:15], v[190:193], v[238:241], v[12:15]
	v_mfma_f32_16x16x32_bf16 v[12:15], v[194:197], v[242:245], v[12:15]
	v_mfma_f32_16x16x32_bf16 v[0:3], v[186:189], v[242:245], v[0:3]
	v_mfma_f32_16x16x32_bf16 v[0:3], v[182:185], v[238:241], v[0:3]
	v_mfma_f32_16x16x32_bf16 v[8:11], v[104:107], v[238:241], v[8:11]
	v_mfma_f32_16x16x32_bf16 v[8:11], v[108:111], v[242:245], v[8:11]
	v_mfma_f32_16x16x32_bf16 v[4:7], v[100:103], v[242:245], v[4:7]
	v_mfma_f32_16x16x32_bf16 v[4:7], v[96:99], v[238:241], v[4:7]
	s_cmp_lg_u32 s32, 0
	s_cbranch_scc1 .Lrs_7
	s_barrier
.Lrs_7:
	s_setprio 0
	s_add_i32 s99, s99, 2
	s_add_u32 s22, s22, 0x100
	s_addc_u32 s23, s23, 0
	s_add_u32 s93, s93, 0x100
	s_addc_u32 s98, s98, 0
	s_cmp_gt_u32 s99, 29
.LBB0_59:
	s_add_u32 s20, s22, 0xfff80080
	s_addc_u32 s21, s23, -1
	s_add_i32 s46, 0, 0x10000
	s_cmp_eq_u32 s99, 28
	s_cselect_b32 s27, s29, s21
	s_cselect_b32 s26, s30, s20
	s_cselect_b32 s21, s31, s98
	s_cselect_b32 s20, s91, s93
	s_add_i32 s58, 0, 0x14000
	v_add_u32_e32 v108, s46, v164
	v_add_u32_e32 v128, s58, v164
	ds_read_b128 v[96:99], v108
	ds_read_b128 v[100:103], v108 offset:1024
	ds_read_b128 v[104:107], v108 offset:2048
	ds_read_b128 v[108:111], v108 offset:3072
	ds_read_b128 v[182:185], v128
	ds_read_b128 v[186:189], v128 offset:1024
	ds_read_b128 v[190:193], v128 offset:2048
	ds_read_b128 v[194:197], v128 offset:3072
	v_lshl_add_u64 v[162:163], s[22:23], 0, v[158:159]
	s_add_i32 m0, s43, 0xc000
	ds_read_b128 v[200:203], v167
	ds_read_b128 v[204:207], v167 offset:1024
	ds_read_b128 v[210:213], v167 offset:2048
	ds_read_b128 v[226:229], v167 offset:3072
	ds_read_b128 v[230:233], v167 offset:4096
	ds_read_b128 v[234:237], v167 offset:5120
	ds_read_b128 v[238:241], v167 offset:6144
	ds_read_b128 v[242:245], v167 offset:7168
	global_load_lds_dwordx4 v[162:163], off
	v_lshl_add_u64 v[162:163], s[22:23], 0, v[160:161]
	s_add_i32 m0, s43, 0xe000
	s_nop 0
	global_load_lds_dwordx4 v[162:163], off
	s_waitcnt vmcnt(8)
	s_waitcnt lgkmcnt(0)
	s_setprio 1
	s_cmp_eq_u32 s32, 0
	s_cbranch_scc1 .Lrs_8
	s_barrier
	s_setprio 2

; #define PG8_BAR __builtin_amdgcn_s_barrier()
;     __device__ __forceinline__ void operator()(const f32x4 (&acc)[2][2][4][2], const Unit& u, int wr, int wc, int fr, int fq, int ui) const {
;     ...
;         const int pn = u.pn, row0 = u.pm * BM + wr * 64 + fr, colh = pn * BM + 64 * wc;
;         int mode = 0, vslot = 0;
;         if (pn >= 9 && pn <= 12) mode = 1; else if (pn == 13) mode = 2; else if (pn == 14) { mode = 3; vslot = 10 + wc; }
;         else if (pn == 7 || pn == 8) { mode = 3; vslot = 2 + 4 * (pn - 7) + wc; } else if (pn == 2 && wc >= 2) { mode = 3; vslot = wc - 2; }
; template <class Epi, class Sched, bool ALIGN_EPI = false, bool SP2 = false, class Hook = NoHook, bool REVK = false>
; __device__ __forceinline__ void gemm_phase(PG8_LAS unsigned char* lds, const Gemm g, const Sched& S, const Epi& E, const Hook H = Hook()) {
;     ...
;         }
;         if constexpr (Hook::ENABLED) H(acc, nt, nt, ui, wr, fr);
;         if constexpr (ALIGN_EPI) { if (wr == 0) PG8_BAR; }
;         if constexpr (!Epi::AFTER_DRAIN) { E(acc, cur, wr, wc, fr, fq, ui); S.done(cur); }
;         if (!has_next) break;
.Lrs_15:
	s_setprio 0
	s_add_i32 s99, s99, 2
	s_add_u32 s22, s22, 0x100
	s_addc_u32 s23, s23, 0
	s_add_u32 s93, s93, 0x100
	s_addc_u32 s98, s98, 0
	s_cmp_gt_u32 s99, 29
	s_cbranch_scc0 .LBB0_59
	s_and_b64 vcc, exec, s[84:85]
	s_cbranch_vccz .LBB0_62
.LBB0_62:
	s_nop 7
	s_nop 7
	s_lshl_b32 s46, s28, 8
	s_lshl_b32 s20, s11, 8
	s_add_i32 s46, s46, s81
	s_or_b32 s22, s20, s47
	s_add_i32 s20, s11, -9
	s_cmp_lt_u32 s20, 4
	v_or_b32_e32 v168, s46, v155
	s_cbranch_scc1 .LBB0_72
	s_mov_b64 s[30:31], -1
	s_mov_b64 s[28:29], 0
	s_cmp_lt_i32 s11, 14
	s_mov_b64 s[20:21], 0
	s_mov_b64 s[26:27], 0
	s_cbranch_scc0 .LBB0_73
	s_andn2_b64 vcc, exec, s[30:31]
	s_mov_b32 s30, 0x3e38aa3b
	s_cbranch_vccz .LBB0_74

; #define PG8_BAR __builtin_amdgcn_s_barrier()
; template <class Epi, class Sched, bool ALIGN_EPI = false, bool SP2 = false, class Hook = NoHook, bool REVK = false>
; __device__ __forceinline__ void gemm_phase(PG8_LAS unsigned char* lds, const Gemm g, const Sched& S, const Epi& E, const Hook H = Hook()) {
;     ...
;         if (!has_next) break;
; #pragma unroll
;         for (int a = 0; a < 2; ++a)
; #pragma unroll
;             for (int b = 0; b < 2; ++b)
; #pragma unroll
;                 for (int m = 0; m < 4; ++m)
; #pragma unroll
;                     for (int n = 0; n < 2; ++n) acc[a][b][m][n] = (f32x4){0.f, 0.f, 0.f, 0.f};
;         cur = nxt; cA = nA; cB = nB; ++ui;
;         if constexpr (ALIGN_EPI) { if (wr == 1) PG8_BAR; }
.LBB0_69:
	s_andn2_b64 vcc, exec, s[6:7]
	s_mov_b64 s[6:7], -1
	s_cbranch_vccnz .LBB0_55
	s_andn2_b64 vcc, exec, s[8:9]
	s_cbranch_vccnz .LBB0_54
	s_branch .LBB0_54

; template <class Epi, class Sched, bool ALIGN_EPI = false, bool SP2 = false, class Hook = NoHook, bool REVK = false>
; __device__ __forceinline__ void gemm_phase(PG8_LAS unsigned char* lds, const Gemm g, const Sched& S, const Epi& E, const Hook H = Hook()) {
;     int tid_ = threadIdx.x; asm volatile("" : "+v"(tid_));
;     const int tid = tid_, wid = __builtin_amdgcn_readfirstlane(tid >> 6), lane = tid & 63, wr = wid >> 2, wc = wid & 3, fr = lane & 15, fq = lane >> 4;
;     const int K = g.K, nt = K / BK;
;     unsigned voffA[2], voffB[2];
; #pragma unroll
;     for (int i = 0; i < 2; ++i) { int R, C; stage_rc(tid * 16 + i * 8192, R, C); const int Rb = Epi::PERM ? ((R & ~31) + perm32(R & 31)) : R;
;         voffA[i] = (unsigned)(R * K + C) * 2u; voffB[i] = (unsigned)(Rb * K + C) * 2u; }
;     const long kstep = REVK ? -(long)(BK * 2) : (long)(BK * 2);
;     const size_t krev = REVK ? (size_t)(K / BK - 1) * (size_t)(BK * 2) : 0;
;     const size_t hstep = (size_t)HALF * K * 2;
;     const size_t tstep = 2 * hstep;
;     const unsigned ldsw = (unsigned)wid * 1024u;
;     const int aoff = lds_byte(wr * 64 + fr, fq * 8), boff = lds_byte(wc * 32 + fr, fq * 8);
;     ...
;     Unit cur, nxt; int ui = 0;
;     if (!S.next(0, cur)) return;
;     f32x4 acc[2][2][4][2];
; #pragma unroll
;     for (int a = 0; a < 2; ++a)
; #pragma unroll
;         for (int b = 0; b < 2; ++b)
; #pragma unroll
;             for (int m = 0; m < 4; ++m)
; #pragma unroll
;                 for (int n = 0; n < 2; ++n) acc[a][b][m][n] = (f32x4){0.f, 0.f, 0.f, 0.f};
;     bf16x8 At[4][2], B0[2][2], B1[2][2];
;     const char* cA = (const char*)g.A + (size_t)cur.pm * tstep + krev; const char* cB = (const char*)g.Bt + (size_t)cur.pn * tstep + krev;
;     S.a_ready(cur);
;     if constexpr (SP2) {
;         PG8_STAGE(PG8_SB(0, 0), cB, voffB); PG8_STAGE(PG8_SB(0, 1), cB + hstep, voffB); PG8_STAGE(PG8_SA(0, 0), cA, voffA); PG8_STAGE(PG8_SA(0, 1), cA + hstep, voffA);
;         if (wr == 1) PG8_BAR;
;         PG8_WAIT_V(2); PG8_BAR;
;         PG8_STAGE(PG8_SB(1, 0), cB + kstep, voffB); PG8_STAGE(PG8_SA(1, 0), cA + kstep, voffA); PG8_STAGE(PG8_SB(1, 1), cB + hstep + kstep, voffB);
;         PG8_WAIT_V(6); PG8_BAR;
;     } else {
;         PG8_STAGE(PG8_SB(0, 0), cB, voffB); PG8_STAGE(PG8_SA(0, 0), cA, voffA); PG8_STAGE(PG8_SB(0, 1), cB + hstep, voffB); PG8_STAGE(PG8_SA(0, 1), cA + hstep, voffA);
.LBB0_460:
	v_readlane_b32 s4, v250, 48
	v_mov_b32_e32 v14, v199
	v_readlane_b32 s5, v250, 49
	s_lshl_b32 s54, s74, 15
	s_waitcnt lgkmcnt(0)
	s_barrier
	s_and_b64 vcc, exec, s[4:5]
	v_readfirstlane_b32 s4, v14
	s_cbranch_vccnz .LBB0_504
	v_lshlrev_b32_e32 v0, 4, v14
	v_add_u32_e32 v1, 0x2000, v0
	v_ashrrev_i32_e32 v2, 31, v1
	v_lshrrev_b32_e32 v2, 22, v2
	v_add_u32_e32 v2, v1, v2
	v_ashrrev_i32_e32 v8, 10, v2
	v_mul_i32_i24_e32 v2, 0x400, v8
	v_sub_u32_e32 v1, v1, v2
	v_lshrrev_b32_e32 v2, 4, v1
	s_ashr_i32 s5, s4, 6
	v_bitop3_b32 v1, v2, v1, 32 bitop3:0x6c
	s_ashr_i32 s6, s4, 8
	s_lshl_b32 s24, s5, 10
	v_ashrrev_i32_e32 v2, 31, v1
	s_add_u32 s28, s22, 0x23000000
	v_lshrrev_b32_e32 v2, 26, v2
	s_addc_u32 s29, s23, 0
	s_lshl_b64 s[8:9], s[74:75], 23
	v_add_u32_e32 v2, v1, v2
	v_lshlrev_b32_e32 v3, 3, v8
	s_add_u32 s7, s22, s8
	v_ashrrev_i32_e32 v9, 6, v2
	v_and_b32_e32 v3, -16, v3
	s_addc_u32 s8, s23, s9
	v_add_u32_e32 v3, v9, v3
	s_add_u32 s30, s7, 0x3c00000
	v_and_b32_e32 v4, 3, v9
	s_mov_b32 s7, 0xfffe0
	v_lshrrev_b32_e32 v5, 2, v3
	v_lshlrev_b32_e32 v6, 1, v3
	v_and_b32_e32 v2, 0xc0, v2
	v_and_or_b32 v4, v3, s7, v4
	v_and_b32_e32 v5, 4, v5
	v_and_b32_e32 v6, 24, v6
	v_sub_u32_e32 v1, v1, v2
	v_or3_b32 v4, v4, v5, v6
	v_lshlrev_b32_e32 v5, 5, v8
	v_ashrrev_i16_sdwa v1, v219, sext(v1) dst_sel:DWORD dst_unused:UNUSED_PAD src0_sel:DWORD src1_sel:BYTE_0
	v_and_b32_e32 v5, 32, v5
	v_bfe_i32 v10, v1, 0, 16
	v_add_lshl_u32 v1, v5, v10, 1
	v_lshl_add_u32 v162, v4, 12, v1
	v_lshl_add_u32 v164, v3, 12, v1
	v_bfe_i32 v1, v14, 27, 1
	v_lshrrev_b32_e32 v1, 22, v1
	v_add_u32_e32 v1, v0, v1
	v_and_b32_e32 v1, 0xfffffc00, v1
	v_sub_u32_e32 v0, v0, v1
	v_lshrrev_b32_e32 v1, 4, v0
	v_ashrrev_i32_e32 v2, 31, v14
	v_bitop3_b32 v0, v1, v0, 32 bitop3:0x6c
	v_lshrrev_b32_e32 v2, 26, v2
	v_ashrrev_i32_e32 v1, 31, v0
	v_add_u32_e32 v2, v14, v2
	v_lshrrev_b32_e32 v1, 26, v1
	v_ashrrev_i32_e32 v12, 6, v2
	v_add_u32_e32 v1, v0, v1
	v_lshlrev_b32_e32 v2, 3, v12
	v_ashrrev_i32_e32 v11, 6, v1
	v_and_b32_e32 v2, -16, v2
	v_add_u32_e32 v2, v11, v2
	v_and_b32_e32 v3, 3, v11
	v_lshrrev_b32_e32 v4, 2, v2
	v_lshlrev_b32_e32 v5, 1, v2
	v_and_b32_e32 v1, 0xc0, v1
	v_and_or_b32 v3, v2, s7, v3
	v_and_b32_e32 v4, 4, v4
	v_and_b32_e32 v5, 24, v5
	v_sub_u32_e32 v0, v0, v1
	s_addc_u32 s31, s8, 0
	v_or3_b32 v3, v3, v4, v5
	v_lshlrev_b32_e32 v4, 5, v12
	v_ashrrev_i16_sdwa v0, v219, sext(v0) dst_sel:DWORD dst_unused:UNUSED_PAD src0_sel:DWORD src1_sel:BYTE_0
	v_readlane_b32 s8, v250, 30
	v_and_b32_e32 v4, 32, v4
	v_bfe_i32 v13, v0, 0, 16
	v_readlane_b32 s9, v250, 31
	s_add_u32 s20, s30, s8
	v_add_lshl_u32 v0, v4, v13, 1
	s_addc_u32 s21, s31, s9
	s_add_i32 s34, s24, 0
	v_lshl_add_u32 v166, v3, 12, v0
	s_add_i32 m0, s34, 0x10000
	v_lshl_add_u32 v168, v2, 12, v0
	global_load_lds_dwordx4 v166, s[20:21]
	s_add_i32 m0, s34, 0x12000
	s_add_u32 s8, s20, 0x80000
	global_load_lds_dwordx4 v162, s[20:21]
	s_addc_u32 s9, s21, 0
	s_add_i32 m0, s34, 0x14000
	v_mov_b32_e32 v167, v129
	global_load_lds_dwordx4 v166, s[8:9]
	s_add_i32 m0, s34, 0x16000
	v_mov_b32_e32 v163, v129
	global_load_lds_dwordx4 v162, s[8:9]
	v_readlane_b32 s8, v250, 28
	v_readlane_b32 s9, v250, 29
	s_add_u32 s26, s28, s8
	s_addc_u32 s27, s29, s9
	s_add_i32 s35, s34, 0x2000
	s_mov_b32 m0, s34
	s_add_u32 s8, s26, 0x80000
	global_load_lds_dwordx4 v168, s[26:27]
	s_mov_b32 m0, s35
	s_addc_u32 s9, s27, 0
	s_add_i32 s36, s34, 0x4000
	global_load_lds_dwordx4 v164, s[26:27]
	s_mov_b32 m0, s36
	s_add_i32 s38, s34, 0x6000
	global_load_lds_dwordx4 v168, s[8:9]
	s_mov_b32 m0, s38
	v_mov_b32_e32 v169, v129
	global_load_lds_dwordx4 v164, s[8:9]
	v_mov_b32_e32 v165, v129
	s_cmp_eq_u32 s6, 1
	v_lshl_add_u64 v[6:7], s[20:21], 0, v[166:167]
	v_lshl_add_u64 v[4:5], s[20:21], 0, v[162:163]
	v_lshl_add_u64 v[0:1], s[26:27], 0, v[168:169]
	s_cselect_b64 s[12:13], -1, 0
	s_mov_b32 s32, s6
	s_cmp_lg_u32 s6, 1
	v_lshl_add_u64 v[2:3], s[26:27], 0, v[164:165]
	s_cbranch_scc1 .LBB0_463

; #define PG8_STAGE(bufoff, gbase, voff) do { _Pragma("unroll") for (int _i = 0; _i < 2; ++_i) \
;         __builtin_amdgcn_global_load_lds((const unsigned*)((const char*)(gbase) + (voff)[_i]), (PG8_LAS unsigned*)(lds + (bufoff) + ldsw + _i * 8192), 16, 0, 0); } while (0)
; #define PG8_LDA(dst, b, h) do { _Pragma("unroll") for (int m = 0; m < 4; ++m) _Pragma("unroll") for (int k = 0; k < 2; ++k) dst[m][k] = *(const PG8_LAS bf16x8*)(lds + PG8_SA(b, h) + aoff + m * 2048 + k * 1024); } while (0)
; #define PG8_LDB(dst, b, h) do { _Pragma("unroll") for (int n = 0; n < 2; ++n) _Pragma("unroll") for (int k = 0; k < 2; ++k) dst[n][k] = *(const PG8_LAS bf16x8*)(lds + PG8_SB(b, h) + boff + n * 2048 + k * 1024); } while (0)
; #define PG8_MMA(ai, bj, At, Bt) do { __builtin_amdgcn_s_setprio(1); _Pragma("unroll") for (int m = 0; m < 4; ++m) _Pragma("unroll") for (int n = 0; n < 2; ++n) _Pragma("unroll") for (int k = 0; k < 2; ++k) \
;         acc[ai][bj][m][n] = __builtin_amdgcn_mfma_f32_16x16x32_bf16(Bt[n][k], At[m][k], acc[ai][bj][m][n], 0, 0, 0); __builtin_amdgcn_s_setprio(0); } while (0)
; #define PG8_WAIT_V(n) asm volatile("s_waitcnt vmcnt(" #n ")" ::: "memory")
; #define PG8_BAR __builtin_amdgcn_s_barrier()
; template <class Epi, class Sched, bool ALIGN_EPI = false, bool SP2 = false, class Hook = NoHook, bool REVK = false>
; __device__ __forceinline__ void gemm_phase(PG8_LAS unsigned char* lds, const Gemm g, const Sched& S, const Epi& E, const Hook H = Hook()) {
;     ...
;             const bool last = (t == nt - 2);
;             const char* a1 = cA + (long)(t + 1) * kstep;
;             const char* a2 = last ? nA : cA + (long)(t + 2) * kstep; const char* b2 = last ? nB : cB + (long)(t + 2) * kstep;
;             const char* a3 = a2 + kstep; const char* b3 = b2 + kstep;
;             if (last && has_next) S.a_ready(nxt);
;             if constexpr (SP2) {
;             PG8_LDB(B0, 0, 0); PG8_LDB(B1, 0, 1); PG8_SCHED; PG8_LDA(At, 0, 0); PG8_STAGE(PG8_SA(1, 1), a1 + hstep, voffA);
;             PG8_WAIT_V(8); PG8_WAIT_L(0); PG8_BAR; PG8_MMA(0, 0, At, B0); PG8_MMA(0, 1, At, B1); PG8_BAR; PG8_SCHED;
;             PG8_LDA(At, 0, 1); PG8_STAGE(PG8_SB(0, 0), b2, voffB); PG8_STAGE(PG8_SB(0, 1), b2 + hstep, voffB); PG8_STAGE(PG8_SA(0, 0), a2, voffA);
;             PG8_WAIT_V(8); PG8_WAIT_L(0); PG8_BAR; PG8_MMA(1, 0, At, B0); PG8_MMA(1, 1, At, B1); PG8_BAR; PG8_SCHED;
.LBB0_477:
	s_add_u32 s20, s22, 0xfff80080
	s_addc_u32 s21, s23, -1
	s_add_i32 s46, 0, 0x10000
	s_cmp_eq_u32 s53, 30
	s_cselect_b32 s27, s11, s21
	s_cselect_b32 s26, s42, s20
	v_add_u32_e32 v128, s46, v226
	s_cselect_b32 s21, s43, s51
	s_cselect_b32 s20, s44, s47
	s_add_i32 s58, 0, 0x14000
	ds_read_b128 v[130:133], v128
	ds_read_b128 v[134:137], v128 offset:1024
	ds_read_b128 v[138:141], v128 offset:2048
	ds_read_b128 v[142:145], v128 offset:3072
	v_add_u32_e32 v128, s58, v226
	ds_read_b128 v[146:149], v128
	ds_read_b128 v[150:153], v128 offset:1024
	ds_read_b128 v[154:157], v128 offset:2048
	ds_read_b128 v[158:161], v128 offset:3072
	v_lshl_add_u64 v[196:197], s[22:23], 0, v[182:183]
	s_add_i32 m0, s34, 0xc000
	ds_read_b128 v[186:189], v229
	ds_read_b128 v[192:195], v229 offset:1024
	ds_read_b128 v[200:203], v229 offset:2048
	ds_read_b128 v[204:207], v229 offset:3072
	ds_read_b128 v[210:213], v229 offset:4096
	ds_read_b128 v[230:233], v229 offset:5120
	ds_read_b128 v[234:237], v229 offset:6144
	ds_read_b128 v[238:241], v229 offset:7168
	global_load_lds_dwordx4 v[196:197], off
	v_lshl_add_u64 v[196:197], s[22:23], 0, v[184:185]
	s_add_i32 m0, s34, 0xe000
	s_nop 0
	global_load_lds_dwordx4 v[196:197], off
	s_waitcnt vmcnt(8)
	s_waitcnt lgkmcnt(0)
	s_setprio 1
	s_cmp_eq_u32 s32, 0
	s_cbranch_scc1 .Lrs_16
	s_barrier
	s_setprio 2
.Lrs_16:
	v_mfma_f32_16x16x32_bf16 v[124:127], v[130:133], v[186:189], v[124:127]
	v_mfma_f32_16x16x32_bf16 v[124:127], v[134:137], v[192:195], v[124:127]
	v_mfma_f32_16x16x32_bf16 v[120:123], v[142:145], v[192:195], v[120:123]
	v_mfma_f32_16x16x32_bf16 v[120:123], v[138:141], v[186:189], v[120:123]
	v_mfma_f32_16x16x32_bf16 v[116:119], v[146:149], v[186:189], v[116:119]
	v_mfma_f32_16x16x32_bf16 v[116:119], v[150:153], v[192:195], v[116:119]
	v_mfma_f32_16x16x32_bf16 v[112:115], v[158:161], v[192:195], v[112:115]
	v_mfma_f32_16x16x32_bf16 v[112:115], v[154:157], v[186:189], v[112:115]
	v_mfma_f32_16x16x32_bf16 v[96:99], v[154:157], v[200:203], v[96:99]
	v_mfma_f32_16x16x32_bf16 v[96:99], v[158:161], v[204:207], v[96:99]
	v_mfma_f32_16x16x32_bf16 v[100:103], v[150:153], v[204:207], v[100:103]
	v_mfma_f32_16x16x32_bf16 v[100:103], v[146:149], v[200:203], v[100:103]
	v_mfma_f32_16x16x32_bf16 v[104:107], v[138:141], v[200:203], v[104:107]
	v_mfma_f32_16x16x32_bf16 v[104:107], v[142:145], v[204:207], v[104:107]
	v_mfma_f32_16x16x32_bf16 v[108:111], v[134:137], v[204:207], v[108:111]
	v_mfma_f32_16x16x32_bf16 v[108:111], v[130:133], v[200:203], v[108:111]
	v_mfma_f32_16x16x32_bf16 v[92:95], v[130:133], v[210:213], v[92:95]
	v_mfma_f32_16x16x32_bf16 v[92:95], v[134:137], v[230:233], v[92:95]
	v_mfma_f32_16x16x32_bf16 v[88:91], v[142:145], v[230:233], v[88:91]
	v_mfma_f32_16x16x32_bf16 v[88:91], v[138:141], v[210:213], v[88:91]
	v_mfma_f32_16x16x32_bf16 v[84:87], v[146:149], v[210:213], v[84:87]
	v_mfma_f32_16x16x32_bf16 v[84:87], v[150:153], v[230:233], v[84:87]
	v_mfma_f32_16x16x32_bf16 v[80:83], v[158:161], v[230:233], v[80:83]
	v_mfma_f32_16x16x32_bf16 v[80:83], v[154:157], v[210:213], v[80:83]
	v_mfma_f32_16x16x32_bf16 v[64:67], v[154:157], v[234:237], v[64:67]
	v_mfma_f32_16x16x32_bf16 v[64:67], v[158:161], v[238:241], v[64:67]
	v_mfma_f32_16x16x32_bf16 v[68:71], v[150:153], v[238:241], v[68:71]
	v_mfma_f32_16x16x32_bf16 v[68:71], v[146:149], v[234:237], v[68:71]
	v_mfma_f32_16x16x32_bf16 v[72:75], v[138:141], v[234:237], v[72:75]
	v_mfma_f32_16x16x32_bf16 v[72:75], v[142:145], v[238:241], v[72:75]
	v_mfma_f32_16x16x32_bf16 v[76:79], v[134:137], v[238:241], v[76:79]
	v_mfma_f32_16x16x32_bf16 v[76:79], v[130:133], v[234:237], v[76:79]
	s_cmp_lg_u32 s32, 0
	s_cbranch_scc1 .Lrs_17
	s_barrier
; #define PG8_STAGE(bufoff, gbase, voff) do { _Pragma("unroll") for (int _i = 0; _i < 2; ++_i) \
;         __builtin_amdgcn_global_load_lds((const unsigned*)((const char*)(gbase) + (voff)[_i]), (PG8_LAS unsigned*)(lds + (bufoff) + ldsw + _i * 8192), 16, 0, 0); } while (0)
; #define PG8_LDA(dst, b, h) do { _Pragma("unroll") for (int m = 0; m < 4; ++m) _Pragma("unroll") for (int k = 0; k < 2; ++k) dst[m][k] = *(const PG8_LAS bf16x8*)(lds + PG8_SA(b, h) + aoff + m * 2048 + k * 1024); } while (0)
; #define PG8_LDB(dst, b, h) do { _Pragma("unroll") for (int n = 0; n < 2; ++n) _Pragma("unroll") for (int k = 0; k < 2; ++k) dst[n][k] = *(const PG8_LAS bf16x8*)(lds + PG8_SB(b, h) + boff + n * 2048 + k * 1024); } while (0)
; #define PG8_MMA(ai, bj, At, Bt) do { __builtin_amdgcn_s_setprio(1); _Pragma("unroll") for (int m = 0; m < 4; ++m) _Pragma("unroll") for (int n = 0; n < 2; ++n) _Pragma("unroll") for (int k = 0; k < 2; ++k) \
;         acc[ai][bj][m][n] = __builtin_amdgcn_mfma_f32_16x16x32_bf16(Bt[n][k], At[m][k], acc[ai][bj][m][n], 0, 0, 0); __builtin_amdgcn_s_setprio(0); } while (0)
; #define PG8_WAIT_V(n) asm volatile("s_waitcnt vmcnt(" #n ")" ::: "memory")
; #define PG8_WAIT_L(n) asm volatile("s_waitcnt lgkmcnt(" #n ")" ::: "memory")
; #define PG8_BAR __builtin_amdgcn_s_barrier()
; #define PG8_SCHED __builtin_amdgcn_sched_barrier(0)
; template <class Epi, class Sched, bool ALIGN_EPI = false, bool SP2 = false, class Hook = NoHook, bool REVK = false>
; __device__ __forceinline__ void gemm_phase(PG8_LAS unsigned char* lds, const Gemm g, const Sched& S, const Epi& E, const Hook H = Hook()) {
;     ...
;             PG8_WAIT_V(8); PG8_WAIT_L(0); PG8_BAR; PG8_MMA(0, 0, At, B0); PG8_MMA(0, 1, At, B1); PG8_BAR; PG8_SCHED;
;             PG8_LDA(At, 0, 1); PG8_STAGE(PG8_SB(0, 0), b2, voffB); PG8_STAGE(PG8_SB(0, 1), b2 + hstep, voffB); PG8_STAGE(PG8_SA(0, 0), a2, voffA);
;             PG8_WAIT_V(8); PG8_WAIT_L(0); PG8_BAR; PG8_MMA(1, 0, At, B0); PG8_MMA(1, 1, At, B1); PG8_BAR; PG8_SCHED;
;             PG8_LDB(B0, 1, 0); PG8_LDB(B1, 1, 1); PG8_SCHED; PG8_LDA(At, 1, 0); PG8_STAGE(PG8_SA(0, 1), a2 + hstep, voffA);
;             PG8_WAIT_V(8); PG8_WAIT_L(0); PG8_BAR; PG8_MMA(0, 0, At, B0); PG8_MMA(0, 1, At, B1); PG8_BAR; PG8_SCHED;
.Lrs_17:
	s_setprio 0
	s_add_i32 s46, s46, s24
	v_lshl_add_u64 v[196:197], s[20:21], 0, v[166:167]
	s_mov_b32 m0, s46
	ds_read_b128 v[186:189], v229 offset:16384
	ds_read_b128 v[192:195], v229 offset:17408
	ds_read_b128 v[200:203], v229 offset:18432
	ds_read_b128 v[204:207], v229 offset:19456
	ds_read_b128 v[210:213], v229 offset:20480
	ds_read_b128 v[230:233], v229 offset:21504
	ds_read_b128 v[234:237], v229 offset:22528
	ds_read_b128 v[238:241], v229 offset:23552
	global_load_lds_dwordx4 v[196:197], off
	s_add_i32 m0, s46, 0x2000
	s_add_u32 s56, s20, 0x80000
	v_lshl_add_u64 v[214:215], s[20:21], 0, v[162:163]
	s_addc_u32 s57, s21, 0
	s_add_i32 s46, s58, s24
	global_load_lds_dwordx4 v[214:215], off
	v_lshl_add_u64 v[242:243], s[56:57], 0, v[166:167]
	s_mov_b32 m0, s46
	v_lshl_add_u64 v[244:245], s[26:27], 0, v[164:165]
	global_load_lds_dwordx4 v[242:243], off
	v_lshl_add_u64 v[242:243], s[56:57], 0, v[162:163]
	s_add_i32 m0, s46, 0x2000
	s_nop 0
	global_load_lds_dwordx4 v[242:243], off
	v_lshl_add_u64 v[242:243], s[26:27], 0, v[168:169]
	s_mov_b32 m0, s34
	s_nop 0
	global_load_lds_dwordx4 v[242:243], off
	s_mov_b32 m0, s35
	s_nop 0
	global_load_lds_dwordx4 v[244:245], off
	s_waitcnt vmcnt(8)
	s_waitcnt lgkmcnt(0)
	s_setprio 1
	s_cmp_eq_u32 s32, 0
	s_cbranch_scc1 .Lrs_18
	s_barrier
	s_setprio 2
.Lrs_18:
	v_mfma_f32_16x16x32_bf16 v[60:63], v[130:133], v[186:189], v[60:63]
	v_mfma_f32_16x16x32_bf16 v[60:63], v[134:137], v[192:195], v[60:63]
	v_mfma_f32_16x16x32_bf16 v[56:59], v[142:145], v[192:195], v[56:59]
	v_mfma_f32_16x16x32_bf16 v[56:59], v[138:141], v[186:189], v[56:59]
	v_mfma_f32_16x16x32_bf16 v[52:55], v[146:149], v[186:189], v[52:55]
	v_mfma_f32_16x16x32_bf16 v[52:55], v[150:153], v[192:195], v[52:55]
	v_mfma_f32_16x16x32_bf16 v[48:51], v[158:161], v[192:195], v[48:51]
	v_mfma_f32_16x16x32_bf16 v[48:51], v[154:157], v[186:189], v[48:51]
	v_mfma_f32_16x16x32_bf16 v[32:35], v[154:157], v[200:203], v[32:35]
	v_mfma_f32_16x16x32_bf16 v[32:35], v[158:161], v[204:207], v[32:35]
	v_mfma_f32_16x16x32_bf16 v[36:39], v[150:153], v[204:207], v[36:39]
	v_mfma_f32_16x16x32_bf16 v[36:39], v[146:149], v[200:203], v[36:39]
	v_mfma_f32_16x16x32_bf16 v[40:43], v[138:141], v[200:203], v[40:43]
	v_mfma_f32_16x16x32_bf16 v[40:43], v[142:145], v[204:207], v[40:43]
	v_mfma_f32_16x16x32_bf16 v[44:47], v[134:137], v[204:207], v[44:47]
	v_mfma_f32_16x16x32_bf16 v[44:47], v[130:133], v[200:203], v[44:47]
	v_mfma_f32_16x16x32_bf16 v[28:31], v[130:133], v[210:213], v[28:31]
	v_mfma_f32_16x16x32_bf16 v[28:31], v[134:137], v[230:233], v[28:31]
	v_mfma_f32_16x16x32_bf16 v[24:27], v[142:145], v[230:233], v[24:27]
	v_mfma_f32_16x16x32_bf16 v[24:27], v[138:141], v[210:213], v[24:27]
	v_mfma_f32_16x16x32_bf16 v[20:23], v[146:149], v[210:213], v[20:23]
	v_mfma_f32_16x16x32_bf16 v[20:23], v[150:153], v[230:233], v[20:23]
	v_mfma_f32_16x16x32_bf16 v[16:19], v[158:161], v[230:233], v[16:19]
	v_mfma_f32_16x16x32_bf16 v[16:19], v[154:157], v[210:213], v[16:19]
	v_mfma_f32_16x16x32_bf16 v[0:3], v[154:157], v[234:237], v[0:3]
	v_mfma_f32_16x16x32_bf16 v[0:3], v[158:161], v[238:241], v[0:3]
	v_mfma_f32_16x16x32_bf16 v[4:7], v[150:153], v[238:241], v[4:7]
	v_mfma_f32_16x16x32_bf16 v[4:7], v[146:149], v[234:237], v[4:7]
	v_mfma_f32_16x16x32_bf16 v[8:11], v[138:141], v[234:237], v[8:11]
	v_mfma_f32_16x16x32_bf16 v[8:11], v[142:145], v[238:241], v[8:11]
	v_mfma_f32_16x16x32_bf16 v[12:15], v[134:137], v[238:241], v[12:15]
	v_mfma_f32_16x16x32_bf16 v[12:15], v[130:133], v[234:237], v[12:15]
	s_cmp_lg_u32 s32, 0
	s_cbranch_scc1 .Lrs_19
	s_barrier
.Lrs_19:
	s_setprio 0
	s_add_i32 s46, 0, 0x18000
	v_add_u32_e32 v128, s46, v226
	s_add_i32 s56, 0, 0x1c000
	ds_read_b128 v[130:133], v128
	ds_read_b128 v[134:137], v128 offset:1024
	ds_read_b128 v[138:141], v128 offset:2048
	ds_read_b128 v[142:145], v128 offset:3072
	v_add_u32_e32 v128, s56, v226
	ds_read_b128 v[146:149], v128
	ds_read_b128 v[150:153], v128 offset:1024
	ds_read_b128 v[154:157], v128 offset:2048
	ds_read_b128 v[158:161], v128 offset:3072
	s_add_u32 s26, s26, 0x80000
	s_addc_u32 s27, s27, 0
	s_mov_b32 m0, s36
	v_lshl_add_u64 v[246:247], s[26:27], 0, v[168:169]
	ds_read_b128 v[186:189], v229 offset:32768
	ds_read_b128 v[192:195], v229 offset:33792
	ds_read_b128 v[200:203], v229 offset:34816
	ds_read_b128 v[204:207], v229 offset:35840
	ds_read_b128 v[210:213], v229 offset:36864
	ds_read_b128 v[230:233], v229 offset:37888
	ds_read_b128 v[234:237], v229 offset:38912
	ds_read_b128 v[238:241], v229 offset:39936
	global_load_lds_dwordx4 v[246:247], off
	v_lshl_add_u64 v[246:247], s[26:27], 0, v[164:165]
	s_mov_b32 m0, s38
	s_nop 0
	global_load_lds_dwordx4 v[246:247], off
	s_waitcnt vmcnt(8)
	s_waitcnt lgkmcnt(0)
	s_setprio 1
	s_cmp_eq_u32 s32, 0
	s_cbranch_scc1 .Lrs_20
	s_barrier
	s_setprio 2

; #define PG8_STAGE(bufoff, gbase, voff) do { _Pragma("unroll") for (int _i = 0; _i < 2; ++_i) \
;         __builtin_amdgcn_global_load_lds((const unsigned*)((const char*)(gbase) + (voff)[_i]), (PG8_LAS unsigned*)(lds + (bufoff) + ldsw + _i * 8192), 16, 0, 0); } while (0)
; #define PG8_LDA(dst, b, h) do { _Pragma("unroll") for (int m = 0; m < 4; ++m) _Pragma("unroll") for (int k = 0; k < 2; ++k) dst[m][k] = *(const PG8_LAS bf16x8*)(lds + PG8_SA(b, h) + aoff + m * 2048 + k * 1024); } while (0)
; #define PG8_MMA(ai, bj, At, Bt) do { __builtin_amdgcn_s_setprio(1); _Pragma("unroll") for (int m = 0; m < 4; ++m) _Pragma("unroll") for (int n = 0; n < 2; ++n) _Pragma("unroll") for (int k = 0; k < 2; ++k) \
;         acc[ai][bj][m][n] = __builtin_amdgcn_mfma_f32_16x16x32_bf16(Bt[n][k], At[m][k], acc[ai][bj][m][n], 0, 0, 0); __builtin_amdgcn_s_setprio(0); } while (0)
; #define PG8_WAIT_V(n) asm volatile("s_waitcnt vmcnt(" #n ")" ::: "memory")
; #define PG8_WAIT_L(n) asm volatile("s_waitcnt lgkmcnt(" #n ")" ::: "memory")
; #define PG8_BAR __builtin_amdgcn_s_barrier()
; #define PG8_SCHED __builtin_amdgcn_sched_barrier(0)
; template <class Epi, class Sched, bool ALIGN_EPI = false, bool SP2 = false, class Hook = NoHook, bool REVK = false>
; __device__ __forceinline__ void gemm_phase(PG8_LAS unsigned char* lds, const Gemm g, const Sched& S, const Epi& E, const Hook H = Hook()) {
;     ...
;             PG8_LDA(At, 1, 1); PG8_STAGE(PG8_SB(1, 0), b3, voffB); PG8_STAGE(PG8_SB(1, 1), b3 + hstep, voffB); PG8_STAGE(PG8_SA(1, 0), a3, voffA);
;             PG8_WAIT_V(8); PG8_WAIT_L(0); PG8_BAR; PG8_MMA(1, 0, At, B0); PG8_MMA(1, 1, At, B1); PG8_BAR; PG8_SCHED;
.Lrs_21:
	s_setprio 0
	s_add_i32 s26, s46, s24
	v_lshl_add_u64 v[196:197], v[196:197], 0, s[64:65]
	s_mov_b32 m0, s26
	ds_read_b128 v[186:189], v229 offset:49152
	ds_read_b128 v[192:195], v229 offset:50176
	ds_read_b128 v[200:203], v229 offset:51200
	ds_read_b128 v[204:207], v229 offset:52224
	ds_read_b128 v[210:213], v229 offset:53248
	ds_read_b128 v[230:233], v229 offset:54272
	ds_read_b128 v[234:237], v229 offset:55296
	ds_read_b128 v[238:241], v229 offset:56320
	global_load_lds_dwordx4 v[196:197], off
	s_add_i32 m0, s26, 0x2000
	s_add_u32 s20, s20, 0x80080
	v_lshl_add_u64 v[196:197], v[214:215], 0, s[64:65]
	s_addc_u32 s21, s21, 0
	s_add_i32 s26, s56, s24
	global_load_lds_dwordx4 v[196:197], off
	v_lshl_add_u64 v[196:197], s[20:21], 0, v[166:167]
	s_mov_b32 m0, s26
	s_nop 0
	global_load_lds_dwordx4 v[196:197], off
	v_lshl_add_u64 v[196:197], s[20:21], 0, v[162:163]
	s_add_i32 m0, s26, 0x2000
	s_nop 0
	global_load_lds_dwordx4 v[196:197], off
	v_lshl_add_u64 v[196:197], v[242:243], 0, s[64:65]
	s_mov_b32 m0, s39
	s_nop 0
	global_load_lds_dwordx4 v[196:197], off
	v_lshl_add_u64 v[196:197], v[244:245], 0, s[64:65]
	s_mov_b32 m0, s40
	s_nop 0
	global_load_lds_dwordx4 v[196:197], off
	s_waitcnt vmcnt(8)
	s_waitcnt lgkmcnt(0)
	s_setprio 1
	s_cmp_eq_u32 s32, 0
	s_cbranch_scc1 .Lrs_22
	s_barrier
	s_setprio 2

; template <class Epi, class Sched, bool ALIGN_EPI = false, bool SP2 = false, class Hook = NoHook, bool REVK = false>
; __device__ __forceinline__ void gemm_phase(PG8_LAS unsigned char* lds, const Gemm g, const Sched& S, const Epi& E, const Hook H = Hook()) {
;     ...
;         for (int t = 0; t < nt; t += 2) {
;             if constexpr (Hook::ENABLED) H(acc, t, nt, ui, wr, fr);
.Lrs_23:
	s_setprio 0
	s_add_i32 s20, s53, 2
	s_add_u32 s22, s22, 0x100
	s_addc_u32 s23, s23, 0
	s_add_u32 s47, s47, 0x100
	s_addc_u32 s51, s51, 0
	s_cmp_gt_u32 s53, 29
	s_cbranch_scc1 .LBB0_482
	s_mov_b32 s53, s20
	s_cmp_lt_i32 s53, 16
	s_cbranch_scc0 .LBB0_473

; __device__ __forceinline__ unsigned cvt_pk_bf16(float lo, float hi) { f32x2_t v = {lo, hi}; bf16x2_t b = __builtin_convertvector(v, bf16x2_t); return __builtin_bit_cast(unsigned, b); }
;     __device__ __forceinline__ void operator()(const f32x4 (&acc)[2][2][4][2], const Unit& u, int wr, int wc, int fr, int fq, int ui) const {
;         const int row0 = u.pm * BM + wr * 64 + fr; const int col0 = u.pn * BM + wc * 32 + 8 * fq;
; #pragma unroll
;         for (int ai = 0; ai < 2; ++ai) {
;             u32x4 bs[4][2];
; #pragma unroll
;             for (int m = 0; m < 4; ++m) { const bf16_t* rowp = xb + (size_t)(row0 + ai * HALF + m * 16) * ldc + col0;
; #pragma unroll
;                 for (int bj = 0; bj < 2; ++bj) bs[m][bj] = *(const u32x4*)(rowp + bj * HALF); }
; #pragma unroll
;             for (int m = 0; m < 4; ++m) { const int row = row0 + ai * HALF + m * 16; bf16_t* rowp = xb + (size_t)row * ldc + col0;
;                 float q = 0.f;
; #pragma unroll
;                 for (int bj = 0; bj < 2; ++bj) { u32x4 w;
; #pragma unroll
;                     for (int p = 0; p < 4; ++p) { const f32x4 a = acc[ai][bj][m][p >> 1]; const unsigned b = bs[m][bj][p];
;                         const float lo = __uint_as_float(b << 16) + a[2 * (p & 1)], hi = __uint_as_float(b & 0xffff0000u) + a[2 * (p & 1) + 1];
;                         const unsigned pk = cvt_pk_bf16(lo, hi); w[p] = pk;
;                         const float rl = __uint_as_float(pk << 16), rh = __uint_as_float(pk & 0xffff0000u); q += rl * rl + rh * rh; }
;                     *(u32x4*)(rowp + bj * HALF) = w; }
;                 q += __shfl_xor(q, 16); q += __shfl_xor(q, 32);
;                 if (fq == 0) atomicAdd(ssq + row, (unsigned long long)(q * 16777216.f)); }
.LBB0_484:
	s_nop 7
	s_nop 7
	v_and_b32_e32 v131, 64, v221
	v_xor_b32_e32 v130, 16, v221
	v_add_u32_e32 v131, 64, v131
	v_cmp_lt_i32_e32 vcc, v130, v131
	v_lshl_or_b32 v186, s4, 8, v228
	v_lshl_add_u32 v194, s5, 8, v191
	v_cndmask_b32_e32 v130, v221, v130, vcc
	v_ashrrev_i32_e32 v187, 31, v186
	v_lshlrev_b32_e32 v193, 2, v130
	v_xor_b32_e32 v130, 32, v221
	v_cmp_lt_i32_e32 vcc, v130, v131
	v_lshlrev_b64 v[214:215], 1, v[186:187]
	v_ashrrev_i32_e32 v195, 31, v194
	v_cndmask_b32_e32 v130, v221, v130, vcc
	v_lshl_add_u64 v[196:197], s[14:15], 0, v[214:215]
	v_lshlrev_b64 v[200:201], 12, v[194:195]
	v_lshlrev_b32_e32 v189, 2, v130
	v_lshl_add_u64 v[130:131], v[196:197], 0, v[200:201]
	global_load_dwordx4 v[158:161], v[130:131], off
	global_load_dwordx4 v[154:157], v[130:131], off offset:256
	v_or_b32_e32 v210, 16, v194
	v_ashrrev_i32_e32 v211, 31, v210
	v_lshlrev_b64 v[130:131], 12, v[210:211]
	v_or_b32_e32 v206, 32, v194
	v_lshl_add_u64 v[130:131], v[196:197], 0, v[130:131]
	v_ashrrev_i32_e32 v207, 31, v206
	global_load_dwordx4 v[150:153], v[130:131], off
	global_load_dwordx4 v[146:149], v[130:131], off offset:256
	v_lshlrev_b64 v[130:131], 12, v[206:207]
	v_or_b32_e32 v204, 48, v194
	v_lshl_add_u64 v[130:131], v[196:197], 0, v[130:131]
	v_ashrrev_i32_e32 v205, 31, v204
	global_load_dwordx4 v[142:145], v[130:131], off
	global_load_dwordx4 v[138:141], v[130:131], off offset:256
	v_lshlrev_b64 v[130:131], 12, v[204:205]
	v_lshl_add_u64 v[130:131], v[196:197], 0, v[130:131]
	global_load_dwordx4 v[134:137], v[130:131], off
	s_nop 0
	global_load_dwordx4 v[130:133], v[130:131], off offset:256
	v_lshl_add_u64 v[230:231], s[14:15], 0, v[200:201]
	v_lshl_add_u64 v[214:215], v[230:231], 0, v[214:215]
	s_waitcnt vmcnt(0)
	v_lshlrev_b32_e32 v230, 16, v158
	v_and_b32_e32 v231, 0xffff0000, v158
	v_pk_fma_f32 v[124:125], v[124:125], v[212:213], v[230:231] op_sel_hi:[1,0,1]
	s_nop 0
	v_cvt_pk_bf16_f32 v124, v124, v125
	v_and_b32_e32 v158, 0xffff0000, v124
	v_mul_f32_e32 v203, v158, v158
	v_lshlrev_b32_e32 v158, 16, v159
	v_and_b32_e32 v159, 0xffff0000, v159
	v_lshlrev_b32_e32 v125, 16, v124
	v_pk_fma_f32 v[126:127], v[126:127], v[212:213], v[158:159] op_sel_hi:[1,0,1]
	v_fmac_f32_e32 v203, v125, v125
	v_cvt_pk_bf16_f32 v125, v126, v127
	v_and_b32_e32 v127, 0xffff0000, v125
	v_lshlrev_b32_e32 v126, 16, v125
	v_mul_f32_e32 v127, v127, v127
	v_fmac_f32_e32 v127, v126, v126
	v_add_f32_e32 v158, v203, v127
	v_lshlrev_b32_e32 v126, 16, v160
	v_and_b32_e32 v127, 0xffff0000, v160
	v_pk_fma_f32 v[120:121], v[120:121], v[212:213], v[126:127] op_sel_hi:[1,0,1]
	s_nop 0
	v_cvt_pk_bf16_f32 v126, v120, v121
	v_and_b32_e32 v121, 0xffff0000, v126
	v_lshlrev_b32_e32 v120, 16, v126
	v_mul_f32_e32 v121, v121, v121
	v_fmac_f32_e32 v121, v120, v120
	v_add_f32_e32 v158, v121, v158
	v_lshlrev_b32_e32 v120, 16, v161
	v_and_b32_e32 v121, 0xffff0000, v161
	v_pk_fma_f32 v[120:121], v[122:123], v[212:213], v[120:121] op_sel_hi:[1,0,1]
	s_nop 0
	v_cvt_pk_bf16_f32 v127, v120, v121
	v_and_b32_e32 v121, 0xffff0000, v127
	v_lshlrev_b32_e32 v120, 16, v127
	v_mul_f32_e32 v121, v121, v121
	v_fmac_f32_e32 v121, v120, v120
	v_add_f32_e32 v122, v121, v158
	v_lshlrev_b32_e32 v120, 16, v154
	v_and_b32_e32 v121, 0xffff0000, v154
	v_pk_fma_f32 v[116:117], v[116:117], v[212:213], v[120:121] op_sel_hi:[1,0,1]
	v_and_b32_e32 v121, 0xffff0000, v155
	v_cvt_pk_bf16_f32 v116, v116, v117
	v_and_b32_e32 v120, 0xffff0000, v116
	v_lshlrev_b32_e32 v117, 16, v116
	v_mul_f32_e32 v120, v120, v120
	v_fmac_f32_e32 v120, v117, v117
	v_add_f32_e32 v122, v120, v122
	v_lshlrev_b32_e32 v120, 16, v155
	v_pk_fma_f32 v[118:119], v[118:119], v[212:213], v[120:121] op_sel_hi:[1,0,1]
	global_store_dwordx4 v[214:215], v[124:127], off
	v_cvt_pk_bf16_f32 v117, v118, v119
	v_and_b32_e32 v119, 0xffff0000, v117
	v_lshlrev_b32_e32 v118, 16, v117
	v_mul_f32_e32 v119, v119, v119
	v_fmac_f32_e32 v119, v118, v118
	v_add_f32_e32 v120, v119, v122
	v_lshlrev_b32_e32 v118, 16, v156
	v_and_b32_e32 v119, 0xffff0000, v156
	v_pk_fma_f32 v[112:113], v[112:113], v[212:213], v[118:119] op_sel_hi:[1,0,1]
	s_nop 0
	v_cvt_pk_bf16_f32 v118, v112, v113
	v_and_b32_e32 v113, 0xffff0000, v118
	v_lshlrev_b32_e32 v112, 16, v118
	v_mul_f32_e32 v113, v113, v113
	v_fmac_f32_e32 v113, v112, v112
	v_add_f32_e32 v120, v113, v120
	v_lshlrev_b32_e32 v112, 16, v157
	v_and_b32_e32 v113, 0xffff0000, v157
	v_pk_fma_f32 v[112:113], v[114:115], v[212:213], v[112:113] op_sel_hi:[1,0,1]
	s_nop 0
	v_cvt_pk_bf16_f32 v119, v112, v113
	v_and_b32_e32 v113, 0xffff0000, v119
	v_lshlrev_b32_e32 v112, 16, v119
	v_mul_f32_e32 v113, v113, v113
	v_fmac_f32_e32 v113, v112, v112
	v_add_f32_e32 v112, v113, v120
	ds_bpermute_b32 v113, v193, v112
	global_store_dwordx4 v[214:215], v[116:119], off offset:256
	s_waitcnt lgkmcnt(0)
	v_add_f32_e32 v114, v112, v113
	ds_bpermute_b32 v115, v189, v114
	v_lshl_add_u64 v[112:113], v[194:195], 3, s[82:83]
	s_and_saveexec_b64 s[20:21], s[6:7]
	s_cbranch_execz .LBB0_486
	s_waitcnt lgkmcnt(0)
	v_add_f32_e32 v114, v114, v115
	v_mul_f32_e32 v114, 0x4b800000, v114
	v_trunc_f32_e32 v114, v114
	v_mul_f32_e32 v115, 0x2f800000, v114
	v_floor_f32_e32 v115, v115
	v_fmac_f32_e32 v114, 0xcf800000, v115
	v_cvt_u32_f32_e32 v114, v114
	v_cvt_u32_f32_e32 v115, v115
	global_atomic_add_x2 v[112:113], v[114:115], off

; #define PG8_BAR __builtin_amdgcn_s_barrier()
; template <class Epi, class Sched, bool ALIGN_EPI = false, bool SP2 = false, class Hook = NoHook, bool REVK = false>
; __device__ __forceinline__ void gemm_phase(PG8_LAS unsigned char* lds, const Gemm g, const Sched& S, const Epi& E, const Hook H = Hook()) {
;     ...
;         if (!has_next) break;
; #pragma unroll
;         for (int a = 0; a < 2; ++a)
; #pragma unroll
;             for (int b = 0; b < 2; ++b)
; #pragma unroll
;                 for (int m = 0; m < 4; ++m)
; #pragma unroll
;                     for (int n = 0; n < 2; ++n) acc[a][b][m][n] = (f32x4){0.f, 0.f, 0.f, 0.f};
;         cur = nxt; cA = nA; cB = nB; ++ui;
;         if constexpr (ALIGN_EPI) { if (wr == 1) PG8_BAR; }
.LBB0_500:
	s_or_b64 exec, exec, s[20:21]
	s_andn2_b64 vcc, exec, s[8:9]
	s_mov_b64 s[8:9], -1
	s_cbranch_vccnz .LBB0_465
	s_andn2_b64 vcc, exec, s[12:13]
	s_cbranch_vccnz .LBB0_464
	s_branch .LBB0_464

; template <class Epi, class Sched, bool ALIGN_EPI = false, bool SP2 = false, class Hook = NoHook, bool REVK = false>
; __device__ __forceinline__ void gemm_phase(PG8_LAS unsigned char* lds, const Gemm g, const Sched& S, const Epi& E, const Hook H = Hook()) {
;     int tid_ = threadIdx.x; asm volatile("" : "+v"(tid_));
;     const int tid = tid_, wid = __builtin_amdgcn_readfirstlane(tid >> 6), lane = tid & 63, wr = wid >> 2, wc = wid & 3, fr = lane & 15, fq = lane >> 4;
;     const int K = g.K, nt = K / BK;
;     unsigned voffA[2], voffB[2];
; #pragma unroll
;     for (int i = 0; i < 2; ++i) { int R, C; stage_rc(tid * 16 + i * 8192, R, C); const int Rb = Epi::PERM ? ((R & ~31) + perm32(R & 31)) : R;
;         voffA[i] = (unsigned)(R * K + C) * 2u; voffB[i] = (unsigned)(Rb * K + C) * 2u; }
;     const long kstep = REVK ? -(long)(BK * 2) : (long)(BK * 2);
;     const size_t krev = REVK ? (size_t)(K / BK - 1) * (size_t)(BK * 2) : 0;
;     const size_t hstep = (size_t)HALF * K * 2;
;     const size_t tstep = 2 * hstep;
;     const unsigned ldsw = (unsigned)wid * 1024u;
;     const int aoff = lds_byte(wr * 64 + fr, fq * 8), boff = lds_byte(wc * 32 + fr, fq * 8);
;     ...
;     Unit cur, nxt; int ui = 0;
;     if (!S.next(0, cur)) return;
;     f32x4 acc[2][2][4][2];
; #pragma unroll
;     for (int a = 0; a < 2; ++a)
; #pragma unroll
;         for (int b = 0; b < 2; ++b)
; #pragma unroll
;             for (int m = 0; m < 4; ++m)
; #pragma unroll
;                 for (int n = 0; n < 2; ++n) acc[a][b][m][n] = (f32x4){0.f, 0.f, 0.f, 0.f};
;     bf16x8 At[4][2], B0[2][2], B1[2][2];
;     const char* cA = (const char*)g.A + (size_t)cur.pm * tstep + krev; const char* cB = (const char*)g.Bt + (size_t)cur.pn * tstep + krev;
;     S.a_ready(cur);
;     if constexpr (SP2) {
;         PG8_STAGE(PG8_SB(0, 0), cB, voffB); PG8_STAGE(PG8_SB(0, 1), cB + hstep, voffB); PG8_STAGE(PG8_SA(0, 0), cA, voffA); PG8_STAGE(PG8_SA(0, 1), cA + hstep, voffA);
;         if (wr == 1) PG8_BAR;
;         PG8_WAIT_V(2); PG8_BAR;
;         PG8_STAGE(PG8_SB(1, 0), cB + kstep, voffB); PG8_STAGE(PG8_SA(1, 0), cA + kstep, voffA); PG8_STAGE(PG8_SB(1, 1), cB + hstep + kstep, voffB);
;         PG8_WAIT_V(6); PG8_BAR;
;     } else {
;         PG8_STAGE(PG8_SB(0, 0), cB, voffB); PG8_STAGE(PG8_SA(0, 0), cA, voffA); PG8_STAGE(PG8_SB(0, 1), cB + hstep, voffB); PG8_STAGE(PG8_SA(0, 1), cA + hstep, voffA);
.LBB0_569:
	v_readlane_b32 s4, v250, 9
	v_mov_b32_e32 v14, v199
	v_readlane_b32 s5, v250, 10
	s_lshl_b64 s[8:9], s[74:75], 25
	s_waitcnt lgkmcnt(0)
	s_barrier
	s_andn2_b64 vcc, exec, s[4:5]
	v_readfirstlane_b32 s4, v14
	s_cbranch_vccnz .LBB0_589
	v_lshlrev_b32_e32 v0, 4, v14
	v_add_u32_e32 v1, 0x2000, v0
	v_ashrrev_i32_e32 v2, 31, v1
	v_lshrrev_b32_e32 v2, 22, v2
	v_add_u32_e32 v2, v1, v2
	v_ashrrev_i32_e32 v8, 10, v2
	v_mul_i32_i24_e32 v2, 0x400, v8
	v_sub_u32_e32 v1, v1, v2
	v_lshrrev_b32_e32 v2, 4, v1
	s_ashr_i32 s6, s4, 6
	v_bitop3_b32 v1, v2, v1, 32 bitop3:0x6c
	s_ashr_i32 s5, s4, 8
	s_lshl_b32 s10, s6, 10
	v_ashrrev_i32_e32 v2, 31, v1
	s_add_u32 s11, s14, 0x15c00000
	v_lshrrev_b32_e32 v2, 26, v2
	s_addc_u32 s24, s15, 0
	v_add_u32_e32 v2, v1, v2
	v_lshlrev_b32_e32 v3, 3, v8
	s_add_u32 s7, s14, s8
	v_ashrrev_i32_e32 v9, 6, v2
	v_and_b32_e32 v3, -16, v3
	s_addc_u32 s12, s15, s9
	v_add_u32_e32 v3, v9, v3
	s_add_u32 s28, s7, 0x5c00000
	v_and_b32_e32 v4, 3, v9
	s_mov_b32 s7, 0xfffe0
	v_lshrrev_b32_e32 v5, 2, v3
	v_lshlrev_b32_e32 v6, 1, v3
	v_and_b32_e32 v2, 0xc0, v2
	v_and_or_b32 v4, v3, s7, v4
	v_and_b32_e32 v5, 4, v5
	v_and_b32_e32 v6, 24, v6
	v_sub_u32_e32 v1, v1, v2
	v_or3_b32 v4, v4, v5, v6
	v_lshlrev_b32_e32 v5, 5, v8
	v_ashrrev_i16_sdwa v1, v219, sext(v1) dst_sel:DWORD dst_unused:UNUSED_PAD src0_sel:DWORD src1_sel:BYTE_0
	v_and_b32_e32 v5, 32, v5
	v_bfe_i32 v10, v1, 0, 16
	v_add_lshl_u32 v1, v5, v10, 1
	s_waitcnt vmcnt(9)
	v_lshl_add_u32 v130, v4, 12, v1
	v_lshl_add_u32 v132, v3, 12, v1
	v_bfe_i32 v1, v14, 27, 1
	v_lshrrev_b32_e32 v1, 22, v1
	v_add_u32_e32 v1, v0, v1
	v_and_b32_e32 v1, 0xfffffc00, v1
	v_sub_u32_e32 v0, v0, v1
	v_lshrrev_b32_e32 v1, 4, v0
	v_ashrrev_i32_e32 v2, 31, v14
	v_bitop3_b32 v0, v1, v0, 32 bitop3:0x6c
	v_lshrrev_b32_e32 v2, 26, v2
	v_ashrrev_i32_e32 v1, 31, v0
	v_add_u32_e32 v2, v14, v2
	v_lshrrev_b32_e32 v1, 26, v1
	v_ashrrev_i32_e32 v12, 6, v2
	v_add_u32_e32 v1, v0, v1
	v_lshlrev_b32_e32 v2, 3, v12
	v_ashrrev_i32_e32 v11, 6, v1
	v_and_b32_e32 v2, -16, v2
	v_add_u32_e32 v2, v11, v2
	v_and_b32_e32 v3, 3, v11
	v_lshrrev_b32_e32 v4, 2, v2
	v_lshlrev_b32_e32 v5, 1, v2
	v_and_b32_e32 v1, 0xc0, v1
	v_and_or_b32 v3, v2, s7, v3
	v_and_b32_e32 v4, 4, v4
	v_and_b32_e32 v5, 24, v5
	v_sub_u32_e32 v0, v0, v1
	s_addc_u32 s29, s12, 0
	v_or3_b32 v3, v3, v4, v5
	v_lshlrev_b32_e32 v4, 5, v12
	v_ashrrev_i16_sdwa v0, v219, sext(v0) dst_sel:DWORD dst_unused:UNUSED_PAD src0_sel:DWORD src1_sel:BYTE_0
	v_readlane_b32 s12, v250, 26
	v_and_b32_e32 v4, 32, v4
	v_bfe_i32 v13, v0, 0, 16
	v_readlane_b32 s13, v250, 27
	s_add_u32 s20, s28, s12
	v_add_lshl_u32 v0, v4, v13, 1
	s_addc_u32 s21, s29, s13
	s_add_i32 s30, s10, 0
	v_lshl_add_u32 v128, v3, 12, v0
	s_add_i32 m0, s30, 0x10000
	s_waitcnt vmcnt(8)
	v_lshl_add_u32 v134, v2, 12, v0
	global_load_lds_dwordx4 v128, s[20:21]
	s_add_i32 m0, s30, 0x12000
	s_add_u32 s12, s20, 0x80000
	global_load_lds_dwordx4 v130, s[20:21]
	s_addc_u32 s13, s21, 0
	s_add_i32 m0, s30, 0x14000
	v_mov_b32_e32 v131, v129
	global_load_lds_dwordx4 v128, s[12:13]
	s_add_i32 m0, s30, 0x16000
	v_mov_b32_e32 v135, v129
	global_load_lds_dwordx4 v130, s[12:13]
	v_readlane_b32 s12, v250, 24
	v_readlane_b32 s13, v250, 25
	s_add_u32 s22, s11, s12
	s_addc_u32 s23, s24, s13
	s_add_i32 s31, s30, 0x2000
	s_mov_b32 m0, s30
	s_add_u32 s12, s22, 0x80000
	global_load_lds_dwordx4 v134, s[22:23]
	s_mov_b32 m0, s31
	s_addc_u32 s13, s23, 0
	s_add_i32 s34, s30, 0x4000
	global_load_lds_dwordx4 v132, s[22:23]
	s_mov_b32 m0, s34
	s_add_i32 s35, s30, 0x6000
	global_load_lds_dwordx4 v134, s[12:13]
	s_mov_b32 m0, s35
	v_mov_b32_e32 v133, v129
	global_load_lds_dwordx4 v132, s[12:13]
	s_cmp_eq_u32 s5, 1
	v_lshl_add_u64 v[6:7], s[20:21], 0, v[128:129]
	v_lshl_add_u64 v[4:5], s[20:21], 0, v[130:131]
	v_lshl_add_u64 v[0:1], s[22:23], 0, v[134:135]
	s_cselect_b64 s[12:13], -1, 0
	s_mov_b32 s32, s5
	s_cmp_lg_u32 s5, 1
	v_lshl_add_u64 v[2:3], s[22:23], 0, v[132:133]
	s_cbranch_scc1 .LBB0_572

; #define PG8_STAGE(bufoff, gbase, voff) do { _Pragma("unroll") for (int _i = 0; _i < 2; ++_i) \
;         __builtin_amdgcn_global_load_lds((const unsigned*)((const char*)(gbase) + (voff)[_i]), (PG8_LAS unsigned*)(lds + (bufoff) + ldsw + _i * 8192), 16, 0, 0); } while (0)
; #define PG8_LDA(dst, b, h) do { _Pragma("unroll") for (int m = 0; m < 4; ++m) _Pragma("unroll") for (int k = 0; k < 2; ++k) dst[m][k] = *(const PG8_LAS bf16x8*)(lds + PG8_SA(b, h) + aoff + m * 2048 + k * 1024); } while (0)
; #define PG8_MMA(ai, bj, At, Bt) do { __builtin_amdgcn_s_setprio(1); _Pragma("unroll") for (int m = 0; m < 4; ++m) _Pragma("unroll") for (int n = 0; n < 2; ++n) _Pragma("unroll") for (int k = 0; k < 2; ++k) \
;         acc[ai][bj][m][n] = __builtin_amdgcn_mfma_f32_16x16x32_bf16(Bt[n][k], At[m][k], acc[ai][bj][m][n], 0, 0, 0); __builtin_amdgcn_s_setprio(0); } while (0)
; #define PG8_WAIT_V(n) asm volatile("s_waitcnt vmcnt(" #n ")" ::: "memory")
; #define PG8_WAIT_L(n) asm volatile("s_waitcnt lgkmcnt(" #n ")" ::: "memory")
; #define PG8_BAR __builtin_amdgcn_s_barrier()
; #define PG8_SCHED __builtin_amdgcn_sched_barrier(0)
; template <class Epi, class Sched, bool ALIGN_EPI = false, bool SP2 = false, class Hook = NoHook, bool REVK = false>
; __device__ __forceinline__ void gemm_phase(PG8_LAS unsigned char* lds, const Gemm g, const Sched& S, const Epi& E, const Hook H = Hook()) {
;     ...
;             PG8_WAIT_V(8); PG8_WAIT_L(0); PG8_BAR; PG8_MMA(0, 0, At, B0); PG8_MMA(0, 1, At, B1); PG8_BAR; PG8_SCHED;
;             PG8_LDA(At, 0, 1); PG8_STAGE(PG8_SB(0, 0), b2, voffB); PG8_STAGE(PG8_SB(0, 1), b2 + hstep, voffB); PG8_STAGE(PG8_SA(0, 0), a2, voffA);
;             PG8_WAIT_V(8); PG8_WAIT_L(0); PG8_BAR; PG8_MMA(1, 0, At, B0); PG8_MMA(1, 1, At, B1); PG8_BAR; PG8_SCHED;
.Lvw_up_0:
	s_waitcnt vmcnt(24)
	s_waitcnt lgkmcnt(0)
	s_setprio 1
	s_cmp_eq_u32 s32, 0
	s_cbranch_scc1 .Lrs_24
	s_barrier
	s_setprio 2
.Lrs_24:
	v_mfma_f32_16x16x32_bf16 v[124:127], v[140:143], v[194:197], 0
	v_mfma_f32_16x16x32_bf16 v[124:127], v[152:155], v[200:203], v[124:127]
	v_mfma_f32_16x16x32_bf16 v[120:123], v[160:163], v[200:203], 0
	v_mfma_f32_16x16x32_bf16 v[120:123], v[156:159], v[194:197], v[120:123]
	v_mfma_f32_16x16x32_bf16 v[116:119], v[164:167], v[194:197], 0
	v_mfma_f32_16x16x32_bf16 v[116:119], v[182:185], v[200:203], v[116:119]
	v_mfma_f32_16x16x32_bf16 v[112:115], v[190:193], v[200:203], 0
	v_mfma_f32_16x16x32_bf16 v[112:115], v[186:189], v[194:197], v[112:115]
	v_mfma_f32_16x16x32_bf16 v[96:99], v[186:189], v[204:207], 0
	v_mfma_f32_16x16x32_bf16 v[96:99], v[190:193], v[210:213], v[96:99]
	v_mfma_f32_16x16x32_bf16 v[100:103], v[182:185], v[210:213], 0
	v_mfma_f32_16x16x32_bf16 v[100:103], v[164:167], v[204:207], v[100:103]
	v_mfma_f32_16x16x32_bf16 v[104:107], v[156:159], v[204:207], 0
	v_mfma_f32_16x16x32_bf16 v[104:107], v[160:163], v[210:213], v[104:107]
	v_mfma_f32_16x16x32_bf16 v[108:111], v[152:155], v[210:213], 0
	v_mfma_f32_16x16x32_bf16 v[108:111], v[140:143], v[204:207], v[108:111]
	v_mfma_f32_16x16x32_bf16 v[92:95], v[140:143], v[226:229], 0
	v_mfma_f32_16x16x32_bf16 v[92:95], v[152:155], v[230:233], v[92:95]
	v_mfma_f32_16x16x32_bf16 v[88:91], v[160:163], v[230:233], 0
	v_mfma_f32_16x16x32_bf16 v[88:91], v[156:159], v[226:229], v[88:91]
	v_mfma_f32_16x16x32_bf16 v[84:87], v[164:167], v[226:229], 0
	v_mfma_f32_16x16x32_bf16 v[84:87], v[182:185], v[230:233], v[84:87]
	v_mfma_f32_16x16x32_bf16 v[80:83], v[190:193], v[230:233], 0
	v_mfma_f32_16x16x32_bf16 v[80:83], v[186:189], v[226:229], v[80:83]
	v_mfma_f32_16x16x32_bf16 v[64:67], v[186:189], v[234:237], 0
	v_mfma_f32_16x16x32_bf16 v[64:67], v[190:193], v[238:241], v[64:67]
	v_mfma_f32_16x16x32_bf16 v[68:71], v[182:185], v[238:241], 0
	v_mfma_f32_16x16x32_bf16 v[68:71], v[164:167], v[234:237], v[68:71]
	v_mfma_f32_16x16x32_bf16 v[72:75], v[156:159], v[234:237], 0
	v_mfma_f32_16x16x32_bf16 v[72:75], v[160:163], v[238:241], v[72:75]
	v_mfma_f32_16x16x32_bf16 v[76:79], v[152:155], v[238:241], 0
	v_mfma_f32_16x16x32_bf16 v[76:79], v[140:143], v[234:237], v[76:79]
	s_cmp_lg_u32 s32, 0
	s_cbranch_scc1 .Lrs_25
	s_barrier
.Lrs_25:
	s_setprio 0
	s_add_i32 s46, s46, s10
	v_lshl_add_u64 v[144:145], s[20:21], 0, v[128:129]
	s_mov_b32 m0, s46
	ds_read_b128 v[194:197], v150 offset:16384
	ds_read_b128 v[200:203], v150 offset:17408
	ds_read_b128 v[204:207], v150 offset:18432
	ds_read_b128 v[210:213], v150 offset:19456
	ds_read_b128 v[226:229], v150 offset:20480
	ds_read_b128 v[230:233], v150 offset:21504
	ds_read_b128 v[234:237], v150 offset:22528
	ds_read_b128 v[238:241], v150 offset:23552
	global_load_lds_dwordx4 v[144:145], off
	s_add_i32 m0, s46, 0x2000
	s_add_u32 s56, s20, 0x80000
	v_lshl_add_u64 v[168:169], s[20:21], 0, v[130:131]
	s_addc_u32 s57, s21, 0
	s_add_i32 s46, s58, s10
	global_load_lds_dwordx4 v[168:169], off
	v_lshl_add_u64 v[214:215], s[56:57], 0, v[128:129]
	s_mov_b32 m0, s46
	v_lshl_add_u64 v[242:243], s[26:27], 0, v[132:133]
	global_load_lds_dwordx4 v[214:215], off
	v_lshl_add_u64 v[214:215], s[56:57], 0, v[130:131]
	s_add_i32 m0, s46, 0x2000
	s_nop 0
	global_load_lds_dwordx4 v[214:215], off
	v_lshl_add_u64 v[214:215], s[26:27], 0, v[134:135]
	s_mov_b32 m0, s30
	s_nop 0
	global_load_lds_dwordx4 v[214:215], off
	s_mov_b32 m0, s31
	s_nop 0
	global_load_lds_dwordx4 v[242:243], off
	s_cmp_lg_u32 s4, 0
	s_cbranch_scc1 .Lvw_up_1
	s_waitcnt vmcnt(8)

; #define PG8_STAGE(bufoff, gbase, voff) do { _Pragma("unroll") for (int _i = 0; _i < 2; ++_i) \
;         __builtin_amdgcn_global_load_lds((const unsigned*)((const char*)(gbase) + (voff)[_i]), (PG8_LAS unsigned*)(lds + (bufoff) + ldsw + _i * 8192), 16, 0, 0); } while (0)
; #define PG8_LDA(dst, b, h) do { _Pragma("unroll") for (int m = 0; m < 4; ++m) _Pragma("unroll") for (int k = 0; k < 2; ++k) dst[m][k] = *(const PG8_LAS bf16x8*)(lds + PG8_SA(b, h) + aoff + m * 2048 + k * 1024); } while (0)
; #define PG8_LDB(dst, b, h) do { _Pragma("unroll") for (int n = 0; n < 2; ++n) _Pragma("unroll") for (int k = 0; k < 2; ++k) dst[n][k] = *(const PG8_LAS bf16x8*)(lds + PG8_SB(b, h) + boff + n * 2048 + k * 1024); } while (0)
; #define PG8_MMA(ai, bj, At, Bt) do { __builtin_amdgcn_s_setprio(1); _Pragma("unroll") for (int m = 0; m < 4; ++m) _Pragma("unroll") for (int n = 0; n < 2; ++n) _Pragma("unroll") for (int k = 0; k < 2; ++k) \
;         acc[ai][bj][m][n] = __builtin_amdgcn_mfma_f32_16x16x32_bf16(Bt[n][k], At[m][k], acc[ai][bj][m][n], 0, 0, 0); __builtin_amdgcn_s_setprio(0); } while (0)
; #define PG8_WAIT_V(n) asm volatile("s_waitcnt vmcnt(" #n ")" ::: "memory")
; #define PG8_WAIT_L(n) asm volatile("s_waitcnt lgkmcnt(" #n ")" ::: "memory")
; #define PG8_BAR __builtin_amdgcn_s_barrier()
; #define PG8_SCHED __builtin_amdgcn_sched_barrier(0)
; template <class Epi, class Sched, bool ALIGN_EPI = false, bool SP2 = false, class Hook = NoHook, bool REVK = false>
; __device__ __forceinline__ void gemm_phase(PG8_LAS unsigned char* lds, const Gemm g, const Sched& S, const Epi& E, const Hook H = Hook()) {
;     ...
;             PG8_WAIT_V(8); PG8_WAIT_L(0); PG8_BAR; PG8_MMA(1, 0, At, B0); PG8_MMA(1, 1, At, B1); PG8_BAR; PG8_SCHED;
;             PG8_LDB(B0, 1, 0); PG8_LDB(B1, 1, 1); PG8_SCHED; PG8_LDA(At, 1, 0); PG8_STAGE(PG8_SA(0, 1), a2 + hstep, voffA);
;             PG8_WAIT_V(8); PG8_WAIT_L(0); PG8_BAR; PG8_MMA(0, 0, At, B0); PG8_MMA(0, 1, At, B1); PG8_BAR; PG8_SCHED;
.Lrs_26:
	v_mfma_f32_16x16x32_bf16 v[60:63], v[140:143], v[194:197], 0
	v_mfma_f32_16x16x32_bf16 v[60:63], v[152:155], v[200:203], v[60:63]
	v_mfma_f32_16x16x32_bf16 v[56:59], v[160:163], v[200:203], 0
	v_mfma_f32_16x16x32_bf16 v[56:59], v[156:159], v[194:197], v[56:59]
	v_mfma_f32_16x16x32_bf16 v[52:55], v[164:167], v[194:197], 0
	v_mfma_f32_16x16x32_bf16 v[52:55], v[182:185], v[200:203], v[52:55]
	v_mfma_f32_16x16x32_bf16 v[48:51], v[190:193], v[200:203], 0
	v_mfma_f32_16x16x32_bf16 v[48:51], v[186:189], v[194:197], v[48:51]
	v_mfma_f32_16x16x32_bf16 v[32:35], v[186:189], v[204:207], 0
	v_mfma_f32_16x16x32_bf16 v[32:35], v[190:193], v[210:213], v[32:35]
	v_mfma_f32_16x16x32_bf16 v[36:39], v[182:185], v[210:213], 0
	v_mfma_f32_16x16x32_bf16 v[36:39], v[164:167], v[204:207], v[36:39]
	v_mfma_f32_16x16x32_bf16 v[40:43], v[156:159], v[204:207], 0
	v_mfma_f32_16x16x32_bf16 v[40:43], v[160:163], v[210:213], v[40:43]
	v_mfma_f32_16x16x32_bf16 v[44:47], v[152:155], v[210:213], 0
	v_mfma_f32_16x16x32_bf16 v[44:47], v[140:143], v[204:207], v[44:47]
	v_mfma_f32_16x16x32_bf16 v[28:31], v[140:143], v[226:229], 0
	v_mfma_f32_16x16x32_bf16 v[28:31], v[152:155], v[230:233], v[28:31]
	v_mfma_f32_16x16x32_bf16 v[24:27], v[160:163], v[230:233], 0
	v_mfma_f32_16x16x32_bf16 v[24:27], v[156:159], v[226:229], v[24:27]
	v_mfma_f32_16x16x32_bf16 v[20:23], v[164:167], v[226:229], 0
	v_mfma_f32_16x16x32_bf16 v[20:23], v[182:185], v[230:233], v[20:23]
	v_mfma_f32_16x16x32_bf16 v[16:19], v[190:193], v[230:233], 0
	v_mfma_f32_16x16x32_bf16 v[16:19], v[186:189], v[226:229], v[16:19]
	v_mfma_f32_16x16x32_bf16 v[0:3], v[186:189], v[234:237], 0
	v_mfma_f32_16x16x32_bf16 v[0:3], v[190:193], v[238:241], v[0:3]
	v_mfma_f32_16x16x32_bf16 v[4:7], v[182:185], v[238:241], 0
	v_mfma_f32_16x16x32_bf16 v[4:7], v[164:167], v[234:237], v[4:7]
	v_mfma_f32_16x16x32_bf16 v[8:11], v[156:159], v[234:237], 0
	v_mfma_f32_16x16x32_bf16 v[8:11], v[160:163], v[238:241], v[8:11]
	v_mfma_f32_16x16x32_bf16 v[12:15], v[152:155], v[238:241], 0
	v_mfma_f32_16x16x32_bf16 v[12:15], v[140:143], v[234:237], v[12:15]
	s_cmp_lg_u32 s32, 0
	s_cbranch_scc1 .Lrs_27
	s_barrier
.Lrs_27:
	s_setprio 0
	s_add_i32 s46, 0, 0x18000
	v_add_u32_e32 v151, s46, v147
	s_add_i32 s56, 0, 0x1c000
	ds_read_b128 v[140:143], v151
	ds_read_b128 v[152:155], v151 offset:1024
	ds_read_b128 v[156:159], v151 offset:2048
	ds_read_b128 v[160:163], v151 offset:3072
	v_add_u32_e32 v151, s56, v147
	ds_read_b128 v[164:167], v151
	ds_read_b128 v[182:185], v151 offset:1024
	ds_read_b128 v[186:189], v151 offset:2048
	ds_read_b128 v[190:193], v151 offset:3072
	s_add_u32 s26, s26, 0x80000
	s_addc_u32 s27, s27, 0
	s_mov_b32 m0, s34
	v_lshl_add_u64 v[244:245], s[26:27], 0, v[134:135]
	ds_read_b128 v[194:197], v150 offset:32768
	ds_read_b128 v[200:203], v150 offset:33792
	ds_read_b128 v[204:207], v150 offset:34816
	ds_read_b128 v[210:213], v150 offset:35840
	ds_read_b128 v[226:229], v150 offset:36864
	ds_read_b128 v[230:233], v150 offset:37888
	ds_read_b128 v[234:237], v150 offset:38912
	ds_read_b128 v[238:241], v150 offset:39936
	global_load_lds_dwordx4 v[244:245], off
	v_lshl_add_u64 v[244:245], s[26:27], 0, v[132:133]
	s_mov_b32 m0, s35
	s_nop 0
	global_load_lds_dwordx4 v[244:245], off
	s_waitcnt vmcnt(8)
	s_waitcnt lgkmcnt(0)
	s_setprio 1
	s_cmp_eq_u32 s32, 0
	s_cbranch_scc1 .Lrs_28
	s_barrier
	s_setprio 2
.Lrs_28:
	v_mfma_f32_16x16x32_bf16 v[124:127], v[140:143], v[194:197], v[124:127]
	v_mfma_f32_16x16x32_bf16 v[124:127], v[152:155], v[200:203], v[124:127]
	v_mfma_f32_16x16x32_bf16 v[120:123], v[160:163], v[200:203], v[120:123]
	v_mfma_f32_16x16x32_bf16 v[120:123], v[156:159], v[194:197], v[120:123]
	v_mfma_f32_16x16x32_bf16 v[116:119], v[164:167], v[194:197], v[116:119]
	v_mfma_f32_16x16x32_bf16 v[116:119], v[182:185], v[200:203], v[116:119]
	v_mfma_f32_16x16x32_bf16 v[112:115], v[190:193], v[200:203], v[112:115]
	v_mfma_f32_16x16x32_bf16 v[112:115], v[186:189], v[194:197], v[112:115]
	v_mfma_f32_16x16x32_bf16 v[96:99], v[186:189], v[204:207], v[96:99]
	v_mfma_f32_16x16x32_bf16 v[96:99], v[190:193], v[210:213], v[96:99]
	v_mfma_f32_16x16x32_bf16 v[100:103], v[182:185], v[210:213], v[100:103]
	v_mfma_f32_16x16x32_bf16 v[100:103], v[164:167], v[204:207], v[100:103]
	v_mfma_f32_16x16x32_bf16 v[104:107], v[156:159], v[204:207], v[104:107]
	v_mfma_f32_16x16x32_bf16 v[104:107], v[160:163], v[210:213], v[104:107]
	v_mfma_f32_16x16x32_bf16 v[108:111], v[152:155], v[210:213], v[108:111]
	v_mfma_f32_16x16x32_bf16 v[108:111], v[140:143], v[204:207], v[108:111]
	v_mfma_f32_16x16x32_bf16 v[92:95], v[140:143], v[226:229], v[92:95]
	v_mfma_f32_16x16x32_bf16 v[92:95], v[152:155], v[230:233], v[92:95]
	v_mfma_f32_16x16x32_bf16 v[88:91], v[160:163], v[230:233], v[88:91]
	v_mfma_f32_16x16x32_bf16 v[88:91], v[156:159], v[226:229], v[88:91]
	v_mfma_f32_16x16x32_bf16 v[84:87], v[164:167], v[226:229], v[84:87]
	v_mfma_f32_16x16x32_bf16 v[84:87], v[182:185], v[230:233], v[84:87]
	v_mfma_f32_16x16x32_bf16 v[80:83], v[190:193], v[230:233], v[80:83]
	v_mfma_f32_16x16x32_bf16 v[80:83], v[186:189], v[226:229], v[80:83]
	v_mfma_f32_16x16x32_bf16 v[64:67], v[186:189], v[234:237], v[64:67]
	v_mfma_f32_16x16x32_bf16 v[64:67], v[190:193], v[238:241], v[64:67]
	v_mfma_f32_16x16x32_bf16 v[68:71], v[182:185], v[238:241], v[68:71]
	v_mfma_f32_16x16x32_bf16 v[68:71], v[164:167], v[234:237], v[68:71]
	v_mfma_f32_16x16x32_bf16 v[72:75], v[156:159], v[234:237], v[72:75]
	v_mfma_f32_16x16x32_bf16 v[72:75], v[160:163], v[238:241], v[72:75]
	v_mfma_f32_16x16x32_bf16 v[76:79], v[152:155], v[238:241], v[76:79]
	v_mfma_f32_16x16x32_bf16 v[76:79], v[140:143], v[234:237], v[76:79]
	s_cmp_lg_u32 s32, 0
	s_cbranch_scc1 .Lrs_29
	s_barrier
; #define PG8_STAGE(bufoff, gbase, voff) do { _Pragma("unroll") for (int _i = 0; _i < 2; ++_i) \
;         __builtin_amdgcn_global_load_lds((const unsigned*)((const char*)(gbase) + (voff)[_i]), (PG8_LAS unsigned*)(lds + (bufoff) + ldsw + _i * 8192), 16, 0, 0); } while (0)
; #define PG8_LDA(dst, b, h) do { _Pragma("unroll") for (int m = 0; m < 4; ++m) _Pragma("unroll") for (int k = 0; k < 2; ++k) dst[m][k] = *(const PG8_LAS bf16x8*)(lds + PG8_SA(b, h) + aoff + m * 2048 + k * 1024); } while (0)
; #define PG8_LDB(dst, b, h) do { _Pragma("unroll") for (int n = 0; n < 2; ++n) _Pragma("unroll") for (int k = 0; k < 2; ++k) dst[n][k] = *(const PG8_LAS bf16x8*)(lds + PG8_SB(b, h) + boff + n * 2048 + k * 1024); } while (0)
; #define PG8_MMA(ai, bj, At, Bt) do { __builtin_amdgcn_s_setprio(1); _Pragma("unroll") for (int m = 0; m < 4; ++m) _Pragma("unroll") for (int n = 0; n < 2; ++n) _Pragma("unroll") for (int k = 0; k < 2; ++k) \
;         acc[ai][bj][m][n] = __builtin_amdgcn_mfma_f32_16x16x32_bf16(Bt[n][k], At[m][k], acc[ai][bj][m][n], 0, 0, 0); __builtin_amdgcn_s_setprio(0); } while (0)
; #define PG8_WAIT_V(n) asm volatile("s_waitcnt vmcnt(" #n ")" ::: "memory")
; #define PG8_WAIT_L(n) asm volatile("s_waitcnt lgkmcnt(" #n ")" ::: "memory")
; #define PG8_BAR __builtin_amdgcn_s_barrier()
; #define PG8_SCHED __builtin_amdgcn_sched_barrier(0)
; template <class Epi, class Sched, bool ALIGN_EPI = false, bool SP2 = false, class Hook = NoHook, bool REVK = false>
; __device__ __forceinline__ void gemm_phase(PG8_LAS unsigned char* lds, const Gemm g, const Sched& S, const Epi& E, const Hook H = Hook()) {
;     ...
;             PG8_LDB(B0, 0, 0); PG8_LDB(B1, 0, 1); PG8_SCHED; PG8_LDA(At, 0, 0); PG8_STAGE(PG8_SA(1, 1), a1 + hstep, voffA);
;             PG8_WAIT_V(8); PG8_WAIT_L(0); PG8_BAR; PG8_MMA(0, 0, At, B0); PG8_MMA(0, 1, At, B1); PG8_BAR; PG8_SCHED;
;     ...
;             PG8_LDA(At, 1, 1); PG8_STAGE(PG8_SB(1, 0), b3, voffB); PG8_STAGE(PG8_SB(1, 1), b3 + hstep, voffB); PG8_STAGE(PG8_SA(1, 0), a3, voffA);
;             PG8_WAIT_V(8); PG8_WAIT_L(0); PG8_BAR; PG8_MMA(1, 0, At, B0); PG8_MMA(1, 1, At, B1); PG8_BAR; PG8_SCHED;
.Lrs_29:
	s_setprio 0
	s_add_i32 s26, s46, s10
	v_lshl_add_u64 v[144:145], v[144:145], 0, s[64:65]
	s_mov_b32 m0, s26
	ds_read_b128 v[194:197], v150 offset:49152
	ds_read_b128 v[200:203], v150 offset:50176
	ds_read_b128 v[204:207], v150 offset:51200
	ds_read_b128 v[210:213], v150 offset:52224
	ds_read_b128 v[226:229], v150 offset:53248
	ds_read_b128 v[230:233], v150 offset:54272
	ds_read_b128 v[234:237], v150 offset:55296
	ds_read_b128 v[238:241], v150 offset:56320
	global_load_lds_dwordx4 v[144:145], off
	s_add_i32 m0, s26, 0x2000
	s_add_u32 s20, s20, 0x80080
	v_lshl_add_u64 v[144:145], v[168:169], 0, s[64:65]
	s_addc_u32 s21, s21, 0
	s_add_i32 s26, s56, s10
	global_load_lds_dwordx4 v[144:145], off
	v_lshl_add_u64 v[144:145], s[20:21], 0, v[128:129]
	s_mov_b32 m0, s26
	s_nop 0
	global_load_lds_dwordx4 v[144:145], off
	v_lshl_add_u64 v[144:145], s[20:21], 0, v[130:131]
	s_add_i32 m0, s26, 0x2000
	s_nop 0
	global_load_lds_dwordx4 v[144:145], off
	v_lshl_add_u64 v[144:145], v[214:215], 0, s[64:65]
	s_mov_b32 m0, s36
	s_nop 0
	global_load_lds_dwordx4 v[144:145], off
	v_lshl_add_u64 v[144:145], v[242:243], 0, s[64:65]
	s_mov_b32 m0, s38
	s_nop 0
	global_load_lds_dwordx4 v[144:145], off
	s_waitcnt vmcnt(8)
	s_waitcnt lgkmcnt(0)
	s_setprio 1
	s_cmp_eq_u32 s32, 0
	s_cbranch_scc1 .Lrs_30
	s_barrier
	s_setprio 2
.Lrs_30:
	v_mfma_f32_16x16x32_bf16 v[60:63], v[140:143], v[194:197], v[60:63]
	v_mfma_f32_16x16x32_bf16 v[60:63], v[152:155], v[200:203], v[60:63]
	v_mfma_f32_16x16x32_bf16 v[56:59], v[160:163], v[200:203], v[56:59]
	v_mfma_f32_16x16x32_bf16 v[56:59], v[156:159], v[194:197], v[56:59]
	v_mfma_f32_16x16x32_bf16 v[52:55], v[164:167], v[194:197], v[52:55]
	v_mfma_f32_16x16x32_bf16 v[52:55], v[182:185], v[200:203], v[52:55]
	v_mfma_f32_16x16x32_bf16 v[48:51], v[190:193], v[200:203], v[48:51]
	v_mfma_f32_16x16x32_bf16 v[48:51], v[186:189], v[194:197], v[48:51]
	v_mfma_f32_16x16x32_bf16 v[32:35], v[186:189], v[204:207], v[32:35]
	v_mfma_f32_16x16x32_bf16 v[32:35], v[190:193], v[210:213], v[32:35]
	v_mfma_f32_16x16x32_bf16 v[36:39], v[182:185], v[210:213], v[36:39]
	v_mfma_f32_16x16x32_bf16 v[36:39], v[164:167], v[204:207], v[36:39]
	v_mfma_f32_16x16x32_bf16 v[40:43], v[156:159], v[204:207], v[40:43]
	v_mfma_f32_16x16x32_bf16 v[40:43], v[160:163], v[210:213], v[40:43]
	v_mfma_f32_16x16x32_bf16 v[44:47], v[152:155], v[210:213], v[44:47]
	v_mfma_f32_16x16x32_bf16 v[44:47], v[140:143], v[204:207], v[44:47]
	v_mfma_f32_16x16x32_bf16 v[28:31], v[140:143], v[226:229], v[28:31]
	v_mfma_f32_16x16x32_bf16 v[28:31], v[152:155], v[230:233], v[28:31]
	v_mfma_f32_16x16x32_bf16 v[24:27], v[160:163], v[230:233], v[24:27]
	v_mfma_f32_16x16x32_bf16 v[24:27], v[156:159], v[226:229], v[24:27]
	v_mfma_f32_16x16x32_bf16 v[20:23], v[164:167], v[226:229], v[20:23]
	v_mfma_f32_16x16x32_bf16 v[20:23], v[182:185], v[230:233], v[20:23]
	v_mfma_f32_16x16x32_bf16 v[16:19], v[190:193], v[230:233], v[16:19]
	v_mfma_f32_16x16x32_bf16 v[16:19], v[186:189], v[226:229], v[16:19]
	v_mfma_f32_16x16x32_bf16 v[0:3], v[186:189], v[234:237], v[0:3]
	v_mfma_f32_16x16x32_bf16 v[0:3], v[190:193], v[238:241], v[0:3]
	v_mfma_f32_16x16x32_bf16 v[4:7], v[182:185], v[238:241], v[4:7]
	v_mfma_f32_16x16x32_bf16 v[4:7], v[164:167], v[234:237], v[4:7]
	v_mfma_f32_16x16x32_bf16 v[8:11], v[156:159], v[234:237], v[8:11]
	v_mfma_f32_16x16x32_bf16 v[8:11], v[160:163], v[238:241], v[8:11]
	v_mfma_f32_16x16x32_bf16 v[12:15], v[152:155], v[238:241], v[12:15]
	v_mfma_f32_16x16x32_bf16 v[12:15], v[140:143], v[234:237], v[12:15]
	s_cmp_lg_u32 s32, 0
	s_cbranch_scc1 .Lrs_31
	s_barrier
.Lrs_31:
	s_setprio 0
	s_add_i32 s53, s53, 2
	s_add_u32 s22, s22, 0x100
	s_addc_u32 s23, s23, 0
	s_add_u32 s47, s47, 0x100
	s_addc_u32 s51, s51, 0
	s_cmp_gt_u32 s53, 29
.LBB0_582:
	s_add_u32 s20, s22, 0xfff80080
	s_addc_u32 s21, s23, -1
	s_add_i32 s46, 0, 0x10000
	s_cmp_eq_u32 s53, 28
	s_cselect_b32 s27, s41, s21
	s_cselect_b32 s26, s42, s20
	v_add_u32_e32 v144, s46, v147
	s_cselect_b32 s21, s43, s51
	s_cselect_b32 s20, s44, s47
	s_add_i32 s58, 0, 0x14000
	ds_read_b128 v[140:143], v144
	ds_read_b128 v[152:155], v144 offset:1024
	ds_read_b128 v[156:159], v144 offset:2048
	ds_read_b128 v[160:163], v144 offset:3072
	v_add_u32_e32 v144, s58, v147
	ds_read_b128 v[164:167], v144
	ds_read_b128 v[182:185], v144 offset:1024
	ds_read_b128 v[186:189], v144 offset:2048
	ds_read_b128 v[190:193], v144 offset:3072
	v_lshl_add_u64 v[144:145], s[22:23], 0, v[136:137]
	s_add_i32 m0, s30, 0xc000
	ds_read_b128 v[194:197], v150
	ds_read_b128 v[200:203], v150 offset:1024
	ds_read_b128 v[204:207], v150 offset:2048
	ds_read_b128 v[210:213], v150 offset:3072
	ds_read_b128 v[226:229], v150 offset:4096
	ds_read_b128 v[230:233], v150 offset:5120
	ds_read_b128 v[234:237], v150 offset:6144
	ds_read_b128 v[238:241], v150 offset:7168
	global_load_lds_dwordx4 v[144:145], off
	v_lshl_add_u64 v[144:145], s[22:23], 0, v[138:139]
	s_add_i32 m0, s30, 0xe000
	s_nop 0
	global_load_lds_dwordx4 v[144:145], off
	s_waitcnt vmcnt(8)
	s_waitcnt lgkmcnt(0)
	s_setprio 1
	s_cmp_eq_u32 s32, 0
	s_cbranch_scc1 .Lrs_32
	s_barrier
	s_setprio 2

; #define PG8_STAGE(bufoff, gbase, voff) do { _Pragma("unroll") for (int _i = 0; _i < 2; ++_i) \
;         __builtin_amdgcn_global_load_lds((const unsigned*)((const char*)(gbase) + (voff)[_i]), (PG8_LAS unsigned*)(lds + (bufoff) + ldsw + _i * 8192), 16, 0, 0); } while (0)
; #define PG8_LDA(dst, b, h) do { _Pragma("unroll") for (int m = 0; m < 4; ++m) _Pragma("unroll") for (int k = 0; k < 2; ++k) dst[m][k] = *(const PG8_LAS bf16x8*)(lds + PG8_SA(b, h) + aoff + m * 2048 + k * 1024); } while (0)
; #define PG8_MMA(ai, bj, At, Bt) do { __builtin_amdgcn_s_setprio(1); _Pragma("unroll") for (int m = 0; m < 4; ++m) _Pragma("unroll") for (int n = 0; n < 2; ++n) _Pragma("unroll") for (int k = 0; k < 2; ++k) \
;         acc[ai][bj][m][n] = __builtin_amdgcn_mfma_f32_16x16x32_bf16(Bt[n][k], At[m][k], acc[ai][bj][m][n], 0, 0, 0); __builtin_amdgcn_s_setprio(0); } while (0)
; #define PG8_WAIT_V(n) asm volatile("s_waitcnt vmcnt(" #n ")" ::: "memory")
; #define PG8_WAIT_L(n) asm volatile("s_waitcnt lgkmcnt(" #n ")" ::: "memory")
; #define PG8_BAR __builtin_amdgcn_s_barrier()
; #define PG8_SCHED __builtin_amdgcn_sched_barrier(0)
; template <class Epi, class Sched, bool ALIGN_EPI = false, bool SP2 = false, class Hook = NoHook, bool REVK = false>
; __device__ __forceinline__ void gemm_phase(PG8_LAS unsigned char* lds, const Gemm g, const Sched& S, const Epi& E, const Hook H = Hook()) {
;     ...
;             PG8_LDA(At, 0, 1); PG8_STAGE(PG8_SB(0, 0), b2, voffB); PG8_STAGE(PG8_SB(0, 1), b2 + hstep, voffB); PG8_STAGE(PG8_SA(0, 0), a2, voffA);
;             PG8_WAIT_V(8); PG8_WAIT_L(0); PG8_BAR; PG8_MMA(1, 0, At, B0); PG8_MMA(1, 1, At, B1); PG8_BAR; PG8_SCHED;
.Lrs_33:
	s_setprio 0
	s_add_i32 s46, s46, s10
	v_lshl_add_u64 v[144:145], s[20:21], 0, v[128:129]
	s_mov_b32 m0, s46
	ds_read_b128 v[194:197], v150 offset:16384
	ds_read_b128 v[200:203], v150 offset:17408
	ds_read_b128 v[204:207], v150 offset:18432
	ds_read_b128 v[210:213], v150 offset:19456
	ds_read_b128 v[226:229], v150 offset:20480
	ds_read_b128 v[230:233], v150 offset:21504
	ds_read_b128 v[234:237], v150 offset:22528
	ds_read_b128 v[238:241], v150 offset:23552
	global_load_lds_dwordx4 v[144:145], off
	s_add_i32 m0, s46, 0x2000
	s_add_u32 s56, s20, 0x80000
	v_lshl_add_u64 v[168:169], s[20:21], 0, v[130:131]
	s_addc_u32 s57, s21, 0
	s_add_i32 s46, s58, s10
	global_load_lds_dwordx4 v[168:169], off
	v_lshl_add_u64 v[214:215], s[56:57], 0, v[128:129]
	s_mov_b32 m0, s46
	v_lshl_add_u64 v[242:243], s[26:27], 0, v[132:133]
	global_load_lds_dwordx4 v[214:215], off
	v_lshl_add_u64 v[214:215], s[56:57], 0, v[130:131]
	s_add_i32 m0, s46, 0x2000
	s_nop 0
	global_load_lds_dwordx4 v[214:215], off
	v_lshl_add_u64 v[214:215], s[26:27], 0, v[134:135]
	s_mov_b32 m0, s30
	s_nop 0
	global_load_lds_dwordx4 v[214:215], off
	s_mov_b32 m0, s31
	s_nop 0
	global_load_lds_dwordx4 v[242:243], off
	s_waitcnt vmcnt(8)
	s_waitcnt lgkmcnt(0)
	s_setprio 1
	s_cmp_eq_u32 s32, 0
	s_cbranch_scc1 .Lrs_34
	s_barrier
	s_setprio 2

; __device__ __forceinline__ unsigned cvt_pk_bf16(float lo, float hi) { f32x2_t v = {lo, hi}; bf16x2_t b = __builtin_convertvector(v, bf16x2_t); return __builtin_bit_cast(unsigned, b); }
; #define PG8_BAR __builtin_amdgcn_s_barrier()
;     __device__ __forceinline__ void operator()(const f32x4 (&acc)[2][2][4][2], const Unit& u, int wr, int wc, int fr, int fq, int ui) const {
;     ...
;             for (int m = 0; m < 4; ++m) { const int row = row0 + ai * HALF + m * 16; bf16_t* rowp = O + (size_t)row * ldc + col0;
;                 const float rs = rstab[ui * 256 + wr * 64 + fr + ai * HALF + m * 16];
; #pragma unroll
;                 for (int bj = 0; bj < 2; ++bj) { f32x4 v0 = acc[ai][bj][m][0] * rs, v1 = acc[ai][bj][m][1] * rs;
;                     if (ACT == 2) {
; #pragma unroll
;                         for (int e = 0; e < 4; ++e) { const float a = fmaxf(v0[e], 0.f), b = fmaxf(v1[e], 0.f); v0[e] = a * a; v1[e] = b * b; } }
;                     u32x4 w; w.x = cvt_pk_bf16(v0[0], v0[1]); w.y = cvt_pk_bf16(v0[2], v0[3]); w.z = cvt_pk_bf16(v1[0], v1[1]); w.w = cvt_pk_bf16(v1[2], v1[3]);
;                     *(u32x4*)(rowp + bj * HALF) = w; } }
; template <class Epi, class Sched, bool ALIGN_EPI = false, bool SP2 = false, class Hook = NoHook, bool REVK = false>
; __device__ __forceinline__ void gemm_phase(PG8_LAS unsigned char* lds, const Gemm g, const Sched& S, const Epi& E, const Hook H = Hook()) {
;     ...
;         }
;         if constexpr (Hook::ENABLED) H(acc, nt, nt, ui, wr, fr);
;         if constexpr (ALIGN_EPI) { if (wr == 0) PG8_BAR; }
;         if constexpr (!Epi::AFTER_DRAIN) { E(acc, cur, wr, wc, fr, fq, ui); S.done(cur); }
.Lrs_39:
	s_setprio 0
	s_add_i32 s53, s53, 2
	s_add_u32 s22, s22, 0x100
	s_addc_u32 s23, s23, 0
	s_add_u32 s47, s47, 0x100
	s_addc_u32 s51, s51, 0
	s_cmp_gt_u32 s53, 29
	s_cbranch_scc0 .LBB0_582
	s_and_b64 vcc, exec, s[82:83]
	s_cbranch_vccz .LBB0_585
.LBB0_585:
	s_nop 7
	s_nop 7
	v_lshl_add_u32 v151, s4, 10, v148
	ds_read2_b32 v[152:153], v151 offset1:16
	v_lshl_add_u32 v142, s40, 8, v146
	v_lshl_or_b32 v140, s5, 8, v149
	v_ashrrev_i32_e32 v143, 31, v142
	v_ashrrev_i32_e32 v141, 31, v140
	v_lshlrev_b64 v[144:145], 14, v[142:143]
	s_waitcnt lgkmcnt(0)
	v_pk_mul_f32 v[120:121], v[120:121], v[152:153] op_sel_hi:[1,0]
	v_lshl_add_u64 v[154:155], s[14:15], 0, v[144:145]
	v_lshlrev_b64 v[144:145], 1, v[140:141]
	v_pk_mul_f32 v[126:127], v[126:127], v[152:153] op_sel_hi:[1,0]
	v_pk_mul_f32 v[124:125], v[124:125], v[152:153] op_sel_hi:[1,0]
	v_pk_mul_f32 v[122:123], v[122:123], v[152:153] op_sel_hi:[1,0]
	v_max_f32_e32 v120, 0, v120
	v_max_f32_e32 v121, 0, v121
	v_lshl_add_u64 v[140:141], v[154:155], 0, v[144:145]
	v_max_f32_e32 v124, 0, v124
	v_max_f32_e32 v125, 0, v125
	v_pk_mul_f32 v[154:155], v[120:121], v[120:121]
	v_max_f32_e32 v120, 0, v126
	v_max_f32_e32 v122, 0, v122
	v_max_f32_e32 v121, 0, v127
	v_max_f32_e32 v123, 0, v123
	v_pk_mul_f32 v[124:125], v[124:125], v[124:125]
	v_pk_mul_f32 v[126:127], v[120:121], v[120:121]
	v_pk_mul_f32 v[156:157], v[122:123], v[122:123]
	v_pk_mul_f32 v[112:113], v[112:113], v[152:153] op_sel_hi:[1,0]
	v_cvt_pk_bf16_f32 v120, v124, v125
	v_cvt_pk_bf16_f32 v121, v126, v127
	v_cvt_pk_bf16_f32 v122, v154, v155
	v_cvt_pk_bf16_f32 v123, v156, v157
	v_pk_mul_f32 v[118:119], v[118:119], v[152:153] op_sel_hi:[1,0]
	v_pk_mul_f32 v[116:117], v[116:117], v[152:153] op_sel_hi:[1,0]
	v_pk_mul_f32 v[114:115], v[114:115], v[152:153] op_sel_hi:[1,0]
	v_max_f32_e32 v112, 0, v112
	v_max_f32_e32 v113, 0, v113
	global_store_dwordx4 v[140:141], v[120:123], off
	v_max_f32_e32 v116, 0, v116
	v_max_f32_e32 v117, 0, v117
	v_pk_mul_f32 v[120:121], v[112:113], v[112:113]
	v_max_f32_e32 v112, 0, v118
	v_max_f32_e32 v114, 0, v114
	v_max_f32_e32 v113, 0, v119
	v_max_f32_e32 v115, 0, v115
	v_pk_mul_f32 v[116:117], v[116:117], v[116:117]
	v_pk_mul_f32 v[118:119], v[112:113], v[112:113]
	v_pk_mul_f32 v[122:123], v[114:115], v[114:115]
	v_cvt_pk_bf16_f32 v112, v116, v117
	v_cvt_pk_bf16_f32 v113, v118, v119
	v_cvt_pk_bf16_f32 v114, v120, v121
	v_cvt_pk_bf16_f32 v115, v122, v123
	global_store_dwordx4 v[140:141], v[112:115], off offset:256
	s_mov_b64 s[4:5], 0x200000
	s_nop 0
	v_mov_b32_e32 v114, v153
	v_or_b32_e32 v112, 16, v142
	v_pk_mul_f32 v[104:105], v[104:105], v[114:115] op_sel_hi:[1,0]
	v_ashrrev_i32_e32 v113, 31, v112
	v_pk_mul_f32 v[110:111], v[110:111], v[114:115] op_sel_hi:[1,0]
	v_pk_mul_f32 v[108:109], v[108:109], v[114:115] op_sel_hi:[1,0]
	v_pk_mul_f32 v[106:107], v[106:107], v[114:115] op_sel_hi:[1,0]
	v_max_f32_e32 v104, 0, v104
	v_max_f32_e32 v105, 0, v105
	v_lshlrev_b64 v[112:113], 14, v[112:113]
	v_max_f32_e32 v108, 0, v108
	v_max_f32_e32 v109, 0, v109
	v_pk_mul_f32 v[116:117], v[104:105], v[104:105]
	v_max_f32_e32 v104, 0, v110
	v_max_f32_e32 v106, 0, v106
	v_max_f32_e32 v105, 0, v111
	v_max_f32_e32 v107, 0, v107
	v_lshl_add_u64 v[112:113], s[14:15], 0, v[112:113]
	v_pk_mul_f32 v[108:109], v[108:109], v[108:109]
	v_pk_mul_f32 v[110:111], v[104:105], v[104:105]
	v_pk_mul_f32 v[118:119], v[106:107], v[106:107]
	v_pk_mul_f32 v[96:97], v[96:97], v[114:115] op_sel_hi:[1,0]
	v_lshl_add_u64 v[112:113], v[112:113], 0, v[144:145]
	v_cvt_pk_bf16_f32 v104, v108, v109
	v_cvt_pk_bf16_f32 v105, v110, v111
	v_cvt_pk_bf16_f32 v106, v116, v117
	v_cvt_pk_bf16_f32 v107, v118, v119
	v_pk_mul_f32 v[102:103], v[102:103], v[114:115] op_sel_hi:[1,0]
	v_pk_mul_f32 v[100:101], v[100:101], v[114:115] op_sel_hi:[1,0]
	v_pk_mul_f32 v[98:99], v[98:99], v[114:115] op_sel_hi:[1,0]
	v_max_f32_e32 v96, 0, v96
	v_max_f32_e32 v97, 0, v97
	global_store_dwordx4 v[112:113], v[104:107], off
	v_max_f32_e32 v100, 0, v100
	v_max_f32_e32 v101, 0, v101
	v_pk_mul_f32 v[104:105], v[96:97], v[96:97]
	v_max_f32_e32 v96, 0, v102
	v_max_f32_e32 v98, 0, v98
	v_max_f32_e32 v97, 0, v103
	v_max_f32_e32 v99, 0, v99
	v_pk_mul_f32 v[100:101], v[100:101], v[100:101]
	v_pk_mul_f32 v[102:103], v[96:97], v[96:97]
	v_pk_mul_f32 v[106:107], v[98:99], v[98:99]
	v_cvt_pk_bf16_f32 v96, v100, v101
	v_cvt_pk_bf16_f32 v97, v102, v103
	v_cvt_pk_bf16_f32 v98, v104, v105
	v_cvt_pk_bf16_f32 v99, v106, v107
	global_store_dwordx4 v[112:113], v[96:99], off offset:256
	ds_read2_b32 v[98:99], v151 offset0:32 offset1:48
	s_waitcnt lgkmcnt(0)
; __device__ __forceinline__ unsigned cvt_pk_bf16(float lo, float hi) { f32x2_t v = {lo, hi}; bf16x2_t b = __builtin_convertvector(v, bf16x2_t); return __builtin_bit_cast(unsigned, b); }
;     __device__ __forceinline__ void operator()(const f32x4 (&acc)[2][2][4][2], const Unit& u, int wr, int wc, int fr, int fq, int ui) const {
;     ...
;             for (int m = 0; m < 4; ++m) { const int row = row0 + ai * HALF + m * 16; bf16_t* rowp = O + (size_t)row * ldc + col0;
;                 const float rs = rstab[ui * 256 + wr * 64 + fr + ai * HALF + m * 16];
; #pragma unroll
;                 for (int bj = 0; bj < 2; ++bj) { f32x4 v0 = acc[ai][bj][m][0] * rs, v1 = acc[ai][bj][m][1] * rs;
;                     if (ACT == 2) {
; #pragma unroll
;                         for (int e = 0; e < 4; ++e) { const float a = fmaxf(v0[e], 0.f), b = fmaxf(v1[e], 0.f); v0[e] = a * a; v1[e] = b * b; } }
;                     u32x4 w; w.x = cvt_pk_bf16(v0[0], v0[1]); w.y = cvt_pk_bf16(v0[2], v0[3]); w.z = cvt_pk_bf16(v1[0], v1[1]); w.w = cvt_pk_bf16(v1[2], v1[3]);
;                     *(u32x4*)(rowp + bj * HALF) = w; } }
	v_pk_mul_f32 v[88:89], v[88:89], v[98:99] op_sel_hi:[1,0]
	v_or_b32_e32 v96, 32, v142
	v_ashrrev_i32_e32 v97, 31, v96
	v_pk_mul_f32 v[94:95], v[94:95], v[98:99] op_sel_hi:[1,0]
	v_pk_mul_f32 v[92:93], v[92:93], v[98:99] op_sel_hi:[1,0]
	v_pk_mul_f32 v[90:91], v[90:91], v[98:99] op_sel_hi:[1,0]
	v_max_f32_e32 v88, 0, v88
	v_max_f32_e32 v89, 0, v89
	v_lshlrev_b64 v[96:97], 14, v[96:97]
	v_max_f32_e32 v92, 0, v92
	v_max_f32_e32 v93, 0, v93
	v_pk_mul_f32 v[100:101], v[88:89], v[88:89]
	v_max_f32_e32 v88, 0, v94
	v_max_f32_e32 v90, 0, v90
	v_max_f32_e32 v89, 0, v95
	v_max_f32_e32 v91, 0, v91
	v_lshl_add_u64 v[96:97], s[14:15], 0, v[96:97]
	v_pk_mul_f32 v[92:93], v[92:93], v[92:93]
	v_pk_mul_f32 v[94:95], v[88:89], v[88:89]
	v_pk_mul_f32 v[102:103], v[90:91], v[90:91]
	v_pk_mul_f32 v[80:81], v[80:81], v[98:99] op_sel_hi:[1,0]
	v_lshl_add_u64 v[96:97], v[96:97], 0, v[144:145]
	v_cvt_pk_bf16_f32 v88, v92, v93
	v_cvt_pk_bf16_f32 v89, v94, v95
	v_cvt_pk_bf16_f32 v90, v100, v101
	v_cvt_pk_bf16_f32 v91, v102, v103
	v_pk_mul_f32 v[86:87], v[86:87], v[98:99] op_sel_hi:[1,0]
	v_pk_mul_f32 v[84:85], v[84:85], v[98:99] op_sel_hi:[1,0]
	v_pk_mul_f32 v[82:83], v[82:83], v[98:99] op_sel_hi:[1,0]
	v_max_f32_e32 v80, 0, v80
	v_max_f32_e32 v81, 0, v81
	global_store_dwordx4 v[96:97], v[88:91], off
	v_max_f32_e32 v84, 0, v84
	v_max_f32_e32 v85, 0, v85
	v_pk_mul_f32 v[88:89], v[80:81], v[80:81]
	v_max_f32_e32 v80, 0, v86
	v_max_f32_e32 v82, 0, v82
	v_max_f32_e32 v81, 0, v87
	v_max_f32_e32 v83, 0, v83
	v_pk_mul_f32 v[84:85], v[84:85], v[84:85]
	v_pk_mul_f32 v[86:87], v[80:81], v[80:81]
	v_pk_mul_f32 v[90:91], v[82:83], v[82:83]
	v_cvt_pk_bf16_f32 v80, v84, v85
	v_cvt_pk_bf16_f32 v81, v86, v87
	v_cvt_pk_bf16_f32 v82, v88, v89
	v_cvt_pk_bf16_f32 v83, v90, v91
	global_store_dwordx4 v[96:97], v[80:83], off offset:256
	s_nop 1
	v_mov_b32_e32 v82, v99
	v_or_b32_e32 v80, 48, v142
	v_pk_mul_f32 v[72:73], v[72:73], v[82:83] op_sel_hi:[1,0]
	v_ashrrev_i32_e32 v81, 31, v80
	v_pk_mul_f32 v[78:79], v[78:79], v[82:83] op_sel_hi:[1,0]
	v_pk_mul_f32 v[76:77], v[76:77], v[82:83] op_sel_hi:[1,0]
	v_pk_mul_f32 v[74:75], v[74:75], v[82:83] op_sel_hi:[1,0]
	v_max_f32_e32 v72, 0, v72
	v_max_f32_e32 v73, 0, v73
	v_lshlrev_b64 v[80:81], 14, v[80:81]
	v_max_f32_e32 v76, 0, v76
	v_max_f32_e32 v77, 0, v77
	v_pk_mul_f32 v[84:85], v[72:73], v[72:73]
	v_max_f32_e32 v72, 0, v78
	v_max_f32_e32 v74, 0, v74
	v_max_f32_e32 v73, 0, v79
	v_max_f32_e32 v75, 0, v75
	v_lshl_add_u64 v[80:81], s[14:15], 0, v[80:81]
	v_pk_mul_f32 v[76:77], v[76:77], v[76:77]
	v_pk_mul_f32 v[78:79], v[72:73], v[72:73]
	v_pk_mul_f32 v[86:87], v[74:75], v[74:75]
	v_pk_mul_f32 v[68:69], v[68:69], v[82:83] op_sel_hi:[1,0]
	v_pk_mul_f32 v[64:65], v[64:65], v[82:83] op_sel_hi:[1,0]
	v_lshl_add_u64 v[80:81], v[80:81], 0, v[144:145]
	v_cvt_pk_bf16_f32 v72, v76, v77
	v_cvt_pk_bf16_f32 v73, v78, v79
	v_cvt_pk_bf16_f32 v74, v84, v85
	v_cvt_pk_bf16_f32 v75, v86, v87
	v_pk_mul_f32 v[70:71], v[70:71], v[82:83] op_sel_hi:[1,0]
	v_max_f32_e32 v68, 0, v68
	v_max_f32_e32 v64, 0, v64
	v_max_f32_e32 v69, 0, v69
	v_max_f32_e32 v65, 0, v65
	global_store_dwordx4 v[80:81], v[72:75], off
	v_pk_mul_f32 v[68:69], v[68:69], v[68:69]
	v_pk_mul_f32 v[66:67], v[66:67], v[82:83] op_sel_hi:[1,0]
	v_pk_mul_f32 v[72:73], v[64:65], v[64:65]
	v_max_f32_e32 v64, 0, v70
	v_max_f32_e32 v65, 0, v71
	v_pk_mul_f32 v[70:71], v[64:65], v[64:65]
	v_cvt_pk_bf16_f32 v64, v68, v69
	ds_read2_b32 v[68:69], v151 offset0:128 offset1:144
	v_max_f32_e32 v66, 0, v66
	v_max_f32_e32 v67, 0, v67
	v_pk_mul_f32 v[74:75], v[66:67], v[66:67]
	v_cvt_pk_bf16_f32 v65, v70, v71
	s_waitcnt lgkmcnt(0)
	v_pk_mul_f32 v[60:61], v[60:61], v[68:69] op_sel_hi:[1,0]
	v_pk_mul_f32 v[56:57], v[56:57], v[68:69] op_sel_hi:[1,0]
	v_cvt_pk_bf16_f32 v66, v72, v73
	v_cvt_pk_bf16_f32 v67, v74, v75
	v_pk_mul_f32 v[62:63], v[62:63], v[68:69] op_sel_hi:[1,0]
	v_pk_mul_f32 v[58:59], v[58:59], v[68:69] op_sel_hi:[1,0]
	v_max_f32_e32 v60, 0, v60
	v_max_f32_e32 v56, 0, v56
	v_max_f32_e32 v61, 0, v61
	v_max_f32_e32 v57, 0, v57
	global_store_dwordx4 v[80:81], v[64:67], off offset:256
	v_pk_mul_f32 v[60:61], v[60:61], v[60:61]
	v_max_f32_e32 v58, 0, v58
	v_lshl_add_u64 v[64:65], v[140:141], 0, s[4:5]
	v_pk_mul_f32 v[66:67], v[56:57], v[56:57]
	v_max_f32_e32 v56, 0, v62
	v_max_f32_e32 v57, 0, v63
	v_max_f32_e32 v59, 0, v59
	s_mov_b32 s4, 0x200000
	v_pk_mul_f32 v[62:63], v[56:57], v[56:57]
	v_pk_mul_f32 v[70:71], v[58:59], v[58:59]
	v_cvt_pk_bf16_f32 v56, v60, v61
	v_add_co_u32_e32 v60, vcc, s4, v140
	v_pk_mul_f32 v[48:49], v[48:49], v[68:69] op_sel_hi:[1,0]
	v_cvt_pk_bf16_f32 v57, v62, v63
	v_cvt_pk_bf16_f32 v58, v66, v67
	v_cvt_pk_bf16_f32 v59, v70, v71
	v_addc_co_u32_e32 v61, vcc, 0, v141, vcc
	v_pk_mul_f32 v[54:55], v[54:55], v[68:69] op_sel_hi:[1,0]
	v_pk_mul_f32 v[52:53], v[52:53], v[68:69] op_sel_hi:[1,0]
	v_pk_mul_f32 v[50:51], v[50:51], v[68:69] op_sel_hi:[1,0]
	v_max_f32_e32 v48, 0, v48
	v_max_f32_e32 v49, 0, v49
	global_store_dwordx4 v[60:61], v[56:59], off
	v_max_f32_e32 v52, 0, v52
	v_max_f32_e32 v53, 0, v53
	v_pk_mul_f32 v[56:57], v[48:49], v[48:49]
	v_max_f32_e32 v48, 0, v54
	v_max_f32_e32 v50, 0, v50
	v_max_f32_e32 v49, 0, v55
	v_max_f32_e32 v51, 0, v51
	v_pk_mul_f32 v[52:53], v[52:53], v[52:53]
	v_pk_mul_f32 v[54:55], v[48:49], v[48:49]
	v_pk_mul_f32 v[58:59], v[50:51], v[50:51]
	v_cvt_pk_bf16_f32 v48, v52, v53
	v_cvt_pk_bf16_f32 v49, v54, v55
	v_cvt_pk_bf16_f32 v50, v56, v57
	v_cvt_pk_bf16_f32 v51, v58, v59
	global_store_dwordx4 v[64:65], v[48:51], off offset:256
	s_mov_b64 s[4:5], 0x240000
	s_nop 0
; __device__ __forceinline__ unsigned cvt_pk_bf16(float lo, float hi) { f32x2_t v = {lo, hi}; bf16x2_t b = __builtin_convertvector(v, bf16x2_t); return __builtin_bit_cast(unsigned, b); }
; #define PG8_BAR __builtin_amdgcn_s_barrier()
;     __device__ __forceinline__ void operator()(const f32x4 (&acc)[2][2][4][2], const Unit& u, int wr, int wc, int fr, int fq, int ui) const {
;     ...
;             for (int m = 0; m < 4; ++m) { const int row = row0 + ai * HALF + m * 16; bf16_t* rowp = O + (size_t)row * ldc + col0;
;                 const float rs = rstab[ui * 256 + wr * 64 + fr + ai * HALF + m * 16];
; #pragma unroll
;                 for (int bj = 0; bj < 2; ++bj) { f32x4 v0 = acc[ai][bj][m][0] * rs, v1 = acc[ai][bj][m][1] * rs;
;                     if (ACT == 2) {
; #pragma unroll
;                         for (int e = 0; e < 4; ++e) { const float a = fmaxf(v0[e], 0.f), b = fmaxf(v1[e], 0.f); v0[e] = a * a; v1[e] = b * b; } }
;                     u32x4 w; w.x = cvt_pk_bf16(v0[0], v0[1]); w.y = cvt_pk_bf16(v0[2], v0[3]); w.z = cvt_pk_bf16(v1[0], v1[1]); w.w = cvt_pk_bf16(v1[2], v1[3]);
;                     *(u32x4*)(rowp + bj * HALF) = w; } }
; template <class Epi, class Sched, bool ALIGN_EPI = false, bool SP2 = false, class Hook = NoHook, bool REVK = false>
; __device__ __forceinline__ void gemm_phase(PG8_LAS unsigned char* lds, const Gemm g, const Sched& S, const Epi& E, const Hook H = Hook()) {
;     ...
;         if (!has_next) break;
; #pragma unroll
;         for (int a = 0; a < 2; ++a)
; #pragma unroll
;             for (int b = 0; b < 2; ++b)
; #pragma unroll
;                 for (int m = 0; m < 4; ++m)
; #pragma unroll
;                     for (int n = 0; n < 2; ++n) acc[a][b][m][n] = (f32x4){0.f, 0.f, 0.f, 0.f};
;         cur = nxt; cA = nA; cB = nB; ++ui;
;         if constexpr (ALIGN_EPI) { if (wr == 1) PG8_BAR; }
	v_mov_b32_e32 v50, v69
	v_pk_mul_f32 v[44:45], v[44:45], v[50:51] op_sel_hi:[1,0]
	v_pk_mul_f32 v[40:41], v[40:41], v[50:51] op_sel_hi:[1,0]
	v_pk_mul_f32 v[46:47], v[46:47], v[50:51] op_sel_hi:[1,0]
	v_pk_mul_f32 v[42:43], v[42:43], v[50:51] op_sel_hi:[1,0]
	v_max_f32_e32 v44, 0, v44
	v_max_f32_e32 v40, 0, v40
	v_max_f32_e32 v45, 0, v45
	v_max_f32_e32 v41, 0, v41
	v_lshl_add_u64 v[48:49], v[140:141], 0, s[4:5]
	v_pk_mul_f32 v[44:45], v[44:45], v[44:45]
	v_pk_mul_f32 v[52:53], v[40:41], v[40:41]
	v_max_f32_e32 v40, 0, v46
	v_max_f32_e32 v42, 0, v42
	v_max_f32_e32 v41, 0, v47
	v_max_f32_e32 v43, 0, v43
	s_mov_b32 s4, 0x240000
	v_pk_mul_f32 v[46:47], v[40:41], v[40:41]
	v_pk_mul_f32 v[54:55], v[42:43], v[42:43]
	v_cvt_pk_bf16_f32 v40, v44, v45
	v_add_co_u32_e32 v44, vcc, s4, v140
	v_pk_mul_f32 v[36:37], v[36:37], v[50:51] op_sel_hi:[1,0]
	v_pk_mul_f32 v[32:33], v[32:33], v[50:51] op_sel_hi:[1,0]
	v_cvt_pk_bf16_f32 v41, v46, v47
	v_cvt_pk_bf16_f32 v42, v52, v53
	v_cvt_pk_bf16_f32 v43, v54, v55
	v_addc_co_u32_e32 v45, vcc, 0, v141, vcc
	v_pk_mul_f32 v[38:39], v[38:39], v[50:51] op_sel_hi:[1,0]
	v_max_f32_e32 v36, 0, v36
	v_max_f32_e32 v32, 0, v32
	v_max_f32_e32 v37, 0, v37
	v_max_f32_e32 v33, 0, v33
	global_store_dwordx4 v[44:45], v[40:43], off
	v_pk_mul_f32 v[36:37], v[36:37], v[36:37]
	v_pk_mul_f32 v[34:35], v[34:35], v[50:51] op_sel_hi:[1,0]
	v_pk_mul_f32 v[40:41], v[32:33], v[32:33]
	v_max_f32_e32 v32, 0, v38
	v_max_f32_e32 v33, 0, v39
	v_pk_mul_f32 v[38:39], v[32:33], v[32:33]
	v_cvt_pk_bf16_f32 v32, v36, v37
	ds_read2_b32 v[36:37], v151 offset0:160 offset1:176
	v_max_f32_e32 v34, 0, v34
	v_max_f32_e32 v35, 0, v35
	v_pk_mul_f32 v[42:43], v[34:35], v[34:35]
	v_cvt_pk_bf16_f32 v33, v38, v39
	s_waitcnt lgkmcnt(0)
	v_pk_mul_f32 v[28:29], v[28:29], v[36:37] op_sel_hi:[1,0]
	v_pk_mul_f32 v[24:25], v[24:25], v[36:37] op_sel_hi:[1,0]
	v_cvt_pk_bf16_f32 v34, v40, v41
	v_cvt_pk_bf16_f32 v35, v42, v43
	s_mov_b64 s[4:5], 0x280000
	v_pk_mul_f32 v[30:31], v[30:31], v[36:37] op_sel_hi:[1,0]
	v_pk_mul_f32 v[26:27], v[26:27], v[36:37] op_sel_hi:[1,0]
	v_max_f32_e32 v28, 0, v28
	v_max_f32_e32 v24, 0, v24
	v_max_f32_e32 v29, 0, v29
	v_max_f32_e32 v25, 0, v25
	global_store_dwordx4 v[48:49], v[32:35], off offset:256
	v_pk_mul_f32 v[28:29], v[28:29], v[28:29]
	v_max_f32_e32 v26, 0, v26
	v_lshl_add_u64 v[32:33], v[140:141], 0, s[4:5]
	v_pk_mul_f32 v[34:35], v[24:25], v[24:25]
	v_max_f32_e32 v24, 0, v30
	v_max_f32_e32 v25, 0, v31
	v_max_f32_e32 v27, 0, v27
	s_mov_b32 s4, 0x280000
	v_pk_mul_f32 v[30:31], v[24:25], v[24:25]
	v_pk_mul_f32 v[38:39], v[26:27], v[26:27]
	v_cvt_pk_bf16_f32 v24, v28, v29
	v_add_co_u32_e32 v28, vcc, s4, v140
	v_pk_mul_f32 v[16:17], v[16:17], v[36:37] op_sel_hi:[1,0]
	v_cvt_pk_bf16_f32 v25, v30, v31
	v_cvt_pk_bf16_f32 v26, v34, v35
	v_cvt_pk_bf16_f32 v27, v38, v39
	v_addc_co_u32_e32 v29, vcc, 0, v141, vcc
	v_pk_mul_f32 v[22:23], v[22:23], v[36:37] op_sel_hi:[1,0]
	v_pk_mul_f32 v[20:21], v[20:21], v[36:37] op_sel_hi:[1,0]
	v_pk_mul_f32 v[18:19], v[18:19], v[36:37] op_sel_hi:[1,0]
	v_max_f32_e32 v16, 0, v16
	v_max_f32_e32 v17, 0, v17
	global_store_dwordx4 v[28:29], v[24:27], off
	v_max_f32_e32 v20, 0, v20
	v_max_f32_e32 v21, 0, v21
	v_pk_mul_f32 v[24:25], v[16:17], v[16:17]
	v_max_f32_e32 v16, 0, v22
	v_max_f32_e32 v18, 0, v18
	v_max_f32_e32 v17, 0, v23
	v_max_f32_e32 v19, 0, v19
	v_pk_mul_f32 v[20:21], v[20:21], v[20:21]
	v_pk_mul_f32 v[22:23], v[16:17], v[16:17]
	v_pk_mul_f32 v[26:27], v[18:19], v[18:19]
	v_cvt_pk_bf16_f32 v16, v20, v21
	v_cvt_pk_bf16_f32 v17, v22, v23
	v_cvt_pk_bf16_f32 v18, v24, v25
	v_cvt_pk_bf16_f32 v19, v26, v27
	global_store_dwordx4 v[32:33], v[16:19], off offset:256
	s_mov_b64 s[4:5], 0x2c0000
	s_nop 0
	v_mov_b32_e32 v18, v37
	v_pk_mul_f32 v[12:13], v[12:13], v[18:19] op_sel_hi:[1,0]
	v_pk_mul_f32 v[8:9], v[8:9], v[18:19] op_sel_hi:[1,0]
	v_pk_mul_f32 v[14:15], v[14:15], v[18:19] op_sel_hi:[1,0]
	v_pk_mul_f32 v[10:11], v[10:11], v[18:19] op_sel_hi:[1,0]
	v_max_f32_e32 v12, 0, v12
	v_max_f32_e32 v8, 0, v8
	v_max_f32_e32 v13, 0, v13
	v_max_f32_e32 v9, 0, v9
	v_lshl_add_u64 v[16:17], v[140:141], 0, s[4:5]
	v_pk_mul_f32 v[12:13], v[12:13], v[12:13]
	v_pk_mul_f32 v[20:21], v[8:9], v[8:9]
	v_max_f32_e32 v8, 0, v14
	v_max_f32_e32 v10, 0, v10
	v_max_f32_e32 v9, 0, v15
	v_max_f32_e32 v11, 0, v11
	s_mov_b32 s4, 0x2c0000
	v_pk_mul_f32 v[14:15], v[8:9], v[8:9]
	v_pk_mul_f32 v[22:23], v[10:11], v[10:11]
	v_cvt_pk_bf16_f32 v8, v12, v13
	v_add_co_u32_e32 v12, vcc, s4, v140
	v_pk_mul_f32 v[0:1], v[0:1], v[18:19] op_sel_hi:[1,0]
	v_cvt_pk_bf16_f32 v9, v14, v15
	v_cvt_pk_bf16_f32 v10, v20, v21
	v_cvt_pk_bf16_f32 v11, v22, v23
	v_addc_co_u32_e32 v13, vcc, 0, v141, vcc
	v_pk_mul_f32 v[6:7], v[6:7], v[18:19] op_sel_hi:[1,0]
	v_pk_mul_f32 v[4:5], v[4:5], v[18:19] op_sel_hi:[1,0]
	v_pk_mul_f32 v[2:3], v[2:3], v[18:19] op_sel_hi:[1,0]
	v_max_f32_e32 v0, 0, v0
	v_max_f32_e32 v1, 0, v1
	global_store_dwordx4 v[12:13], v[8:11], off
	v_max_f32_e32 v4, 0, v4
	v_max_f32_e32 v5, 0, v5
	v_pk_mul_f32 v[8:9], v[0:1], v[0:1]
	v_max_f32_e32 v0, 0, v6
	v_max_f32_e32 v2, 0, v2
	v_max_f32_e32 v1, 0, v7
	v_max_f32_e32 v3, 0, v3
	v_pk_mul_f32 v[4:5], v[4:5], v[4:5]
	v_pk_mul_f32 v[6:7], v[0:1], v[0:1]
	v_pk_mul_f32 v[10:11], v[2:3], v[2:3]
	v_cvt_pk_bf16_f32 v0, v4, v5
	v_cvt_pk_bf16_f32 v1, v6, v7
	v_cvt_pk_bf16_f32 v2, v8, v9
	v_cvt_pk_bf16_f32 v3, v10, v11
	s_andn2_b64 vcc, exec, s[6:7]
	s_mov_b64 s[6:7], -1
	global_store_dwordx4 v[16:17], v[0:3], off offset:256
	s_cbranch_vccnz .LBB0_574
	s_andn2_b64 vcc, exec, s[12:13]
	s_cbranch_vccnz .LBB0_573
	s_branch .LBB0_573

; #define PG8_STAGE(bufoff, gbase, voff) do { _Pragma("unroll") for (int _i = 0; _i < 2; ++_i) \
;         __builtin_amdgcn_global_load_lds((const unsigned*)((const char*)(gbase) + (voff)[_i]), (PG8_LAS unsigned*)(lds + (bufoff) + ldsw + _i * 8192), 16, 0, 0); } while (0)
; #define PG8_WAIT_V(n) asm volatile("s_waitcnt vmcnt(" #n ")" ::: "memory")
; #define PG8_BAR __builtin_amdgcn_s_barrier()
; template <class Epi, class Sched, bool ALIGN_EPI = false, bool SP2 = false, class Hook = NoHook, bool REVK = false>
; __device__ __forceinline__ void gemm_phase(PG8_LAS unsigned char* lds, const Gemm g, const Sched& S, const Epi& E, const Hook H = Hook()) {
;     int tid_ = threadIdx.x; asm volatile("" : "+v"(tid_));
;     const int tid = tid_, wid = __builtin_amdgcn_readfirstlane(tid >> 6), lane = tid & 63, wr = wid >> 2, wc = wid & 3, fr = lane & 15, fq = lane >> 4;
;     const int K = g.K, nt = K / BK;
;     unsigned voffA[2], voffB[2];
; #pragma unroll
;     for (int i = 0; i < 2; ++i) { int R, C; stage_rc(tid * 16 + i * 8192, R, C); const int Rb = Epi::PERM ? ((R & ~31) + perm32(R & 31)) : R;
;         voffA[i] = (unsigned)(R * K + C) * 2u; voffB[i] = (unsigned)(Rb * K + C) * 2u; }
;     const long kstep = REVK ? -(long)(BK * 2) : (long)(BK * 2);
;     const size_t krev = REVK ? (size_t)(K / BK - 1) * (size_t)(BK * 2) : 0;
;     const size_t hstep = (size_t)HALF * K * 2;
;     const size_t tstep = 2 * hstep;
;     const unsigned ldsw = (unsigned)wid * 1024u;
;     const int aoff = lds_byte(wr * 64 + fr, fq * 8), boff = lds_byte(wc * 32 + fr, fq * 8);
;     ...
;     const char* cA = (const char*)g.A + (size_t)cur.pm * tstep + krev; const char* cB = (const char*)g.Bt + (size_t)cur.pn * tstep + krev;
;     S.a_ready(cur);
;     if constexpr (SP2) {
;         PG8_STAGE(PG8_SB(0, 0), cB, voffB); PG8_STAGE(PG8_SB(0, 1), cB + hstep, voffB); PG8_STAGE(PG8_SA(0, 0), cA, voffA); PG8_STAGE(PG8_SA(0, 1), cA + hstep, voffA);
;         if (wr == 1) PG8_BAR;
;         PG8_WAIT_V(2); PG8_BAR;
.LBB0_641:
	s_or_b64 exec, exec, s[6:7]
	v_readlane_b32 s6, v250, 11
	v_readlane_b32 s4, v250, 48
	v_readlane_b32 s7, v250, 12
	s_waitcnt lgkmcnt(0)
	v_mov_b32_e32 v0, v199
	v_readlane_b32 s5, v250, 49
	s_barrier
	s_and_b64 vcc, exec, s[4:5]
	v_readfirstlane_b32 s10, v0
	s_cbranch_vccnz .LBB0_681
	v_lshlrev_b32_e32 v1, 4, v0
	v_add_u32_e32 v2, 0x2000, v1
	v_ashrrev_i32_e32 v3, 31, v2
	v_lshrrev_b32_e32 v3, 22, v3
	v_add_u32_e32 v3, v2, v3
	v_ashrrev_i32_e32 v3, 10, v3
	v_mul_i32_i24_e32 v4, 0x400, v3
	v_sub_u32_e32 v2, v2, v4
	s_load_dwordx2 s[4:5], s[6:7], 0x88
	v_lshrrev_b32_e32 v4, 4, v2
	v_bitop3_b32 v2, v4, v2, 32 bitop3:0x6c
	v_ashrrev_i32_e32 v4, 31, v2
	v_lshrrev_b32_e32 v4, 26, v4
	v_add_u32_e32 v4, v2, v4
	v_lshlrev_b32_e32 v6, 3, v3
	s_waitcnt lgkmcnt(0)
	s_add_u32 s24, s4, 0x19c00000
	v_ashrrev_i32_e32 v5, 6, v4
	v_and_b32_e32 v6, -16, v6
	v_and_b32_e32 v4, 0xc0, v4
	s_addc_u32 s28, s5, 0
	v_add_u32_e32 v6, v5, v6
	v_sub_u32_e32 v2, v2, v4
	s_add_u32 s6, s4, s8
	v_and_b32_e32 v5, 3, v5
	s_mov_b32 s8, 0x3ffe0
	v_lshrrev_b32_e32 v7, 2, v6
	v_lshlrev_b32_e32 v8, 1, v6
	v_lshlrev_b32_e32 v3, 5, v3
	v_ashrrev_i16_sdwa v2, v219, sext(v2) dst_sel:DWORD dst_unused:UNUSED_PAD src0_sel:DWORD src1_sel:BYTE_0
	v_and_or_b32 v5, v6, s8, v5
	v_and_b32_e32 v7, 4, v7
	v_and_b32_e32 v8, 24, v8
	v_and_b32_e32 v3, 32, v3
	v_bfe_i32 v2, v2, 0, 16
	v_or3_b32 v5, v5, v7, v8
	v_add_lshl_u32 v2, v3, v2, 1
	v_lshl_add_u32 v162, v5, 14, v2
	v_lshl_add_u32 v164, v6, 14, v2
	v_bfe_i32 v2, v0, 27, 1
	v_lshrrev_b32_e32 v2, 22, v2
	v_add_u32_e32 v2, v1, v2
	v_and_b32_e32 v2, 0xfffffc00, v2
	v_sub_u32_e32 v1, v1, v2
	v_lshrrev_b32_e32 v2, 4, v1
	v_ashrrev_i32_e32 v4, 31, v0
	v_bitop3_b32 v1, v2, v1, 32 bitop3:0x6c
	v_lshrrev_b32_e32 v4, 26, v4
	v_ashrrev_i32_e32 v2, 31, v1
	v_add_u32_e32 v4, v0, v4
	v_lshrrev_b32_e32 v2, 26, v2
	v_ashrrev_i32_e32 v4, 6, v4
	s_addc_u32 s7, s5, s9
	v_add_u32_e32 v2, v1, v2
	v_lshlrev_b32_e32 v5, 3, v4
	s_add_u32 s29, s6, 0xdc00000
	v_ashrrev_i32_e32 v3, 6, v2
	v_and_b32_e32 v5, -16, v5
	s_addc_u32 s30, s7, 0
	s_ashr_i32 s7, s10, 6
	v_add_u32_e32 v5, v3, v5
	v_and_b32_e32 v3, 3, v3
	s_ashr_i32 s6, s10, 8
	s_lshl_b32 s31, s7, 10
	v_and_or_b32 v3, v5, s8, v3
	v_readlane_b32 s8, v250, 34
	v_readlane_b32 s9, v250, 35
	s_add_u32 s21, s24, s8
	v_and_b32_e32 v2, 0xc0, v2
	s_addc_u32 s22, s28, s9
	v_readlane_b32 s8, v250, 36
	v_sub_u32_e32 v1, v1, v2
	v_readlane_b32 s9, v250, 37
	s_add_u32 s11, s29, s8
	v_lshrrev_b32_e32 v6, 2, v5
	v_lshlrev_b32_e32 v7, 1, v5
	v_lshlrev_b32_e32 v4, 5, v4
	v_ashrrev_i16_sdwa v1, v219, sext(v1) dst_sel:DWORD dst_unused:UNUSED_PAD src0_sel:DWORD src1_sel:BYTE_0
	s_addc_u32 s20, s30, s9
	v_and_b32_e32 v6, 4, v6
	v_and_b32_e32 v7, 24, v7
	v_and_b32_e32 v4, 32, v4
	v_bfe_i32 v1, v1, 0, 16
	s_add_u32 s92, s11, 0x3f80
	v_or3_b32 v3, v3, v6, v7
	v_add_lshl_u32 v1, v4, v1, 1
	s_addc_u32 s93, s20, 0
	s_add_i32 s34, s31, 0
	v_lshl_add_u32 v128, v3, 14, v1
	s_add_i32 m0, s34, 0x10000
	v_lshl_add_u32 v166, v5, 14, v1
	global_load_lds_dwordx4 v128, s[92:93]
	s_add_i32 m0, s34, 0x12000
	s_add_u32 s8, s11, 0x203f80
	global_load_lds_dwordx4 v162, s[92:93]
	s_addc_u32 s9, s20, 0
	s_add_i32 m0, s34, 0x14000
	s_nop 0
	global_load_lds_dwordx4 v128, s[8:9]
	s_add_i32 m0, s34, 0x16000
	s_add_u32 s94, s21, 0x3f80
	s_addc_u32 s95, s22, 0
	s_add_i32 s35, s34, 0x2000
	global_load_lds_dwordx4 v162, s[8:9]
	s_mov_b32 m0, s34
	s_add_u32 s8, s21, 0x203f80
	global_load_lds_dwordx4 v166, s[94:95]
	s_mov_b32 m0, s35
	s_addc_u32 s9, s22, 0
	s_add_i32 s36, s34, 0x4000
	global_load_lds_dwordx4 v164, s[94:95]
	s_mov_b32 m0, s36
	s_add_i32 s38, s34, 0x6000
	global_load_lds_dwordx4 v166, s[8:9]
	s_mov_b32 m0, s38
	s_cmp_eq_u32 s6, 1
	global_load_lds_dwordx4 v164, s[8:9]
	s_cselect_b64 s[8:9], -1, 0
	s_mov_b32 s32, s6
	s_cmp_lg_u32 s6, 1
	s_cbranch_scc1 .LBB0_644

; #define PG8_STAGE(bufoff, gbase, voff) do { _Pragma("unroll") for (int _i = 0; _i < 2; ++_i) \
;         __builtin_amdgcn_global_load_lds((const unsigned*)((const char*)(gbase) + (voff)[_i]), (PG8_LAS unsigned*)(lds + (bufoff) + ldsw + _i * 8192), 16, 0, 0); } while (0)
; #define PG8_LDA(dst, b, h) do { _Pragma("unroll") for (int m = 0; m < 4; ++m) _Pragma("unroll") for (int k = 0; k < 2; ++k) dst[m][k] = *(const PG8_LAS bf16x8*)(lds + PG8_SA(b, h) + aoff + m * 2048 + k * 1024); } while (0)
; #define PG8_LDB(dst, b, h) do { _Pragma("unroll") for (int n = 0; n < 2; ++n) _Pragma("unroll") for (int k = 0; k < 2; ++k) dst[n][k] = *(const PG8_LAS bf16x8*)(lds + PG8_SB(b, h) + boff + n * 2048 + k * 1024); } while (0)
; #define PG8_MMA(ai, bj, At, Bt) do { __builtin_amdgcn_s_setprio(1); _Pragma("unroll") for (int m = 0; m < 4; ++m) _Pragma("unroll") for (int n = 0; n < 2; ++n) _Pragma("unroll") for (int k = 0; k < 2; ++k) \
;         acc[ai][bj][m][n] = __builtin_amdgcn_mfma_f32_16x16x32_bf16(Bt[n][k], At[m][k], acc[ai][bj][m][n], 0, 0, 0); __builtin_amdgcn_s_setprio(0); } while (0)
; #define PG8_WAIT_V(n) asm volatile("s_waitcnt vmcnt(" #n ")" ::: "memory")
; #define PG8_WAIT_L(n) asm volatile("s_waitcnt lgkmcnt(" #n ")" ::: "memory")
; #define PG8_BAR __builtin_amdgcn_s_barrier()
; #define PG8_SCHED __builtin_amdgcn_sched_barrier(0)
; template <class Epi, class Sched, bool ALIGN_EPI = false, bool SP2 = false, class Hook = NoHook, bool REVK = false>
; __device__ __forceinline__ void gemm_phase(PG8_LAS unsigned char* lds, const Gemm g, const Sched& S, const Epi& E, const Hook H = Hook()) {
;     ...
;             const char* a1 = cA + (long)(t + 1) * kstep;
;             const char* a2 = last ? nA : cA + (long)(t + 2) * kstep; const char* b2 = last ? nB : cB + (long)(t + 2) * kstep;
;             const char* a3 = a2 + kstep; const char* b3 = b2 + kstep;
;             if (last && has_next) S.a_ready(nxt);
;             if constexpr (SP2) {
;             PG8_LDB(B0, 0, 0); PG8_LDB(B1, 0, 1); PG8_SCHED; PG8_LDA(At, 0, 0); PG8_STAGE(PG8_SA(1, 1), a1 + hstep, voffA);
;             PG8_WAIT_V(8); PG8_WAIT_L(0); PG8_BAR; PG8_MMA(0, 0, At, B0); PG8_MMA(0, 1, At, B1); PG8_BAR; PG8_SCHED;
.LBB0_654:
	s_or_b32 s54, s42, 1
	s_lshl_b64 s[46:47], s[54:55], 7
	s_sub_u32 s44, 0, s46
	s_subb_u32 s46, 0, s47
	s_add_u32 s44, s94, s44
	s_addc_u32 s47, s95, s46
	s_add_i32 s51, 0, 0x10000
	s_add_i32 s53, 0, 0x14000
	v_add_u32_e32 v142, s51, v195
	v_add_u32_e32 v158, s53, v195
	ds_read_b128 v[124:127], v142
	ds_read_b128 v[134:137], v142 offset:1024
	ds_read_b128 v[138:141], v142 offset:2048
	ds_read_b128 v[142:145], v142 offset:3072
	ds_read_b128 v[146:149], v158
	ds_read_b128 v[150:153], v158 offset:1024
	ds_read_b128 v[154:157], v158 offset:2048
	ds_read_b128 v[158:161], v158 offset:3072
	s_add_u32 s46, s44, 0x200000
	s_addc_u32 s47, s47, 0
	v_lshl_add_u64 v[168:169], s[46:47], 0, v[166:167]
	s_add_i32 m0, s34, 0xc000
	ds_read_b128 v[182:185], v197
	ds_read_b128 v[186:189], v197 offset:1024
	ds_read_b128 v[190:193], v197 offset:2048
	ds_read_b128 v[200:203], v197 offset:3072
	ds_read_b128 v[204:207], v197 offset:4096
	ds_read_b128 v[210:213], v197 offset:5120
	ds_read_b128 v[226:229], v197 offset:6144
	ds_read_b128 v[230:233], v197 offset:7168
	global_load_lds_dwordx4 v[168:169], off
	v_lshl_add_u64 v[168:169], s[46:47], 0, v[164:165]
	s_add_i32 m0, s34, 0xe000
	s_nop 0
	global_load_lds_dwordx4 v[168:169], off
	s_waitcnt vmcnt(8)
	s_waitcnt lgkmcnt(0)
	s_setprio 1
	s_cmp_eq_u32 s32, 0
	s_cbranch_scc1 .Lrs_40
	s_barrier
	s_setprio 2
.Lrs_40:
	v_mfma_f32_16x16x32_bf16 v[130:133], v[124:127], v[182:185], v[130:133]
	v_mfma_f32_16x16x32_bf16 v[130:133], v[134:137], v[186:189], v[130:133]
	v_mfma_f32_16x16x32_bf16 v[120:123], v[142:145], v[186:189], v[120:123]
	v_mfma_f32_16x16x32_bf16 v[120:123], v[138:141], v[182:185], v[120:123]
	v_mfma_f32_16x16x32_bf16 v[116:119], v[146:149], v[182:185], v[116:119]
	v_mfma_f32_16x16x32_bf16 v[116:119], v[150:153], v[186:189], v[116:119]
	v_mfma_f32_16x16x32_bf16 v[112:115], v[158:161], v[186:189], v[112:115]
	v_mfma_f32_16x16x32_bf16 v[112:115], v[154:157], v[182:185], v[112:115]
	v_mfma_f32_16x16x32_bf16 v[96:99], v[154:157], v[190:193], v[96:99]
	v_mfma_f32_16x16x32_bf16 v[96:99], v[158:161], v[200:203], v[96:99]
	v_mfma_f32_16x16x32_bf16 v[100:103], v[150:153], v[200:203], v[100:103]
	v_mfma_f32_16x16x32_bf16 v[100:103], v[146:149], v[190:193], v[100:103]
	v_mfma_f32_16x16x32_bf16 v[104:107], v[138:141], v[190:193], v[104:107]
	v_mfma_f32_16x16x32_bf16 v[104:107], v[142:145], v[200:203], v[104:107]
	v_mfma_f32_16x16x32_bf16 v[108:111], v[134:137], v[200:203], v[108:111]
	v_mfma_f32_16x16x32_bf16 v[108:111], v[124:127], v[190:193], v[108:111]
	v_mfma_f32_16x16x32_bf16 v[92:95], v[124:127], v[204:207], v[92:95]
	v_mfma_f32_16x16x32_bf16 v[92:95], v[134:137], v[210:213], v[92:95]
	v_mfma_f32_16x16x32_bf16 v[88:91], v[142:145], v[210:213], v[88:91]
	v_mfma_f32_16x16x32_bf16 v[88:91], v[138:141], v[204:207], v[88:91]
	v_mfma_f32_16x16x32_bf16 v[84:87], v[146:149], v[204:207], v[84:87]
	v_mfma_f32_16x16x32_bf16 v[84:87], v[150:153], v[210:213], v[84:87]
	v_mfma_f32_16x16x32_bf16 v[80:83], v[158:161], v[210:213], v[80:83]
	v_mfma_f32_16x16x32_bf16 v[80:83], v[154:157], v[204:207], v[80:83]
	v_mfma_f32_16x16x32_bf16 v[64:67], v[154:157], v[226:229], v[64:67]
	v_mfma_f32_16x16x32_bf16 v[64:67], v[158:161], v[230:233], v[64:67]
	v_mfma_f32_16x16x32_bf16 v[68:71], v[150:153], v[230:233], v[68:71]
	v_mfma_f32_16x16x32_bf16 v[68:71], v[146:149], v[226:229], v[68:71]
	v_mfma_f32_16x16x32_bf16 v[72:75], v[138:141], v[226:229], v[72:75]
	v_mfma_f32_16x16x32_bf16 v[72:75], v[142:145], v[230:233], v[72:75]
	v_mfma_f32_16x16x32_bf16 v[76:79], v[134:137], v[230:233], v[76:79]
	v_mfma_f32_16x16x32_bf16 v[76:79], v[124:127], v[226:229], v[76:79]
	s_cmp_lg_u32 s32, 0
	s_cbranch_scc1 .Lrs_41
	s_barrier
; #define PG8_STAGE(bufoff, gbase, voff) do { _Pragma("unroll") for (int _i = 0; _i < 2; ++_i) \
;         __builtin_amdgcn_global_load_lds((const unsigned*)((const char*)(gbase) + (voff)[_i]), (PG8_LAS unsigned*)(lds + (bufoff) + ldsw + _i * 8192), 16, 0, 0); } while (0)
; #define PG8_LDA(dst, b, h) do { _Pragma("unroll") for (int m = 0; m < 4; ++m) _Pragma("unroll") for (int k = 0; k < 2; ++k) dst[m][k] = *(const PG8_LAS bf16x8*)(lds + PG8_SA(b, h) + aoff + m * 2048 + k * 1024); } while (0)
; #define PG8_LDB(dst, b, h) do { _Pragma("unroll") for (int n = 0; n < 2; ++n) _Pragma("unroll") for (int k = 0; k < 2; ++k) dst[n][k] = *(const PG8_LAS bf16x8*)(lds + PG8_SB(b, h) + boff + n * 2048 + k * 1024); } while (0)
; #define PG8_MMA(ai, bj, At, Bt) do { __builtin_amdgcn_s_setprio(1); _Pragma("unroll") for (int m = 0; m < 4; ++m) _Pragma("unroll") for (int n = 0; n < 2; ++n) _Pragma("unroll") for (int k = 0; k < 2; ++k) \
;         acc[ai][bj][m][n] = __builtin_amdgcn_mfma_f32_16x16x32_bf16(Bt[n][k], At[m][k], acc[ai][bj][m][n], 0, 0, 0); __builtin_amdgcn_s_setprio(0); } while (0)
; #define PG8_WAIT_V(n) asm volatile("s_waitcnt vmcnt(" #n ")" ::: "memory")
; #define PG8_WAIT_L(n) asm volatile("s_waitcnt lgkmcnt(" #n ")" ::: "memory")
; #define PG8_BAR __builtin_amdgcn_s_barrier()
; #define PG8_SCHED __builtin_amdgcn_sched_barrier(0)
; template <class Epi, class Sched, bool ALIGN_EPI = false, bool SP2 = false, class Hook = NoHook, bool REVK = false>
; __device__ __forceinline__ void gemm_phase(PG8_LAS unsigned char* lds, const Gemm g, const Sched& S, const Epi& E, const Hook H = Hook()) {
;     ...
;             PG8_WAIT_V(8); PG8_WAIT_L(0); PG8_BAR; PG8_MMA(0, 0, At, B0); PG8_MMA(0, 1, At, B1); PG8_BAR; PG8_SCHED;
;             PG8_LDA(At, 0, 1); PG8_STAGE(PG8_SB(0, 0), b2, voffB); PG8_STAGE(PG8_SB(0, 1), b2 + hstep, voffB); PG8_STAGE(PG8_SA(0, 0), a2, voffA);
;             PG8_WAIT_V(8); PG8_WAIT_L(0); PG8_BAR; PG8_MMA(1, 0, At, B0); PG8_MMA(1, 1, At, B1); PG8_BAR; PG8_SCHED;
;             PG8_LDB(B0, 1, 0); PG8_LDB(B1, 1, 1); PG8_SCHED; PG8_LDA(At, 1, 0); PG8_STAGE(PG8_SA(0, 1), a2 + hstep, voffA);
;             PG8_WAIT_V(8); PG8_WAIT_L(0); PG8_BAR; PG8_MMA(0, 0, At, B0); PG8_MMA(0, 1, At, B1); PG8_BAR; PG8_SCHED;
.Lrs_41:
	s_setprio 0
	s_add_i32 s44, s51, s31
	v_lshl_add_u64 v[168:169], s[20:21], 0, v[128:129]
	s_mov_b32 m0, s44
	ds_read_b128 v[182:185], v197 offset:16384
	ds_read_b128 v[186:189], v197 offset:17408
	ds_read_b128 v[190:193], v197 offset:18432
	ds_read_b128 v[200:203], v197 offset:19456
	ds_read_b128 v[204:207], v197 offset:20480
	ds_read_b128 v[210:213], v197 offset:21504
	ds_read_b128 v[226:229], v197 offset:22528
	ds_read_b128 v[230:233], v197 offset:23552
	global_load_lds_dwordx4 v[168:169], off
	s_add_i32 m0, s44, 0x2000
	s_add_u32 s46, s20, 0x200000
	v_lshl_add_u64 v[214:215], s[20:21], 0, v[162:163]
	s_addc_u32 s47, s21, 0
	s_add_i32 s44, s53, s31
	global_load_lds_dwordx4 v[214:215], off
	v_lshl_add_u64 v[234:235], s[46:47], 0, v[128:129]
	s_mov_b32 m0, s44
	v_lshl_add_u64 v[236:237], s[26:27], 0, v[164:165]
	global_load_lds_dwordx4 v[234:235], off
	v_lshl_add_u64 v[234:235], s[46:47], 0, v[162:163]
	s_add_i32 m0, s44, 0x2000
	s_nop 0
	global_load_lds_dwordx4 v[234:235], off
	v_lshl_add_u64 v[234:235], s[26:27], 0, v[166:167]
	s_mov_b32 m0, s34
	s_nop 0
	global_load_lds_dwordx4 v[234:235], off
	s_mov_b32 m0, s35
	s_nop 0
	global_load_lds_dwordx4 v[236:237], off
	s_waitcnt vmcnt(8)
	s_waitcnt lgkmcnt(0)
	s_setprio 1
	s_cmp_eq_u32 s32, 0
	s_cbranch_scc1 .Lrs_42
	s_barrier
	s_setprio 2
.Lrs_42:
	v_mfma_f32_16x16x32_bf16 v[60:63], v[124:127], v[182:185], v[60:63]
	v_mfma_f32_16x16x32_bf16 v[60:63], v[134:137], v[186:189], v[60:63]
	v_mfma_f32_16x16x32_bf16 v[56:59], v[142:145], v[186:189], v[56:59]
	v_mfma_f32_16x16x32_bf16 v[56:59], v[138:141], v[182:185], v[56:59]
	v_mfma_f32_16x16x32_bf16 v[52:55], v[146:149], v[182:185], v[52:55]
	v_mfma_f32_16x16x32_bf16 v[52:55], v[150:153], v[186:189], v[52:55]
	v_mfma_f32_16x16x32_bf16 v[48:51], v[158:161], v[186:189], v[48:51]
	v_mfma_f32_16x16x32_bf16 v[48:51], v[154:157], v[182:185], v[48:51]
	v_mfma_f32_16x16x32_bf16 v[32:35], v[154:157], v[190:193], v[32:35]
	v_mfma_f32_16x16x32_bf16 v[32:35], v[158:161], v[200:203], v[32:35]
	v_mfma_f32_16x16x32_bf16 v[36:39], v[150:153], v[200:203], v[36:39]
	v_mfma_f32_16x16x32_bf16 v[36:39], v[146:149], v[190:193], v[36:39]
	v_mfma_f32_16x16x32_bf16 v[40:43], v[138:141], v[190:193], v[40:43]
	v_mfma_f32_16x16x32_bf16 v[40:43], v[142:145], v[200:203], v[40:43]
	v_mfma_f32_16x16x32_bf16 v[44:47], v[134:137], v[200:203], v[44:47]
	v_mfma_f32_16x16x32_bf16 v[44:47], v[124:127], v[190:193], v[44:47]
	v_mfma_f32_16x16x32_bf16 v[28:31], v[124:127], v[204:207], v[28:31]
	v_mfma_f32_16x16x32_bf16 v[28:31], v[134:137], v[210:213], v[28:31]
	v_mfma_f32_16x16x32_bf16 v[24:27], v[142:145], v[210:213], v[24:27]
	v_mfma_f32_16x16x32_bf16 v[24:27], v[138:141], v[204:207], v[24:27]
	v_mfma_f32_16x16x32_bf16 v[20:23], v[146:149], v[204:207], v[20:23]
	v_mfma_f32_16x16x32_bf16 v[20:23], v[150:153], v[210:213], v[20:23]
	v_mfma_f32_16x16x32_bf16 v[16:19], v[158:161], v[210:213], v[16:19]
	v_mfma_f32_16x16x32_bf16 v[16:19], v[154:157], v[204:207], v[16:19]
	v_mfma_f32_16x16x32_bf16 v[0:3], v[154:157], v[226:229], v[0:3]
	v_mfma_f32_16x16x32_bf16 v[0:3], v[158:161], v[230:233], v[0:3]
	v_mfma_f32_16x16x32_bf16 v[4:7], v[150:153], v[230:233], v[4:7]
	v_mfma_f32_16x16x32_bf16 v[4:7], v[146:149], v[226:229], v[4:7]
	v_mfma_f32_16x16x32_bf16 v[8:11], v[138:141], v[226:229], v[8:11]
	v_mfma_f32_16x16x32_bf16 v[8:11], v[142:145], v[230:233], v[8:11]
	v_mfma_f32_16x16x32_bf16 v[12:15], v[134:137], v[230:233], v[12:15]
	v_mfma_f32_16x16x32_bf16 v[12:15], v[124:127], v[226:229], v[12:15]
	s_cmp_lg_u32 s32, 0
	s_cbranch_scc1 .Lrs_43
	s_barrier
.Lrs_43:
	s_setprio 0
	s_add_i32 s44, 0, 0x18000
	s_add_i32 s46, 0, 0x1c000
	v_add_u32_e32 v142, s44, v195
	v_add_u32_e32 v158, s46, v195
	ds_read_b128 v[124:127], v142
	ds_read_b128 v[134:137], v142 offset:1024
	ds_read_b128 v[138:141], v142 offset:2048
	ds_read_b128 v[142:145], v142 offset:3072
	ds_read_b128 v[146:149], v158
	ds_read_b128 v[150:153], v158 offset:1024
	ds_read_b128 v[154:157], v158 offset:2048
	ds_read_b128 v[158:161], v158 offset:3072
	s_add_u32 s26, s26, 0x200000
	s_addc_u32 s27, s27, 0
	s_mov_b32 m0, s36
	v_lshl_add_u64 v[238:239], s[26:27], 0, v[166:167]
	ds_read_b128 v[182:185], v197 offset:32768
	ds_read_b128 v[186:189], v197 offset:33792
	ds_read_b128 v[190:193], v197 offset:34816
	ds_read_b128 v[200:203], v197 offset:35840
	ds_read_b128 v[204:207], v197 offset:36864
	ds_read_b128 v[210:213], v197 offset:37888
	ds_read_b128 v[226:229], v197 offset:38912
	ds_read_b128 v[230:233], v197 offset:39936
	global_load_lds_dwordx4 v[238:239], off
	v_lshl_add_u64 v[238:239], s[26:27], 0, v[164:165]
	s_mov_b32 m0, s38
	s_nop 0
	global_load_lds_dwordx4 v[238:239], off
	s_waitcnt vmcnt(8)
	s_waitcnt lgkmcnt(0)
	s_setprio 1
	s_cmp_eq_u32 s32, 0
	s_cbranch_scc1 .Lrs_44
	s_barrier
	s_setprio 2

; #define PG8_STAGE(bufoff, gbase, voff) do { _Pragma("unroll") for (int _i = 0; _i < 2; ++_i) \
;         __builtin_amdgcn_global_load_lds((const unsigned*)((const char*)(gbase) + (voff)[_i]), (PG8_LAS unsigned*)(lds + (bufoff) + ldsw + _i * 8192), 16, 0, 0); } while (0)
; #define PG8_LDA(dst, b, h) do { _Pragma("unroll") for (int m = 0; m < 4; ++m) _Pragma("unroll") for (int k = 0; k < 2; ++k) dst[m][k] = *(const PG8_LAS bf16x8*)(lds + PG8_SA(b, h) + aoff + m * 2048 + k * 1024); } while (0)
; #define PG8_MMA(ai, bj, At, Bt) do { __builtin_amdgcn_s_setprio(1); _Pragma("unroll") for (int m = 0; m < 4; ++m) _Pragma("unroll") for (int n = 0; n < 2; ++n) _Pragma("unroll") for (int k = 0; k < 2; ++k) \
;         acc[ai][bj][m][n] = __builtin_amdgcn_mfma_f32_16x16x32_bf16(Bt[n][k], At[m][k], acc[ai][bj][m][n], 0, 0, 0); __builtin_amdgcn_s_setprio(0); } while (0)
; #define PG8_WAIT_V(n) asm volatile("s_waitcnt vmcnt(" #n ")" ::: "memory")
; #define PG8_WAIT_L(n) asm volatile("s_waitcnt lgkmcnt(" #n ")" ::: "memory")
; #define PG8_BAR __builtin_amdgcn_s_barrier()
; #define PG8_SCHED __builtin_amdgcn_sched_barrier(0)
; template <class Epi, class Sched, bool ALIGN_EPI = false, bool SP2 = false, class Hook = NoHook, bool REVK = false>
; __device__ __forceinline__ void gemm_phase(PG8_LAS unsigned char* lds, const Gemm g, const Sched& S, const Epi& E, const Hook H = Hook()) {
;     ...
;             PG8_LDA(At, 1, 1); PG8_STAGE(PG8_SB(1, 0), b3, voffB); PG8_STAGE(PG8_SB(1, 1), b3 + hstep, voffB); PG8_STAGE(PG8_SA(1, 0), a3, voffA);
;             PG8_WAIT_V(8); PG8_WAIT_L(0); PG8_BAR; PG8_MMA(1, 0, At, B0); PG8_MMA(1, 1, At, B1); PG8_BAR; PG8_SCHED;
.Lrs_45:
	s_setprio 0
	s_add_i32 s26, s44, s31
	v_lshl_add_u64 v[168:169], v[168:169], 0, s[70:71]
	s_mov_b32 m0, s26
	ds_read_b128 v[182:185], v197 offset:49152
	ds_read_b128 v[186:189], v197 offset:50176
	ds_read_b128 v[190:193], v197 offset:51200
	ds_read_b128 v[200:203], v197 offset:52224
	ds_read_b128 v[204:207], v197 offset:53248
	ds_read_b128 v[210:213], v197 offset:54272
	ds_read_b128 v[226:229], v197 offset:55296
	ds_read_b128 v[230:233], v197 offset:56320
	global_load_lds_dwordx4 v[168:169], off
	s_add_i32 m0, s26, 0x2000
	s_add_u32 s20, s20, 0x1fff80
	v_lshl_add_u64 v[168:169], v[214:215], 0, s[70:71]
	s_addc_u32 s21, s21, 0
	s_add_i32 s26, s46, s31
	global_load_lds_dwordx4 v[168:169], off
	v_lshl_add_u64 v[168:169], s[20:21], 0, v[128:129]
	s_mov_b32 m0, s26
	s_nop 0
	global_load_lds_dwordx4 v[168:169], off
	v_lshl_add_u64 v[168:169], s[20:21], 0, v[162:163]
	s_add_i32 m0, s26, 0x2000
	s_nop 0
	global_load_lds_dwordx4 v[168:169], off
	v_lshl_add_u64 v[168:169], v[234:235], 0, s[70:71]
	s_mov_b32 m0, s39
	s_nop 0
	global_load_lds_dwordx4 v[168:169], off
	v_lshl_add_u64 v[168:169], v[236:237], 0, s[70:71]
	s_mov_b32 m0, s40
	s_nop 0
	global_load_lds_dwordx4 v[168:169], off
	s_waitcnt vmcnt(8)
	s_waitcnt lgkmcnt(0)
	s_setprio 1
	s_cmp_eq_u32 s32, 0
	s_cbranch_scc1 .Lrs_46
	s_barrier
	s_setprio 2

; #define PG8_MMA(ai, bj, At, Bt) do { __builtin_amdgcn_s_setprio(1); _Pragma("unroll") for (int m = 0; m < 4; ++m) _Pragma("unroll") for (int n = 0; n < 2; ++n) _Pragma("unroll") for (int k = 0; k < 2; ++k) \
;         acc[ai][bj][m][n] = __builtin_amdgcn_mfma_f32_16x16x32_bf16(Bt[n][k], At[m][k], acc[ai][bj][m][n], 0, 0, 0); __builtin_amdgcn_s_setprio(0); } while (0)
; #define PG8_WAIT_V(n) asm volatile("s_waitcnt vmcnt(" #n ")" ::: "memory")
; #define PG8_WAIT_L(n) asm volatile("s_waitcnt lgkmcnt(" #n ")" ::: "memory")
; #define PG8_BAR __builtin_amdgcn_s_barrier()
; #define PG8_SCHED __builtin_amdgcn_sched_barrier(0)
; template <class Epi, class Sched, bool ALIGN_EPI = false, bool SP2 = false, class Hook = NoHook, bool REVK = false>
; __device__ __forceinline__ void gemm_phase(PG8_LAS unsigned char* lds, const Gemm g, const Sched& S, const Epi& E, const Hook H = Hook()) {
;     ...
;         for (int t = 0; t < nt; t += 2) {
;     ...
;             PG8_WAIT_V(8); PG8_WAIT_L(0); PG8_BAR; PG8_MMA(1, 0, At, B0); PG8_MMA(1, 1, At, B1); PG8_BAR; PG8_SCHED;
.Lrs_47:
	s_setprio 0
	s_cmpk_gt_u32 s42, 0x7d
	s_mov_b32 s42, s43
	s_cbranch_scc1 .LBB0_659

; __device__ __forceinline__ unsigned cvt_pk_bf16(float lo, float hi) { f32x2_t v = {lo, hi}; bf16x2_t b = __builtin_convertvector(v, bf16x2_t); return __builtin_bit_cast(unsigned, b); }
;     __device__ __forceinline__ void operator()(const f32x4 (&acc)[2][2][4][2], const Unit& u, int wr, int wc, int fr, int fq, int ui) const {
;         const int row0 = u.pm * BM + wr * 64 + fr; const int col0 = u.pn * BM + wc * 32 + 8 * fq;
; #pragma unroll
;         for (int ai = 0; ai < 2; ++ai) {
;             u32x4 bs[4][2];
; #pragma unroll
;             for (int m = 0; m < 4; ++m) { const bf16_t* rowp = xb + (size_t)(row0 + ai * HALF + m * 16) * ldc + col0;
; #pragma unroll
;                 for (int bj = 0; bj < 2; ++bj) bs[m][bj] = *(const u32x4*)(rowp + bj * HALF); }
; #pragma unroll
;             for (int m = 0; m < 4; ++m) { const int row = row0 + ai * HALF + m * 16; bf16_t* rowp = xb + (size_t)row * ldc + col0;
;                 float q = 0.f;
; #pragma unroll
;                 for (int bj = 0; bj < 2; ++bj) { u32x4 w;
; #pragma unroll
;                     for (int p = 0; p < 4; ++p) { const f32x4 a = acc[ai][bj][m][p >> 1]; const unsigned b = bs[m][bj][p];
;                         const float lo = __uint_as_float(b << 16) + a[2 * (p & 1)], hi = __uint_as_float(b & 0xffff0000u) + a[2 * (p & 1) + 1];
;                         const unsigned pk = cvt_pk_bf16(lo, hi); w[p] = pk;
;                         const float rl = __uint_as_float(pk << 16), rh = __uint_as_float(pk & 0xffff0000u); q += rl * rl + rh * rh; }
;                     *(u32x4*)(rowp + bj * HALF) = w; }
;                 q += __shfl_xor(q, 16); q += __shfl_xor(q, 32);
;                 if (fq == 0) atomicAdd(ssq + row, (unsigned long long)(q * 16777216.f)); }
.LBB0_661:
	s_nop 7
	s_nop 7
	v_and_b32_e32 v125, 64, v221
	v_xor_b32_e32 v124, 16, v221
	v_add_u32_e32 v125, 64, v125
	v_cmp_lt_i32_e32 vcc, v124, v125
	v_lshl_or_b32 v168, s10, 8, v196
	v_lshl_add_u32 v182, s11, 8, v194
	v_cndmask_b32_e32 v124, v221, v124, vcc
	v_ashrrev_i32_e32 v169, 31, v168
	v_lshlrev_b32_e32 v198, 2, v124
	v_xor_b32_e32 v124, 32, v221
	v_cmp_lt_i32_e32 vcc, v124, v125
	v_lshlrev_b64 v[192:193], 1, v[168:169]
	v_ashrrev_i32_e32 v183, 31, v182
	v_cndmask_b32_e32 v124, v221, v124, vcc
	v_lshl_add_u64 v[184:185], s[12:13], 0, v[192:193]
	v_lshlrev_b64 v[202:203], 12, v[182:183]
	v_lshlrev_b32_e32 v200, 2, v124
	v_lshl_add_u64 v[124:125], v[184:185], 0, v[202:203]
	global_load_dwordx4 v[158:161], v[124:125], off
	global_load_dwordx4 v[154:157], v[124:125], off offset:256
	v_or_b32_e32 v190, 16, v182
	v_ashrrev_i32_e32 v191, 31, v190
	v_lshlrev_b64 v[124:125], 12, v[190:191]
	v_or_b32_e32 v188, 32, v182
	v_lshl_add_u64 v[124:125], v[184:185], 0, v[124:125]
	v_ashrrev_i32_e32 v189, 31, v188
	global_load_dwordx4 v[150:153], v[124:125], off
	global_load_dwordx4 v[146:149], v[124:125], off offset:256
	v_lshlrev_b64 v[124:125], 12, v[188:189]
	v_or_b32_e32 v186, 48, v182
	v_lshl_add_u64 v[124:125], v[184:185], 0, v[124:125]
	v_ashrrev_i32_e32 v187, 31, v186
	global_load_dwordx4 v[142:145], v[124:125], off
	global_load_dwordx4 v[138:141], v[124:125], off offset:256
	v_lshlrev_b64 v[124:125], 12, v[186:187]
	v_lshl_add_u64 v[124:125], v[184:185], 0, v[124:125]
	global_load_dwordx4 v[134:137], v[124:125], off
	s_nop 0
	global_load_dwordx4 v[124:127], v[124:125], off offset:256
	v_lshl_add_u64 v[202:203], s[12:13], 0, v[202:203]
	v_lshl_add_u64 v[192:193], v[202:203], 0, v[192:193]
	s_waitcnt vmcnt(0)
	v_lshlrev_b32_e32 v202, 16, v158
	v_and_b32_e32 v203, 0xffff0000, v158
	v_pk_add_f32 v[130:131], v[130:131], v[202:203]
	s_nop 0
	v_cvt_pk_bf16_f32 v130, v130, v131
	v_and_b32_e32 v158, 0xffff0000, v130
	v_mul_f32_e32 v201, v158, v158
	v_lshlrev_b32_e32 v158, 16, v159
	v_and_b32_e32 v159, 0xffff0000, v159
	v_lshlrev_b32_e32 v131, 16, v130
	v_pk_add_f32 v[132:133], v[132:133], v[158:159]
	v_fmac_f32_e32 v201, v131, v131
	v_cvt_pk_bf16_f32 v131, v132, v133
	v_and_b32_e32 v133, 0xffff0000, v131
	v_lshlrev_b32_e32 v132, 16, v131
	v_mul_f32_e32 v133, v133, v133
	v_fmac_f32_e32 v133, v132, v132
	v_add_f32_e32 v158, v201, v133
	v_lshlrev_b32_e32 v132, 16, v160
	v_and_b32_e32 v133, 0xffff0000, v160
	v_pk_add_f32 v[120:121], v[120:121], v[132:133]
	s_nop 0
	v_cvt_pk_bf16_f32 v132, v120, v121
	v_and_b32_e32 v121, 0xffff0000, v132
	v_lshlrev_b32_e32 v120, 16, v132
	v_mul_f32_e32 v121, v121, v121
	v_fmac_f32_e32 v121, v120, v120
	v_add_f32_e32 v158, v121, v158
	v_lshlrev_b32_e32 v120, 16, v161
	v_and_b32_e32 v121, 0xffff0000, v161
	v_pk_add_f32 v[120:121], v[122:123], v[120:121]
	s_nop 0
	v_cvt_pk_bf16_f32 v133, v120, v121
	v_and_b32_e32 v121, 0xffff0000, v133
	v_lshlrev_b32_e32 v120, 16, v133
	v_mul_f32_e32 v121, v121, v121
	v_fmac_f32_e32 v121, v120, v120
	v_add_f32_e32 v122, v121, v158
	v_lshlrev_b32_e32 v120, 16, v154
	v_and_b32_e32 v121, 0xffff0000, v154
	v_pk_add_f32 v[116:117], v[116:117], v[120:121]
	v_and_b32_e32 v121, 0xffff0000, v155
	v_cvt_pk_bf16_f32 v116, v116, v117
	v_and_b32_e32 v120, 0xffff0000, v116
	v_lshlrev_b32_e32 v117, 16, v116
	v_mul_f32_e32 v120, v120, v120
	v_fmac_f32_e32 v120, v117, v117
	v_add_f32_e32 v122, v120, v122
	v_lshlrev_b32_e32 v120, 16, v155
	v_pk_add_f32 v[118:119], v[118:119], v[120:121]
	global_store_dwordx4 v[192:193], v[130:133], off
	v_cvt_pk_bf16_f32 v117, v118, v119
	v_and_b32_e32 v119, 0xffff0000, v117
	v_lshlrev_b32_e32 v118, 16, v117
	v_mul_f32_e32 v119, v119, v119
	v_fmac_f32_e32 v119, v118, v118
	v_add_f32_e32 v120, v119, v122
	v_lshlrev_b32_e32 v118, 16, v156
	v_and_b32_e32 v119, 0xffff0000, v156
	v_pk_add_f32 v[112:113], v[112:113], v[118:119]
	s_nop 0
	v_cvt_pk_bf16_f32 v118, v112, v113
	v_and_b32_e32 v113, 0xffff0000, v118
	v_lshlrev_b32_e32 v112, 16, v118
	v_mul_f32_e32 v113, v113, v113
	v_fmac_f32_e32 v113, v112, v112
	v_add_f32_e32 v120, v113, v120
	v_lshlrev_b32_e32 v112, 16, v157
	v_and_b32_e32 v113, 0xffff0000, v157
	v_pk_add_f32 v[112:113], v[114:115], v[112:113]
	s_nop 0
	v_cvt_pk_bf16_f32 v119, v112, v113
	v_and_b32_e32 v113, 0xffff0000, v119
	v_lshlrev_b32_e32 v112, 16, v119
	v_mul_f32_e32 v113, v113, v113
	v_fmac_f32_e32 v113, v112, v112
	v_add_f32_e32 v112, v113, v120
	ds_bpermute_b32 v113, v198, v112
	global_store_dwordx4 v[192:193], v[116:119], off offset:256
	s_waitcnt lgkmcnt(0)
	v_add_f32_e32 v112, v112, v113
	ds_bpermute_b32 v113, v200, v112
	s_and_saveexec_b64 s[20:21], s[4:5]
	s_cbranch_execz .LBB0_663
	s_waitcnt lgkmcnt(0)
	v_add_f32_e32 v112, v112, v113
	v_mul_f32_e32 v112, 0x4b800000, v112
	v_trunc_f32_e32 v112, v112
	v_mul_f32_e32 v113, 0x2f800000, v112
	v_floor_f32_e32 v113, v113
	v_fmac_f32_e32 v112, 0xcf800000, v113
	v_cvt_u32_f32_e32 v112, v112
	v_cvt_u32_f32_e32 v113, v113
	v_lshl_add_u64 v[114:115], v[182:183], 3, s[14:15]
	global_atomic_add_x2 v[114:115], v[112:113], off

; #define PG8_BAR __builtin_amdgcn_s_barrier()
; template <class Epi, class Sched, bool ALIGN_EPI = false, bool SP2 = false, class Hook = NoHook, bool REVK = false>
; __device__ __forceinline__ void gemm_phase(PG8_LAS unsigned char* lds, const Gemm g, const Sched& S, const Epi& E, const Hook H = Hook()) {
;     ...
;         if constexpr (!Epi::AFTER_DRAIN) { E(acc, cur, wr, wc, fr, fq, ui); S.done(cur); }
;         if (!has_next) break;
; #pragma unroll
;         for (int a = 0; a < 2; ++a)
; #pragma unroll
;             for (int b = 0; b < 2; ++b)
; #pragma unroll
;                 for (int m = 0; m < 4; ++m)
; #pragma unroll
;                     for (int n = 0; n < 2; ++n) acc[a][b][m][n] = (f32x4){0.f, 0.f, 0.f, 0.f};
;         cur = nxt; cA = nA; cB = nB; ++ui;
;         if constexpr (ALIGN_EPI) { if (wr == 1) PG8_BAR; }
.LBB0_677:
	s_or_b64 exec, exec, s[20:21]
	s_andn2_b64 vcc, exec, s[6:7]
	s_mov_b64 s[6:7], -1
	s_cbranch_vccnz .LBB0_646
	s_andn2_b64 vcc, exec, s[8:9]
	s_cbranch_vccnz .LBB0_645
	s_branch .LBB0_645
